# merged the back-to-back s_waitcnt vmcnt(8) / s_waitcnt lgkmcnt(0) closing each K-loop load segment into one s_waitcnt (28 sites)
# baseline (speedup 1.0000x reference)
; #define PG8_STAGE(bufoff, gbase, voff) do { _Pragma("unroll") for (int _i = 0; _i < 2; ++_i) \
;         __builtin_amdgcn_global_load_lds((const unsigned*)((const char*)(gbase) + (voff)[_i]), (LAS unsigned*)(lds + (bufoff) + ldsw + _i * 8192), 16, 0, 0); } while (0)
; #define PG8_LDA(dst, b, h) do { _Pragma("unroll") for (int m = 0; m < 4; ++m) _Pragma("unroll") for (int k = 0; k < 2; ++k) dst[m][k] = *(const LAS bf16x8*)(lds + PG8_SA(b, h) + aoff + m * 2048 + k * 1024); } while (0)
; #define PG8_LDB(dst, b, h) do { _Pragma("unroll") for (int n = 0; n < 2; ++n) _Pragma("unroll") for (int k = 0; k < 2; ++k) dst[n][k] = *(const LAS bf16x8*)(lds + PG8_SB(b, h) + boff + n * 2048 + k * 1024); } while (0)
; #define PG8_MMA(ai, bj, At, Bt) do { __builtin_amdgcn_s_setprio(1); _Pragma("unroll") for (int m = 0; m < 4; ++m) _Pragma("unroll") for (int n = 0; n < 2; ++n) _Pragma("unroll") for (int k = 0; k < 2; ++k) \
;         acc[ai][bj][m][n] = __builtin_amdgcn_mfma_f32_16x16x32_bf16(Bt[n][k], At[m][k], acc[ai][bj][m][n], 0, 0, 0); __builtin_amdgcn_s_setprio(0); } while (0)
; #define PG8_WAIT_V(n) asm volatile("s_waitcnt vmcnt(" #n ")" ::: "memory")
; #define PG8_WAIT_L(n) asm volatile("s_waitcnt lgkmcnt(" #n ")" ::: "memory")
; #define PG8_BAR __builtin_amdgcn_s_barrier()
; #define PG8_SCHED __builtin_amdgcn_sched_barrier(0)
; template <class Epi, class Sched>
; __device__ __forceinline__ void gemm_phase(LAS unsigned char* lds, const Gemm g, const Sched& S, const Epi& E) {
;     ...
;             const bool last = (t == nt - 2);
;             const char* a1 = cA + (size_t)(t + 1) * kstep;
;             const char* a2 = last ? nA : cA + (size_t)(t + 2) * kstep; const char* b2 = last ? nB : cB + (size_t)(t + 2) * kstep;
;             const char* a3 = a2 + kstep; const char* b3 = b2 + kstep;
;             PG8_LDB(B0, 0, 0); PG8_LDB(B1, 0, 1); PG8_SCHED; PG8_LDA(At, 0, 0); PG8_STAGE(PG8_SA(1, 1), a1 + hstepA, voffA);
;             PG8_WAIT_V(8); PG8_WAIT_L(0); PG8_BAR; PG8_MMA(0, 0, At, B0); PG8_MMA(0, 1, At, B1); PG8_BAR; PG8_SCHED;
;             PG8_LDA(At, 0, 1); PG8_STAGE(PG8_SB(0, 0), b2, voffB); PG8_STAGE(PG8_SB(0, 1), b2 + hstepB, voffB); PG8_STAGE(PG8_SA(0, 0), a2, voffA);
.LBB0_122:
	ds_read_b128 v[128:131], v209
	ds_read_b128 v[132:135], v209 offset:1024
	ds_read_b128 v[136:139], v209 offset:2048
	ds_read_b128 v[140:143], v209 offset:3072
	ds_read_b128 v[144:147], v210
	ds_read_b128 v[148:151], v210 offset:1024
	ds_read_b128 v[152:155], v210 offset:2048
	ds_read_b128 v[156:159], v210 offset:3072
	s_add_u32 s4, s0, 0xfff80080
	s_addc_u32 s5, s1, -1
	s_cmp_eq_u32 s87, 28
	s_cselect_b32 s7, s8, s5
	s_cselect_b32 s6, s9, s4
	s_cselect_b32 s5, s10, s35
	s_cselect_b32 s4, s11, s34
	v_lshl_add_u64 v[216:217], s[0:1], 0, v[178:179]
	s_add_i32 m0, s15, 0xc000
	ds_read_b128 v[160:163], v211
	ds_read_b128 v[164:167], v211 offset:1024
	ds_read_b128 v[182:185], v211 offset:2048
	ds_read_b128 v[186:189], v211 offset:3072
	ds_read_b128 v[190:193], v211 offset:4096
	ds_read_b128 v[194:197], v211 offset:5120
	ds_read_b128 v[198:201], v211 offset:6144
	ds_read_b128 v[202:205], v211 offset:7168
	global_load_lds_dwordx4 v[216:217], off
	v_lshl_add_u64 v[216:217], s[0:1], 0, v[180:181]
	s_add_i32 m0, s15, 0xe000
	s_nop 0
	global_load_lds_dwordx4 v[216:217], off
	s_waitcnt vmcnt(8) lgkmcnt(0)
	s_barrier
	s_setprio 1
	v_mfma_f32_16x16x32_bf16 v[124:127], v[128:131], v[160:163], v[124:127]
	v_mfma_f32_16x16x32_bf16 v[120:123], v[136:139], v[160:163], v[120:123]
	v_mfma_f32_16x16x32_bf16 v[116:119], v[128:131], v[182:185], v[116:119]
	v_mfma_f32_16x16x32_bf16 v[112:115], v[136:139], v[182:185], v[112:115]
	v_mfma_f32_16x16x32_bf16 v[108:111], v[128:131], v[190:193], v[108:111]
	v_mfma_f32_16x16x32_bf16 v[104:107], v[136:139], v[190:193], v[104:107]
	v_mfma_f32_16x16x32_bf16 v[96:99], v[128:131], v[198:201], v[96:99]
	v_mfma_f32_16x16x32_bf16 v[100:103], v[136:139], v[198:201], v[100:103]
	v_mfma_f32_16x16x32_bf16 v[124:127], v[132:135], v[164:167], v[124:127]
	v_mfma_f32_16x16x32_bf16 v[120:123], v[140:143], v[164:167], v[120:123]
	v_mfma_f32_16x16x32_bf16 v[116:119], v[132:135], v[186:189], v[116:119]
	v_mfma_f32_16x16x32_bf16 v[112:115], v[140:143], v[186:189], v[112:115]
	v_mfma_f32_16x16x32_bf16 v[108:111], v[132:135], v[194:197], v[108:111]
	v_mfma_f32_16x16x32_bf16 v[104:107], v[140:143], v[194:197], v[104:107]
	v_mfma_f32_16x16x32_bf16 v[96:99], v[132:135], v[202:205], v[96:99]
	v_mfma_f32_16x16x32_bf16 v[100:103], v[140:143], v[202:205], v[100:103]
	s_setprio 0
	s_setprio 1
	v_mfma_f32_16x16x32_bf16 v[60:63], v[144:147], v[160:163], v[60:63]
	v_mfma_f32_16x16x32_bf16 v[56:59], v[152:155], v[160:163], v[56:59]
	v_mfma_f32_16x16x32_bf16 v[52:55], v[144:147], v[182:185], v[52:55]
	v_mfma_f32_16x16x32_bf16 v[48:51], v[152:155], v[182:185], v[48:51]
	v_mfma_f32_16x16x32_bf16 v[44:47], v[144:147], v[190:193], v[44:47]
	v_mfma_f32_16x16x32_bf16 v[40:43], v[152:155], v[190:193], v[40:43]
	v_mfma_f32_16x16x32_bf16 v[32:35], v[144:147], v[198:201], v[32:35]
	v_mfma_f32_16x16x32_bf16 v[36:39], v[152:155], v[198:201], v[36:39]
	v_mfma_f32_16x16x32_bf16 v[60:63], v[148:151], v[164:167], v[60:63]
	v_mfma_f32_16x16x32_bf16 v[56:59], v[156:159], v[164:167], v[56:59]
	v_mfma_f32_16x16x32_bf16 v[52:55], v[148:151], v[186:189], v[52:55]
	v_mfma_f32_16x16x32_bf16 v[48:51], v[156:159], v[186:189], v[48:51]
	v_mfma_f32_16x16x32_bf16 v[44:47], v[148:151], v[194:197], v[44:47]
	v_mfma_f32_16x16x32_bf16 v[40:43], v[156:159], v[194:197], v[40:43]
	v_mfma_f32_16x16x32_bf16 v[32:35], v[148:151], v[202:205], v[32:35]
	v_mfma_f32_16x16x32_bf16 v[36:39], v[156:159], v[202:205], v[36:39]
	s_setprio 0
	s_barrier
	s_add_i32 s26, s33, s14
	v_lshl_add_u64 v[216:217], s[4:5], 0, v[170:171]
	s_mov_b32 m0, s26
	ds_read_b128 v[160:163], v211 offset:16384
	ds_read_b128 v[164:167], v211 offset:17408
	ds_read_b128 v[182:185], v211 offset:18432
	ds_read_b128 v[186:189], v211 offset:19456
	ds_read_b128 v[190:193], v211 offset:20480
	ds_read_b128 v[194:197], v211 offset:21504
	ds_read_b128 v[198:201], v211 offset:22528
	ds_read_b128 v[202:205], v211 offset:23552
	global_load_lds_dwordx4 v[216:217], off
	s_add_i32 m0, s26, 0x2000
	s_add_u32 s96, s4, 0x80000
	v_lshl_add_u64 v[218:219], s[4:5], 0, v[174:175]
	s_addc_u32 s97, s5, 0
	s_add_i32 s26, s36, s14
	global_load_lds_dwordx4 v[218:219], off
	v_lshl_add_u64 v[220:221], s[96:97], 0, v[170:171]
	s_mov_b32 m0, s26
	v_lshl_add_u64 v[222:223], s[6:7], 0, v[172:173]
	global_load_lds_dwordx4 v[220:221], off
	v_lshl_add_u64 v[220:221], s[96:97], 0, v[174:175]
	s_add_i32 m0, s26, 0x2000
	s_nop 0
	global_load_lds_dwordx4 v[220:221], off
	v_lshl_add_u64 v[220:221], s[6:7], 0, v[168:169]
	s_mov_b32 m0, s15
	s_nop 0
	global_load_lds_dwordx4 v[220:221], off
	s_mov_b32 m0, s28
	s_nop 0
	global_load_lds_dwordx4 v[222:223], off
	s_waitcnt vmcnt(8) lgkmcnt(0)
	s_barrier
; #define PG8_STAGE(bufoff, gbase, voff) do { _Pragma("unroll") for (int _i = 0; _i < 2; ++_i) \
;         __builtin_amdgcn_global_load_lds((const unsigned*)((const char*)(gbase) + (voff)[_i]), (LAS unsigned*)(lds + (bufoff) + ldsw + _i * 8192), 16, 0, 0); } while (0)
; #define PG8_LDA(dst, b, h) do { _Pragma("unroll") for (int m = 0; m < 4; ++m) _Pragma("unroll") for (int k = 0; k < 2; ++k) dst[m][k] = *(const LAS bf16x8*)(lds + PG8_SA(b, h) + aoff + m * 2048 + k * 1024); } while (0)
; #define PG8_LDB(dst, b, h) do { _Pragma("unroll") for (int n = 0; n < 2; ++n) _Pragma("unroll") for (int k = 0; k < 2; ++k) dst[n][k] = *(const LAS bf16x8*)(lds + PG8_SB(b, h) + boff + n * 2048 + k * 1024); } while (0)
; #define PG8_MMA(ai, bj, At, Bt) do { __builtin_amdgcn_s_setprio(1); _Pragma("unroll") for (int m = 0; m < 4; ++m) _Pragma("unroll") for (int n = 0; n < 2; ++n) _Pragma("unroll") for (int k = 0; k < 2; ++k) \
;         acc[ai][bj][m][n] = __builtin_amdgcn_mfma_f32_16x16x32_bf16(Bt[n][k], At[m][k], acc[ai][bj][m][n], 0, 0, 0); __builtin_amdgcn_s_setprio(0); } while (0)
; #define PG8_WAIT_V(n) asm volatile("s_waitcnt vmcnt(" #n ")" ::: "memory")
; #define PG8_WAIT_L(n) asm volatile("s_waitcnt lgkmcnt(" #n ")" ::: "memory")
; #define PG8_BAR __builtin_amdgcn_s_barrier()
; #define PG8_SCHED __builtin_amdgcn_sched_barrier(0)
; template <class Epi, class Sched>
; __device__ __forceinline__ void gemm_phase(LAS unsigned char* lds, const Gemm g, const Sched& S, const Epi& E) {
;     ...
;             PG8_LDA(At, 0, 1); PG8_STAGE(PG8_SB(0, 0), b2, voffB); PG8_STAGE(PG8_SB(0, 1), b2 + hstepB, voffB); PG8_STAGE(PG8_SA(0, 0), a2, voffA);
;             PG8_WAIT_V(8); PG8_WAIT_L(0); PG8_BAR; PG8_MMA(1, 0, At, B0); PG8_MMA(1, 1, At, B1); PG8_BAR; PG8_SCHED;
;             PG8_LDB(B0, 1, 0); PG8_LDB(B1, 1, 1); PG8_SCHED; PG8_LDA(At, 1, 0); PG8_STAGE(PG8_SA(0, 1), a2 + hstepA, voffA);
;             PG8_WAIT_V(8); PG8_WAIT_L(0); PG8_BAR; PG8_MMA(0, 0, At, B0); PG8_MMA(0, 1, At, B1); PG8_BAR; PG8_SCHED;
	s_setprio 1
	v_mfma_f32_16x16x32_bf16 v[92:95], v[128:131], v[160:163], v[92:95]
	v_mfma_f32_16x16x32_bf16 v[88:91], v[136:139], v[160:163], v[88:91]
	v_mfma_f32_16x16x32_bf16 v[84:87], v[128:131], v[182:185], v[84:87]
	v_mfma_f32_16x16x32_bf16 v[80:83], v[136:139], v[182:185], v[80:83]
	v_mfma_f32_16x16x32_bf16 v[76:79], v[128:131], v[190:193], v[76:79]
	v_mfma_f32_16x16x32_bf16 v[72:75], v[136:139], v[190:193], v[72:75]
	v_mfma_f32_16x16x32_bf16 v[64:67], v[128:131], v[198:201], v[64:67]
	v_mfma_f32_16x16x32_bf16 v[68:71], v[136:139], v[198:201], v[68:71]
	v_mfma_f32_16x16x32_bf16 v[92:95], v[132:135], v[164:167], v[92:95]
	v_mfma_f32_16x16x32_bf16 v[88:91], v[140:143], v[164:167], v[88:91]
	v_mfma_f32_16x16x32_bf16 v[84:87], v[132:135], v[186:189], v[84:87]
	v_mfma_f32_16x16x32_bf16 v[80:83], v[140:143], v[186:189], v[80:83]
	v_mfma_f32_16x16x32_bf16 v[76:79], v[132:135], v[194:197], v[76:79]
	v_mfma_f32_16x16x32_bf16 v[72:75], v[140:143], v[194:197], v[72:75]
	v_mfma_f32_16x16x32_bf16 v[64:67], v[132:135], v[202:205], v[64:67]
	v_mfma_f32_16x16x32_bf16 v[68:71], v[140:143], v[202:205], v[68:71]
	s_setprio 0
	s_setprio 1
	v_mfma_f32_16x16x32_bf16 v[28:31], v[144:147], v[160:163], v[28:31]
	v_mfma_f32_16x16x32_bf16 v[24:27], v[152:155], v[160:163], v[24:27]
	v_mfma_f32_16x16x32_bf16 v[20:23], v[144:147], v[182:185], v[20:23]
	v_mfma_f32_16x16x32_bf16 v[16:19], v[152:155], v[182:185], v[16:19]
	v_mfma_f32_16x16x32_bf16 v[12:15], v[144:147], v[190:193], v[12:15]
	v_mfma_f32_16x16x32_bf16 v[8:11], v[152:155], v[190:193], v[8:11]
	v_mfma_f32_16x16x32_bf16 v[0:3], v[144:147], v[198:201], v[0:3]
	v_mfma_f32_16x16x32_bf16 v[4:7], v[152:155], v[198:201], v[4:7]
	v_mfma_f32_16x16x32_bf16 v[28:31], v[148:151], v[164:167], v[28:31]
	v_mfma_f32_16x16x32_bf16 v[24:27], v[156:159], v[164:167], v[24:27]
	v_mfma_f32_16x16x32_bf16 v[20:23], v[148:151], v[186:189], v[20:23]
	v_mfma_f32_16x16x32_bf16 v[16:19], v[156:159], v[186:189], v[16:19]
	v_mfma_f32_16x16x32_bf16 v[12:15], v[148:151], v[194:197], v[12:15]
	v_mfma_f32_16x16x32_bf16 v[8:11], v[156:159], v[194:197], v[8:11]
	v_mfma_f32_16x16x32_bf16 v[0:3], v[148:151], v[202:205], v[0:3]
	v_mfma_f32_16x16x32_bf16 v[4:7], v[156:159], v[202:205], v[4:7]
	s_setprio 0
	s_barrier
	s_add_i32 s37, 0, 0x18000
	s_add_i32 s26, 0, 0x1c000
	v_add_u32_e32 v140, s37, v208
	v_add_u32_e32 v156, s26, v208
	ds_read_b128 v[128:131], v140
	ds_read_b128 v[132:135], v140 offset:1024
	ds_read_b128 v[136:139], v140 offset:2048
	ds_read_b128 v[140:143], v140 offset:3072
	ds_read_b128 v[144:147], v156
	ds_read_b128 v[148:151], v156 offset:1024
	ds_read_b128 v[152:155], v156 offset:2048
	ds_read_b128 v[156:159], v156 offset:3072
	s_add_u32 s6, s6, 0x80000
	s_addc_u32 s7, s7, 0
	s_mov_b32 m0, s29
	v_lshl_add_u64 v[224:225], s[6:7], 0, v[168:169]
	ds_read_b128 v[160:163], v211 offset:32768
	ds_read_b128 v[164:167], v211 offset:33792
	ds_read_b128 v[182:185], v211 offset:34816
	ds_read_b128 v[186:189], v211 offset:35840
	ds_read_b128 v[190:193], v211 offset:36864
	ds_read_b128 v[194:197], v211 offset:37888
	ds_read_b128 v[198:201], v211 offset:38912
	ds_read_b128 v[202:205], v211 offset:39936
	global_load_lds_dwordx4 v[224:225], off
	v_lshl_add_u64 v[224:225], s[6:7], 0, v[172:173]
	s_mov_b32 m0, s30
	s_nop 0
	global_load_lds_dwordx4 v[224:225], off
	s_waitcnt vmcnt(8) lgkmcnt(0)
	s_barrier
	s_setprio 1
	v_mfma_f32_16x16x32_bf16 v[124:127], v[128:131], v[160:163], v[124:127]
	v_mfma_f32_16x16x32_bf16 v[120:123], v[136:139], v[160:163], v[120:123]
	v_mfma_f32_16x16x32_bf16 v[116:119], v[128:131], v[182:185], v[116:119]
	v_mfma_f32_16x16x32_bf16 v[112:115], v[136:139], v[182:185], v[112:115]
	v_mfma_f32_16x16x32_bf16 v[108:111], v[128:131], v[190:193], v[108:111]
	v_mfma_f32_16x16x32_bf16 v[104:107], v[136:139], v[190:193], v[104:107]
	v_mfma_f32_16x16x32_bf16 v[96:99], v[128:131], v[198:201], v[96:99]
	v_mfma_f32_16x16x32_bf16 v[100:103], v[136:139], v[198:201], v[100:103]
	v_mfma_f32_16x16x32_bf16 v[124:127], v[132:135], v[164:167], v[124:127]
	v_mfma_f32_16x16x32_bf16 v[120:123], v[140:143], v[164:167], v[120:123]
	v_mfma_f32_16x16x32_bf16 v[116:119], v[132:135], v[186:189], v[116:119]
	v_mfma_f32_16x16x32_bf16 v[112:115], v[140:143], v[186:189], v[112:115]
	v_mfma_f32_16x16x32_bf16 v[108:111], v[132:135], v[194:197], v[108:111]
	v_mfma_f32_16x16x32_bf16 v[104:107], v[140:143], v[194:197], v[104:107]
	v_mfma_f32_16x16x32_bf16 v[96:99], v[132:135], v[202:205], v[96:99]
	v_mfma_f32_16x16x32_bf16 v[100:103], v[140:143], v[202:205], v[100:103]
	s_setprio 0
	s_setprio 1
	v_mfma_f32_16x16x32_bf16 v[60:63], v[144:147], v[160:163], v[60:63]
	v_mfma_f32_16x16x32_bf16 v[56:59], v[152:155], v[160:163], v[56:59]
	v_mfma_f32_16x16x32_bf16 v[52:55], v[144:147], v[182:185], v[52:55]
	v_mfma_f32_16x16x32_bf16 v[48:51], v[152:155], v[182:185], v[48:51]
	v_mfma_f32_16x16x32_bf16 v[44:47], v[144:147], v[190:193], v[44:47]
	v_mfma_f32_16x16x32_bf16 v[40:43], v[152:155], v[190:193], v[40:43]
	v_mfma_f32_16x16x32_bf16 v[32:35], v[144:147], v[198:201], v[32:35]
	v_mfma_f32_16x16x32_bf16 v[36:39], v[152:155], v[198:201], v[36:39]
	v_mfma_f32_16x16x32_bf16 v[60:63], v[148:151], v[164:167], v[60:63]
	v_mfma_f32_16x16x32_bf16 v[56:59], v[156:159], v[164:167], v[56:59]
	v_mfma_f32_16x16x32_bf16 v[52:55], v[148:151], v[186:189], v[52:55]
	v_mfma_f32_16x16x32_bf16 v[48:51], v[156:159], v[186:189], v[48:51]
	v_mfma_f32_16x16x32_bf16 v[44:47], v[148:151], v[194:197], v[44:47]
	v_mfma_f32_16x16x32_bf16 v[40:43], v[156:159], v[194:197], v[40:43]
	v_mfma_f32_16x16x32_bf16 v[32:35], v[148:151], v[202:205], v[32:35]
	v_mfma_f32_16x16x32_bf16 v[36:39], v[156:159], v[202:205], v[36:39]
	s_setprio 0
	s_barrier
; #define PG8_STAGE(bufoff, gbase, voff) do { _Pragma("unroll") for (int _i = 0; _i < 2; ++_i) \
;         __builtin_amdgcn_global_load_lds((const unsigned*)((const char*)(gbase) + (voff)[_i]), (LAS unsigned*)(lds + (bufoff) + ldsw + _i * 8192), 16, 0, 0); } while (0)
; #define PG8_LDA(dst, b, h) do { _Pragma("unroll") for (int m = 0; m < 4; ++m) _Pragma("unroll") for (int k = 0; k < 2; ++k) dst[m][k] = *(const LAS bf16x8*)(lds + PG8_SA(b, h) + aoff + m * 2048 + k * 1024); } while (0)
; #define PG8_MMA(ai, bj, At, Bt) do { __builtin_amdgcn_s_setprio(1); _Pragma("unroll") for (int m = 0; m < 4; ++m) _Pragma("unroll") for (int n = 0; n < 2; ++n) _Pragma("unroll") for (int k = 0; k < 2; ++k) \
;         acc[ai][bj][m][n] = __builtin_amdgcn_mfma_f32_16x16x32_bf16(Bt[n][k], At[m][k], acc[ai][bj][m][n], 0, 0, 0); __builtin_amdgcn_s_setprio(0); } while (0)
; #define PG8_WAIT_V(n) asm volatile("s_waitcnt vmcnt(" #n ")" ::: "memory")
; #define PG8_WAIT_L(n) asm volatile("s_waitcnt lgkmcnt(" #n ")" ::: "memory")
; #define PG8_BAR __builtin_amdgcn_s_barrier()
; #define PG8_SCHED __builtin_amdgcn_sched_barrier(0)
; template <class Epi, class Sched>
; __device__ __forceinline__ void gemm_phase(LAS unsigned char* lds, const Gemm g, const Sched& S, const Epi& E) {
;     ...
;             PG8_LDA(At, 1, 1); PG8_STAGE(PG8_SB(1, 0), b3, voffB); PG8_STAGE(PG8_SB(1, 1), b3 + hstepB, voffB); PG8_STAGE(PG8_SA(1, 0), a3, voffA);
;             PG8_WAIT_V(8); PG8_WAIT_L(0); PG8_BAR; PG8_MMA(1, 0, At, B0); PG8_MMA(1, 1, At, B1); PG8_BAR; PG8_SCHED;
;         }
;         if (wr == 0) PG8_BAR;
	s_add_i32 s6, s37, s14
	v_lshl_add_u64 v[216:217], v[216:217], 0, s[80:81]
	s_mov_b32 m0, s6
	ds_read_b128 v[160:163], v211 offset:49152
	ds_read_b128 v[164:167], v211 offset:50176
	ds_read_b128 v[182:185], v211 offset:51200
	ds_read_b128 v[186:189], v211 offset:52224
	ds_read_b128 v[190:193], v211 offset:53248
	ds_read_b128 v[194:197], v211 offset:54272
	ds_read_b128 v[198:201], v211 offset:55296
	ds_read_b128 v[202:205], v211 offset:56320
	global_load_lds_dwordx4 v[216:217], off
	s_add_i32 m0, s6, 0x2000
	s_add_u32 s4, s4, 0x80080
	v_lshl_add_u64 v[216:217], v[218:219], 0, s[80:81]
	s_addc_u32 s5, s5, 0
	s_add_i32 s6, s26, s14
	global_load_lds_dwordx4 v[216:217], off
	v_lshl_add_u64 v[216:217], s[4:5], 0, v[170:171]
	s_mov_b32 m0, s6
	s_nop 0
	global_load_lds_dwordx4 v[216:217], off
	v_lshl_add_u64 v[216:217], s[4:5], 0, v[174:175]
	s_add_i32 m0, s6, 0x2000
	s_nop 0
	global_load_lds_dwordx4 v[216:217], off
	v_lshl_add_u64 v[216:217], v[220:221], 0, s[80:81]
	s_mov_b32 m0, s21
	s_nop 0
	global_load_lds_dwordx4 v[216:217], off
	v_lshl_add_u64 v[216:217], v[222:223], 0, s[80:81]
	s_mov_b32 m0, s18
	s_nop 0
	global_load_lds_dwordx4 v[216:217], off
	s_waitcnt vmcnt(8) lgkmcnt(0)
	s_barrier
	s_setprio 1
	v_mfma_f32_16x16x32_bf16 v[92:95], v[128:131], v[160:163], v[92:95]
	v_mfma_f32_16x16x32_bf16 v[88:91], v[136:139], v[160:163], v[88:91]
	v_mfma_f32_16x16x32_bf16 v[84:87], v[128:131], v[182:185], v[84:87]
	v_mfma_f32_16x16x32_bf16 v[80:83], v[136:139], v[182:185], v[80:83]
	v_mfma_f32_16x16x32_bf16 v[76:79], v[128:131], v[190:193], v[76:79]
	v_mfma_f32_16x16x32_bf16 v[72:75], v[136:139], v[190:193], v[72:75]
	v_mfma_f32_16x16x32_bf16 v[64:67], v[128:131], v[198:201], v[64:67]
	v_mfma_f32_16x16x32_bf16 v[68:71], v[136:139], v[198:201], v[68:71]
	v_mfma_f32_16x16x32_bf16 v[92:95], v[132:135], v[164:167], v[92:95]
	v_mfma_f32_16x16x32_bf16 v[88:91], v[140:143], v[164:167], v[88:91]
	v_mfma_f32_16x16x32_bf16 v[84:87], v[132:135], v[186:189], v[84:87]
	v_mfma_f32_16x16x32_bf16 v[80:83], v[140:143], v[186:189], v[80:83]
	v_mfma_f32_16x16x32_bf16 v[76:79], v[132:135], v[194:197], v[76:79]
	v_mfma_f32_16x16x32_bf16 v[72:75], v[140:143], v[194:197], v[72:75]
	v_mfma_f32_16x16x32_bf16 v[64:67], v[132:135], v[202:205], v[64:67]
	v_mfma_f32_16x16x32_bf16 v[68:71], v[140:143], v[202:205], v[68:71]
	s_setprio 0
	s_setprio 1
	v_mfma_f32_16x16x32_bf16 v[28:31], v[144:147], v[160:163], v[28:31]
	v_mfma_f32_16x16x32_bf16 v[24:27], v[152:155], v[160:163], v[24:27]
	v_mfma_f32_16x16x32_bf16 v[20:23], v[144:147], v[182:185], v[20:23]
	v_mfma_f32_16x16x32_bf16 v[16:19], v[152:155], v[182:185], v[16:19]
	v_mfma_f32_16x16x32_bf16 v[12:15], v[144:147], v[190:193], v[12:15]
	v_mfma_f32_16x16x32_bf16 v[8:11], v[152:155], v[190:193], v[8:11]
	v_mfma_f32_16x16x32_bf16 v[0:3], v[144:147], v[198:201], v[0:3]
	v_mfma_f32_16x16x32_bf16 v[4:7], v[152:155], v[198:201], v[4:7]
	v_mfma_f32_16x16x32_bf16 v[28:31], v[148:151], v[164:167], v[28:31]
	v_mfma_f32_16x16x32_bf16 v[24:27], v[156:159], v[164:167], v[24:27]
	v_mfma_f32_16x16x32_bf16 v[20:23], v[148:151], v[186:189], v[20:23]
	v_mfma_f32_16x16x32_bf16 v[16:19], v[156:159], v[186:189], v[16:19]
	v_mfma_f32_16x16x32_bf16 v[12:15], v[148:151], v[194:197], v[12:15]
	v_mfma_f32_16x16x32_bf16 v[8:11], v[156:159], v[194:197], v[8:11]
	v_mfma_f32_16x16x32_bf16 v[0:3], v[148:151], v[202:205], v[0:3]
	v_mfma_f32_16x16x32_bf16 v[4:7], v[156:159], v[202:205], v[4:7]
	s_setprio 0
	s_barrier
	s_add_i32 s87, s87, 2
	s_add_u32 s0, s0, 0x100
	s_addc_u32 s1, s1, 0
	s_add_u32 s34, s34, 0x100
	s_addc_u32 s35, s35, 0
	s_cmp_gt_u32 s87, 29
	s_cbranch_scc0 .LBB0_122
	s_and_b64 vcc, exec, s[82:83]
	s_cbranch_vccz .LBB0_125
	s_barrier

; #define PG8_STAGE(bufoff, gbase, voff) do { _Pragma("unroll") for (int _i = 0; _i < 2; ++_i) \
;         __builtin_amdgcn_global_load_lds((const unsigned*)((const char*)(gbase) + (voff)[_i]), (LAS unsigned*)(lds + (bufoff) + ldsw + _i * 8192), 16, 0, 0); } while (0)
; #define PG8_LDA(dst, b, h) do { _Pragma("unroll") for (int m = 0; m < 4; ++m) _Pragma("unroll") for (int k = 0; k < 2; ++k) dst[m][k] = *(const LAS bf16x8*)(lds + PG8_SA(b, h) + aoff + m * 2048 + k * 1024); } while (0)
; #define PG8_LDB(dst, b, h) do { _Pragma("unroll") for (int n = 0; n < 2; ++n) _Pragma("unroll") for (int k = 0; k < 2; ++k) dst[n][k] = *(const LAS bf16x8*)(lds + PG8_SB(b, h) + boff + n * 2048 + k * 1024); } while (0)
; #define PG8_MMA(ai, bj, At, Bt) do { __builtin_amdgcn_s_setprio(1); _Pragma("unroll") for (int m = 0; m < 4; ++m) _Pragma("unroll") for (int n = 0; n < 2; ++n) _Pragma("unroll") for (int k = 0; k < 2; ++k) \
;         acc[ai][bj][m][n] = __builtin_amdgcn_mfma_f32_16x16x32_bf16(Bt[n][k], At[m][k], acc[ai][bj][m][n], 0, 0, 0); __builtin_amdgcn_s_setprio(0); } while (0)
; #define PG8_WAIT_V(n) asm volatile("s_waitcnt vmcnt(" #n ")" ::: "memory")
; #define PG8_WAIT_L(n) asm volatile("s_waitcnt lgkmcnt(" #n ")" ::: "memory")
; #define PG8_BAR __builtin_amdgcn_s_barrier()
; #define PG8_SCHED __builtin_amdgcn_sched_barrier(0)
; template <class Epi, class Sched>
; __device__ __forceinline__ void gemm_phase(LAS unsigned char* lds, const Gemm g, const Sched& S, const Epi& E) {
;     ...
;             const bool last = (t == nt - 2);
;             const char* a1 = cA + (size_t)(t + 1) * kstep;
;             const char* a2 = last ? nA : cA + (size_t)(t + 2) * kstep; const char* b2 = last ? nB : cB + (size_t)(t + 2) * kstep;
;             const char* a3 = a2 + kstep; const char* b3 = b2 + kstep;
;             PG8_LDB(B0, 0, 0); PG8_LDB(B1, 0, 1); PG8_SCHED; PG8_LDA(At, 0, 0); PG8_STAGE(PG8_SA(1, 1), a1 + hstepA, voffA);
;             PG8_WAIT_V(8); PG8_WAIT_L(0); PG8_BAR; PG8_MMA(0, 0, At, B0); PG8_MMA(0, 1, At, B1); PG8_BAR; PG8_SCHED;
;             PG8_LDA(At, 0, 1); PG8_STAGE(PG8_SB(0, 0), b2, voffB); PG8_STAGE(PG8_SB(0, 1), b2 + hstepB, voffB); PG8_STAGE(PG8_SA(0, 0), a2, voffA);
.LBB0_531:
	s_add_u32 s61, s76, s82
	s_addc_u32 s73, s77, s83
	s_add_u32 s86, s61, 0x100
	s_addc_u32 s87, s73, 0
	s_and_b64 s[84:85], s[80:81], exec
	s_cselect_b32 s85, s12, s87
	s_cselect_b32 s84, s13, s86
	s_add_u32 s82, s74, s82
	s_addc_u32 s83, s75, s83
	s_add_u32 s82, s82, 0x100
	s_addc_u32 s83, s83, 0
	s_and_b64 s[80:81], s[80:81], exec
	s_cselect_b32 s87, s49, s83
	s_cselect_b32 s86, s59, s82
	s_add_u32 s90, s61, 0x40080
	ds_read_b128 v[128:131], v163
	ds_read_b128 v[132:135], v163 offset:1024
	ds_read_b128 v[136:139], v163 offset:2048
	ds_read_b128 v[140:143], v163 offset:3072
	ds_read_b128 v[156:159], v164
	ds_read_b128 v[166:169], v164 offset:1024
	ds_read_b128 v[170:173], v164 offset:2048
	ds_read_b128 v[174:177], v164 offset:3072
	s_addc_u32 s91, s73, 0
	s_add_i32 s97, s33, s14
	s_add_i32 m0, s15, 0xc000
	s_add_i32 vcc_lo, s15, 0xe000
	s_add_i32 s94, s97, 0x2000
	s_add_u32 s88, s86, 0x10000
	s_addc_u32 s89, s87, 0
	s_add_i32 s96, s36, s14
	s_add_i32 s95, s96, 0x2000
	s_add_u32 s82, s84, 0x40000
	s_addc_u32 s83, s85, 0
	s_add_i32 s93, s37, s14
	s_add_i32 s73, s93, 0x2000
	s_add_u32 s80, s86, 0x10080
	s_addc_u32 s81, s87, 0
	s_add_i32 s92, s26, s14
	s_add_i32 s61, s92, 0x2000
	v_lshl_add_u64 v[210:211], s[90:91], 0, v[150:151]
	ds_read_b128 v[178:181], v165
	ds_read_b128 v[182:185], v165 offset:1024
	ds_read_b128 v[186:189], v165 offset:2048
	ds_read_b128 v[190:193], v165 offset:3072
	ds_read_b128 v[194:197], v165 offset:4096
	ds_read_b128 v[198:201], v165 offset:5120
	ds_read_b128 v[202:205], v165 offset:6144
	ds_read_b128 v[206:209], v165 offset:7168
	global_load_lds_dwordx4 v[210:211], off
	v_lshl_add_u64 v[210:211], s[90:91], 0, v[146:147]
	s_mov_b32 m0, vcc_lo
	s_nop 0
	global_load_lds_dwordx4 v[210:211], off
	s_waitcnt vmcnt(8) lgkmcnt(0)
	s_barrier
	s_setprio 1
	v_mfma_f32_16x16x32_bf16 v[124:127], v[128:131], v[178:181], v[124:127]
	v_mfma_f32_16x16x32_bf16 v[120:123], v[136:139], v[178:181], v[120:123]
	v_mfma_f32_16x16x32_bf16 v[116:119], v[128:131], v[186:189], v[116:119]
	v_mfma_f32_16x16x32_bf16 v[112:115], v[136:139], v[186:189], v[112:115]
	v_mfma_f32_16x16x32_bf16 v[108:111], v[128:131], v[194:197], v[108:111]
	v_mfma_f32_16x16x32_bf16 v[100:103], v[136:139], v[194:197], v[100:103]
	v_mfma_f32_16x16x32_bf16 v[92:95], v[128:131], v[202:205], v[92:95]
	v_mfma_f32_16x16x32_bf16 v[84:87], v[136:139], v[202:205], v[84:87]
	v_mfma_f32_16x16x32_bf16 v[124:127], v[132:135], v[182:185], v[124:127]
	v_mfma_f32_16x16x32_bf16 v[120:123], v[140:143], v[182:185], v[120:123]
	v_mfma_f32_16x16x32_bf16 v[116:119], v[132:135], v[190:193], v[116:119]
	v_mfma_f32_16x16x32_bf16 v[112:115], v[140:143], v[190:193], v[112:115]
	v_mfma_f32_16x16x32_bf16 v[108:111], v[132:135], v[198:201], v[108:111]
	v_mfma_f32_16x16x32_bf16 v[100:103], v[140:143], v[198:201], v[100:103]
	v_mfma_f32_16x16x32_bf16 v[92:95], v[132:135], v[206:209], v[92:95]
	v_mfma_f32_16x16x32_bf16 v[84:87], v[140:143], v[206:209], v[84:87]
	s_setprio 0
	s_setprio 1
	v_mfma_f32_16x16x32_bf16 v[104:107], v[156:159], v[178:181], v[104:107]
	v_mfma_f32_16x16x32_bf16 v[96:99], v[170:173], v[178:181], v[96:99]
	v_mfma_f32_16x16x32_bf16 v[88:91], v[156:159], v[186:189], v[88:91]
	v_mfma_f32_16x16x32_bf16 v[80:83], v[170:173], v[186:189], v[80:83]
	v_mfma_f32_16x16x32_bf16 v[76:79], v[156:159], v[194:197], v[76:79]
	v_mfma_f32_16x16x32_bf16 v[72:75], v[170:173], v[194:197], v[72:75]
	v_mfma_f32_16x16x32_bf16 v[68:71], v[156:159], v[202:205], v[68:71]
	v_mfma_f32_16x16x32_bf16 v[64:67], v[170:173], v[202:205], v[64:67]
	v_mfma_f32_16x16x32_bf16 v[104:107], v[166:169], v[182:185], v[104:107]
	v_mfma_f32_16x16x32_bf16 v[96:99], v[174:177], v[182:185], v[96:99]
	v_mfma_f32_16x16x32_bf16 v[88:91], v[166:169], v[190:193], v[88:91]
	v_mfma_f32_16x16x32_bf16 v[80:83], v[174:177], v[190:193], v[80:83]
	v_mfma_f32_16x16x32_bf16 v[76:79], v[166:169], v[198:201], v[76:79]
	v_mfma_f32_16x16x32_bf16 v[72:75], v[174:177], v[198:201], v[72:75]
	v_mfma_f32_16x16x32_bf16 v[68:71], v[166:169], v[206:209], v[68:71]
	v_mfma_f32_16x16x32_bf16 v[64:67], v[174:177], v[206:209], v[64:67]
	s_setprio 0
	s_barrier
	s_mov_b32 m0, s97
	v_lshl_add_u64 v[210:211], s[86:87], 0, v[148:149]
	ds_read_b128 v[178:181], v165 offset:16384
	ds_read_b128 v[182:185], v165 offset:17408
	ds_read_b128 v[186:189], v165 offset:18432
	ds_read_b128 v[190:193], v165 offset:19456
	ds_read_b128 v[194:197], v165 offset:20480
	ds_read_b128 v[198:201], v165 offset:21504
	ds_read_b128 v[202:205], v165 offset:22528
	ds_read_b128 v[206:209], v165 offset:23552
	global_load_lds_dwordx4 v[210:211], off
	v_lshl_add_u64 v[216:217], s[86:87], 0, v[144:145]
	s_mov_b32 m0, s94
	v_lshl_add_u64 v[218:219], s[88:89], 0, v[148:149]
	global_load_lds_dwordx4 v[216:217], off
	s_mov_b32 m0, s96
	v_lshl_add_u64 v[220:221], s[84:85], 0, v[146:147]
	global_load_lds_dwordx4 v[218:219], off
	v_lshl_add_u64 v[218:219], s[88:89], 0, v[144:145]
	s_mov_b32 m0, s95
	s_nop 0
	global_load_lds_dwordx4 v[218:219], off
	v_lshl_add_u64 v[218:219], s[84:85], 0, v[150:151]
	s_mov_b32 m0, s15
	s_nop 0
	global_load_lds_dwordx4 v[218:219], off
	s_mov_b32 m0, s18
	s_nop 0
	global_load_lds_dwordx4 v[220:221], off
	s_waitcnt vmcnt(8) lgkmcnt(0)
	s_barrier
; #define PG8_STAGE(bufoff, gbase, voff) do { _Pragma("unroll") for (int _i = 0; _i < 2; ++_i) \
;         __builtin_amdgcn_global_load_lds((const unsigned*)((const char*)(gbase) + (voff)[_i]), (LAS unsigned*)(lds + (bufoff) + ldsw + _i * 8192), 16, 0, 0); } while (0)
; #define PG8_LDA(dst, b, h) do { _Pragma("unroll") for (int m = 0; m < 4; ++m) _Pragma("unroll") for (int k = 0; k < 2; ++k) dst[m][k] = *(const LAS bf16x8*)(lds + PG8_SA(b, h) + aoff + m * 2048 + k * 1024); } while (0)
; #define PG8_LDB(dst, b, h) do { _Pragma("unroll") for (int n = 0; n < 2; ++n) _Pragma("unroll") for (int k = 0; k < 2; ++k) dst[n][k] = *(const LAS bf16x8*)(lds + PG8_SB(b, h) + boff + n * 2048 + k * 1024); } while (0)
; #define PG8_MMA(ai, bj, At, Bt) do { __builtin_amdgcn_s_setprio(1); _Pragma("unroll") for (int m = 0; m < 4; ++m) _Pragma("unroll") for (int n = 0; n < 2; ++n) _Pragma("unroll") for (int k = 0; k < 2; ++k) \
;         acc[ai][bj][m][n] = __builtin_amdgcn_mfma_f32_16x16x32_bf16(Bt[n][k], At[m][k], acc[ai][bj][m][n], 0, 0, 0); __builtin_amdgcn_s_setprio(0); } while (0)
; #define PG8_WAIT_V(n) asm volatile("s_waitcnt vmcnt(" #n ")" ::: "memory")
; #define PG8_WAIT_L(n) asm volatile("s_waitcnt lgkmcnt(" #n ")" ::: "memory")
; #define PG8_BAR __builtin_amdgcn_s_barrier()
; #define PG8_SCHED __builtin_amdgcn_sched_barrier(0)
; template <class Epi, class Sched>
; __device__ __forceinline__ void gemm_phase(LAS unsigned char* lds, const Gemm g, const Sched& S, const Epi& E) {
;     ...
;             PG8_LDA(At, 0, 1); PG8_STAGE(PG8_SB(0, 0), b2, voffB); PG8_STAGE(PG8_SB(0, 1), b2 + hstepB, voffB); PG8_STAGE(PG8_SA(0, 0), a2, voffA);
;             PG8_WAIT_V(8); PG8_WAIT_L(0); PG8_BAR; PG8_MMA(1, 0, At, B0); PG8_MMA(1, 1, At, B1); PG8_BAR; PG8_SCHED;
;             PG8_LDB(B0, 1, 0); PG8_LDB(B1, 1, 1); PG8_SCHED; PG8_LDA(At, 1, 0); PG8_STAGE(PG8_SA(0, 1), a2 + hstepA, voffA);
;             PG8_WAIT_V(8); PG8_WAIT_L(0); PG8_BAR; PG8_MMA(0, 0, At, B0); PG8_MMA(0, 1, At, B1); PG8_BAR; PG8_SCHED;
	s_setprio 1
	v_mfma_f32_16x16x32_bf16 v[60:63], v[128:131], v[178:181], v[60:63]
	v_mfma_f32_16x16x32_bf16 v[56:59], v[136:139], v[178:181], v[56:59]
	v_mfma_f32_16x16x32_bf16 v[48:51], v[128:131], v[186:189], v[48:51]
	v_mfma_f32_16x16x32_bf16 v[40:43], v[136:139], v[186:189], v[40:43]
	v_mfma_f32_16x16x32_bf16 v[32:35], v[128:131], v[194:197], v[32:35]
	v_mfma_f32_16x16x32_bf16 v[24:27], v[136:139], v[194:197], v[24:27]
	v_mfma_f32_16x16x32_bf16 v[16:19], v[128:131], v[202:205], v[16:19]
	v_mfma_f32_16x16x32_bf16 v[8:11], v[136:139], v[202:205], v[8:11]
	v_mfma_f32_16x16x32_bf16 v[60:63], v[132:135], v[182:185], v[60:63]
	v_mfma_f32_16x16x32_bf16 v[56:59], v[140:143], v[182:185], v[56:59]
	v_mfma_f32_16x16x32_bf16 v[48:51], v[132:135], v[190:193], v[48:51]
	v_mfma_f32_16x16x32_bf16 v[40:43], v[140:143], v[190:193], v[40:43]
	v_mfma_f32_16x16x32_bf16 v[32:35], v[132:135], v[198:201], v[32:35]
	v_mfma_f32_16x16x32_bf16 v[24:27], v[140:143], v[198:201], v[24:27]
	v_mfma_f32_16x16x32_bf16 v[16:19], v[132:135], v[206:209], v[16:19]
	v_mfma_f32_16x16x32_bf16 v[8:11], v[140:143], v[206:209], v[8:11]
	s_setprio 0
	s_setprio 1
	v_mfma_f32_16x16x32_bf16 v[52:55], v[156:159], v[178:181], v[52:55]
	v_mfma_f32_16x16x32_bf16 v[44:47], v[170:173], v[178:181], v[44:47]
	v_mfma_f32_16x16x32_bf16 v[36:39], v[156:159], v[186:189], v[36:39]
	v_mfma_f32_16x16x32_bf16 v[28:31], v[170:173], v[186:189], v[28:31]
	v_mfma_f32_16x16x32_bf16 v[20:23], v[156:159], v[194:197], v[20:23]
	v_mfma_f32_16x16x32_bf16 v[12:15], v[170:173], v[194:197], v[12:15]
	v_mfma_f32_16x16x32_bf16 v[4:7], v[156:159], v[202:205], v[4:7]
	v_mfma_f32_16x16x32_bf16 v[0:3], v[170:173], v[202:205], v[0:3]
	v_mfma_f32_16x16x32_bf16 v[52:55], v[166:169], v[182:185], v[52:55]
	v_mfma_f32_16x16x32_bf16 v[44:47], v[174:177], v[182:185], v[44:47]
	v_mfma_f32_16x16x32_bf16 v[36:39], v[166:169], v[190:193], v[36:39]
	v_mfma_f32_16x16x32_bf16 v[28:31], v[174:177], v[190:193], v[28:31]
	v_mfma_f32_16x16x32_bf16 v[20:23], v[166:169], v[198:201], v[20:23]
	v_mfma_f32_16x16x32_bf16 v[12:15], v[174:177], v[198:201], v[12:15]
	v_mfma_f32_16x16x32_bf16 v[4:7], v[166:169], v[206:209], v[4:7]
	v_mfma_f32_16x16x32_bf16 v[0:3], v[174:177], v[206:209], v[0:3]
	s_setprio 0
	s_barrier
	v_add_u32_e32 v140, s37, v162
	v_add_u32_e32 v174, s26, v162
	ds_read_b128 v[128:131], v140
	ds_read_b128 v[132:135], v140 offset:1024
	ds_read_b128 v[136:139], v140 offset:2048
	ds_read_b128 v[140:143], v140 offset:3072
	ds_read_b128 v[156:159], v174
	ds_read_b128 v[166:169], v174 offset:1024
	ds_read_b128 v[170:173], v174 offset:2048
	ds_read_b128 v[174:177], v174 offset:3072
	s_mov_b32 m0, s19
	v_lshl_add_u64 v[222:223], s[82:83], 0, v[150:151]
	ds_read_b128 v[178:181], v165 offset:32768
	ds_read_b128 v[182:185], v165 offset:33792
	ds_read_b128 v[186:189], v165 offset:34816
	ds_read_b128 v[190:193], v165 offset:35840
	ds_read_b128 v[194:197], v165 offset:36864
	ds_read_b128 v[198:201], v165 offset:37888
	ds_read_b128 v[202:205], v165 offset:38912
	ds_read_b128 v[206:209], v165 offset:39936
	global_load_lds_dwordx4 v[222:223], off
	v_lshl_add_u64 v[222:223], s[82:83], 0, v[146:147]
	s_mov_b32 m0, s21
	s_nop 0
	global_load_lds_dwordx4 v[222:223], off
	s_waitcnt vmcnt(8) lgkmcnt(0)
	s_barrier
	s_setprio 1
	v_mfma_f32_16x16x32_bf16 v[124:127], v[128:131], v[178:181], v[124:127]
	v_mfma_f32_16x16x32_bf16 v[120:123], v[136:139], v[178:181], v[120:123]
	v_mfma_f32_16x16x32_bf16 v[116:119], v[128:131], v[186:189], v[116:119]
	v_mfma_f32_16x16x32_bf16 v[112:115], v[136:139], v[186:189], v[112:115]
	v_mfma_f32_16x16x32_bf16 v[108:111], v[128:131], v[194:197], v[108:111]
	v_mfma_f32_16x16x32_bf16 v[100:103], v[136:139], v[194:197], v[100:103]
	v_mfma_f32_16x16x32_bf16 v[92:95], v[128:131], v[202:205], v[92:95]
	v_mfma_f32_16x16x32_bf16 v[84:87], v[136:139], v[202:205], v[84:87]
	v_mfma_f32_16x16x32_bf16 v[124:127], v[132:135], v[182:185], v[124:127]
	v_mfma_f32_16x16x32_bf16 v[120:123], v[140:143], v[182:185], v[120:123]
	v_mfma_f32_16x16x32_bf16 v[116:119], v[132:135], v[190:193], v[116:119]
	v_mfma_f32_16x16x32_bf16 v[112:115], v[140:143], v[190:193], v[112:115]
	v_mfma_f32_16x16x32_bf16 v[108:111], v[132:135], v[198:201], v[108:111]
	v_mfma_f32_16x16x32_bf16 v[100:103], v[140:143], v[198:201], v[100:103]
	v_mfma_f32_16x16x32_bf16 v[92:95], v[132:135], v[206:209], v[92:95]
	v_mfma_f32_16x16x32_bf16 v[84:87], v[140:143], v[206:209], v[84:87]
	s_setprio 0
	s_setprio 1
	v_mfma_f32_16x16x32_bf16 v[104:107], v[156:159], v[178:181], v[104:107]
	v_mfma_f32_16x16x32_bf16 v[96:99], v[170:173], v[178:181], v[96:99]
	v_mfma_f32_16x16x32_bf16 v[88:91], v[156:159], v[186:189], v[88:91]
	v_mfma_f32_16x16x32_bf16 v[80:83], v[170:173], v[186:189], v[80:83]
	v_mfma_f32_16x16x32_bf16 v[76:79], v[156:159], v[194:197], v[76:79]
	v_mfma_f32_16x16x32_bf16 v[72:75], v[170:173], v[194:197], v[72:75]
	v_mfma_f32_16x16x32_bf16 v[68:71], v[156:159], v[202:205], v[68:71]
	v_mfma_f32_16x16x32_bf16 v[64:67], v[170:173], v[202:205], v[64:67]
	v_mfma_f32_16x16x32_bf16 v[104:107], v[166:169], v[182:185], v[104:107]
	v_mfma_f32_16x16x32_bf16 v[96:99], v[174:177], v[182:185], v[96:99]
	v_mfma_f32_16x16x32_bf16 v[88:91], v[166:169], v[190:193], v[88:91]
	v_mfma_f32_16x16x32_bf16 v[80:83], v[174:177], v[190:193], v[80:83]
	v_mfma_f32_16x16x32_bf16 v[76:79], v[166:169], v[198:201], v[76:79]
	v_mfma_f32_16x16x32_bf16 v[72:75], v[174:177], v[198:201], v[72:75]
	v_mfma_f32_16x16x32_bf16 v[68:71], v[166:169], v[206:209], v[68:71]
	v_mfma_f32_16x16x32_bf16 v[64:67], v[174:177], v[206:209], v[64:67]
	s_setprio 0
	s_barrier
; #define PG8_STAGE(bufoff, gbase, voff) do { _Pragma("unroll") for (int _i = 0; _i < 2; ++_i) \
;         __builtin_amdgcn_global_load_lds((const unsigned*)((const char*)(gbase) + (voff)[_i]), (LAS unsigned*)(lds + (bufoff) + ldsw + _i * 8192), 16, 0, 0); } while (0)
; #define PG8_LDA(dst, b, h) do { _Pragma("unroll") for (int m = 0; m < 4; ++m) _Pragma("unroll") for (int k = 0; k < 2; ++k) dst[m][k] = *(const LAS bf16x8*)(lds + PG8_SA(b, h) + aoff + m * 2048 + k * 1024); } while (0)
; #define PG8_MMA(ai, bj, At, Bt) do { __builtin_amdgcn_s_setprio(1); _Pragma("unroll") for (int m = 0; m < 4; ++m) _Pragma("unroll") for (int n = 0; n < 2; ++n) _Pragma("unroll") for (int k = 0; k < 2; ++k) \
;         acc[ai][bj][m][n] = __builtin_amdgcn_mfma_f32_16x16x32_bf16(Bt[n][k], At[m][k], acc[ai][bj][m][n], 0, 0, 0); __builtin_amdgcn_s_setprio(0); } while (0)
; #define PG8_WAIT_V(n) asm volatile("s_waitcnt vmcnt(" #n ")" ::: "memory")
; #define PG8_WAIT_L(n) asm volatile("s_waitcnt lgkmcnt(" #n ")" ::: "memory")
; #define PG8_BAR __builtin_amdgcn_s_barrier()
; #define PG8_SCHED __builtin_amdgcn_sched_barrier(0)
; template <class Epi, class Sched>
; __device__ __forceinline__ void gemm_phase(LAS unsigned char* lds, const Gemm g, const Sched& S, const Epi& E) {
;     ...
;             PG8_LDA(At, 1, 1); PG8_STAGE(PG8_SB(1, 0), b3, voffB); PG8_STAGE(PG8_SB(1, 1), b3 + hstepB, voffB); PG8_STAGE(PG8_SA(1, 0), a3, voffA);
;             PG8_WAIT_V(8); PG8_WAIT_L(0); PG8_BAR; PG8_MMA(1, 0, At, B0); PG8_MMA(1, 1, At, B1); PG8_BAR; PG8_SCHED;
;         }
;         if (wr == 0) PG8_BAR;
	s_mov_b32 m0, s93
	v_lshl_add_u64 v[210:211], v[210:211], 0, s[8:9]
	ds_read_b128 v[178:181], v165 offset:49152
	ds_read_b128 v[182:185], v165 offset:50176
	ds_read_b128 v[186:189], v165 offset:51200
	ds_read_b128 v[190:193], v165 offset:52224
	ds_read_b128 v[194:197], v165 offset:53248
	ds_read_b128 v[198:201], v165 offset:54272
	ds_read_b128 v[202:205], v165 offset:55296
	ds_read_b128 v[206:209], v165 offset:56320
	global_load_lds_dwordx4 v[210:211], off
	v_lshl_add_u64 v[210:211], v[216:217], 0, s[8:9]
	s_mov_b32 m0, s73
	s_nop 0
	global_load_lds_dwordx4 v[210:211], off
	v_lshl_add_u64 v[210:211], s[80:81], 0, v[148:149]
	s_mov_b32 m0, s92
	s_nop 0
	global_load_lds_dwordx4 v[210:211], off
	v_lshl_add_u64 v[210:211], s[80:81], 0, v[144:145]
	s_mov_b32 m0, s61
	s_nop 0
	global_load_lds_dwordx4 v[210:211], off
	v_lshl_add_u64 v[210:211], v[218:219], 0, s[8:9]
	s_mov_b32 m0, s34
	s_nop 0
	global_load_lds_dwordx4 v[210:211], off
	v_lshl_add_u64 v[210:211], v[220:221], 0, s[8:9]
	s_mov_b32 m0, s35
	s_nop 0
	global_load_lds_dwordx4 v[210:211], off
	s_waitcnt vmcnt(8) lgkmcnt(0)
	s_barrier
	s_setprio 1
	v_mfma_f32_16x16x32_bf16 v[60:63], v[128:131], v[178:181], v[60:63]
	v_mfma_f32_16x16x32_bf16 v[56:59], v[136:139], v[178:181], v[56:59]
	v_mfma_f32_16x16x32_bf16 v[48:51], v[128:131], v[186:189], v[48:51]
	v_mfma_f32_16x16x32_bf16 v[40:43], v[136:139], v[186:189], v[40:43]
	v_mfma_f32_16x16x32_bf16 v[32:35], v[128:131], v[194:197], v[32:35]
	v_mfma_f32_16x16x32_bf16 v[24:27], v[136:139], v[194:197], v[24:27]
	v_mfma_f32_16x16x32_bf16 v[16:19], v[128:131], v[202:205], v[16:19]
	v_mfma_f32_16x16x32_bf16 v[8:11], v[136:139], v[202:205], v[8:11]
	v_mfma_f32_16x16x32_bf16 v[60:63], v[132:135], v[182:185], v[60:63]
	v_mfma_f32_16x16x32_bf16 v[56:59], v[140:143], v[182:185], v[56:59]
	v_mfma_f32_16x16x32_bf16 v[48:51], v[132:135], v[190:193], v[48:51]
	v_mfma_f32_16x16x32_bf16 v[40:43], v[140:143], v[190:193], v[40:43]
	v_mfma_f32_16x16x32_bf16 v[32:35], v[132:135], v[198:201], v[32:35]
	v_mfma_f32_16x16x32_bf16 v[24:27], v[140:143], v[198:201], v[24:27]
	v_mfma_f32_16x16x32_bf16 v[16:19], v[132:135], v[206:209], v[16:19]
	v_mfma_f32_16x16x32_bf16 v[8:11], v[140:143], v[206:209], v[8:11]
	s_setprio 0
	s_setprio 1
	v_mfma_f32_16x16x32_bf16 v[52:55], v[156:159], v[178:181], v[52:55]
	v_mfma_f32_16x16x32_bf16 v[44:47], v[170:173], v[178:181], v[44:47]
	v_mfma_f32_16x16x32_bf16 v[36:39], v[156:159], v[186:189], v[36:39]
	v_mfma_f32_16x16x32_bf16 v[28:31], v[170:173], v[186:189], v[28:31]
	v_mfma_f32_16x16x32_bf16 v[20:23], v[156:159], v[194:197], v[20:23]
	v_mfma_f32_16x16x32_bf16 v[12:15], v[170:173], v[194:197], v[12:15]
	v_mfma_f32_16x16x32_bf16 v[4:7], v[156:159], v[202:205], v[4:7]
	v_mfma_f32_16x16x32_bf16 v[0:3], v[170:173], v[202:205], v[0:3]
	v_mfma_f32_16x16x32_bf16 v[52:55], v[166:169], v[182:185], v[52:55]
	v_mfma_f32_16x16x32_bf16 v[44:47], v[174:177], v[182:185], v[44:47]
	v_mfma_f32_16x16x32_bf16 v[36:39], v[166:169], v[190:193], v[36:39]
	v_mfma_f32_16x16x32_bf16 v[28:31], v[174:177], v[190:193], v[28:31]
	v_mfma_f32_16x16x32_bf16 v[20:23], v[166:169], v[198:201], v[20:23]
	v_mfma_f32_16x16x32_bf16 v[12:15], v[174:177], v[198:201], v[12:15]
	v_mfma_f32_16x16x32_bf16 v[4:7], v[166:169], v[206:209], v[4:7]
	v_mfma_f32_16x16x32_bf16 v[0:3], v[174:177], v[206:209], v[0:3]
	s_setprio 0
	s_barrier
	s_andn2_b64 vcc, exec, s[78:79]
	s_mov_b64 s[80:81], -1
	s_mov_b64 s[78:79], 0
	s_mov_b64 s[82:83], 0x100
	s_cbranch_vccz .LBB0_531
	v_readlane_b32 s80, v248, 11
	s_and_b64 vcc, exec, s[56:57]
	v_readlane_b32 s81, v248, 12
	v_readlane_b32 s82, v248, 13
	v_readlane_b32 s83, v248, 14
	v_readlane_b32 s84, v248, 15
	v_readlane_b32 s85, v248, 16
	v_readlane_b32 s86, v248, 17
	v_readlane_b32 s87, v248, 18
	v_readlane_b32 s88, v248, 19
	v_readlane_b32 s89, v248, 20
	v_readlane_b32 s90, v248, 21
	v_readlane_b32 s91, v248, 22
	v_readlane_b32 s92, v248, 23
	v_readlane_b32 s93, v248, 24
	v_readlane_b32 s94, v248, 25
	v_readlane_b32 s95, v248, 26
	s_cbranch_vccz .LBB0_534
	s_barrier

; #define PG8_STAGE(bufoff, gbase, voff) do { _Pragma("unroll") for (int _i = 0; _i < 2; ++_i) \
;         __builtin_amdgcn_global_load_lds((const unsigned*)((const char*)(gbase) + (voff)[_i]), (LAS unsigned*)(lds + (bufoff) + ldsw + _i * 8192), 16, 0, 0); } while (0)
; #define PG8_LDA(dst, b, h) do { _Pragma("unroll") for (int m = 0; m < 4; ++m) _Pragma("unroll") for (int k = 0; k < 2; ++k) dst[m][k] = *(const LAS bf16x8*)(lds + PG8_SA(b, h) + aoff + m * 2048 + k * 1024); } while (0)
; #define PG8_LDB(dst, b, h) do { _Pragma("unroll") for (int n = 0; n < 2; ++n) _Pragma("unroll") for (int k = 0; k < 2; ++k) dst[n][k] = *(const LAS bf16x8*)(lds + PG8_SB(b, h) + boff + n * 2048 + k * 1024); } while (0)
; #define PG8_MMA(ai, bj, At, Bt) do { __builtin_amdgcn_s_setprio(1); _Pragma("unroll") for (int m = 0; m < 4; ++m) _Pragma("unroll") for (int n = 0; n < 2; ++n) _Pragma("unroll") for (int k = 0; k < 2; ++k) \
;         acc[ai][bj][m][n] = __builtin_amdgcn_mfma_f32_16x16x32_bf16(Bt[n][k], At[m][k], acc[ai][bj][m][n], 0, 0, 0); __builtin_amdgcn_s_setprio(0); } while (0)
; #define PG8_WAIT_V(n) asm volatile("s_waitcnt vmcnt(" #n ")" ::: "memory")
; #define PG8_WAIT_L(n) asm volatile("s_waitcnt lgkmcnt(" #n ")" ::: "memory")
; #define PG8_BAR __builtin_amdgcn_s_barrier()
; #define PG8_SCHED __builtin_amdgcn_sched_barrier(0)
; template <class Epi, class Sched>
; __device__ __forceinline__ void gemm_phase(LAS unsigned char* lds, const Gemm g, const Sched& S, const Epi& E) {
;     ...
;             const bool last = (t == nt - 2);
;             const char* a1 = cA + (size_t)(t + 1) * kstep;
;             const char* a2 = last ? nA : cA + (size_t)(t + 2) * kstep; const char* b2 = last ? nB : cB + (size_t)(t + 2) * kstep;
;             const char* a3 = a2 + kstep; const char* b3 = b2 + kstep;
;             PG8_LDB(B0, 0, 0); PG8_LDB(B1, 0, 1); PG8_SCHED; PG8_LDA(At, 0, 0); PG8_STAGE(PG8_SA(1, 1), a1 + hstepA, voffA);
;             PG8_WAIT_V(8); PG8_WAIT_L(0); PG8_BAR; PG8_MMA(0, 0, At, B0); PG8_MMA(0, 1, At, B1); PG8_BAR; PG8_SCHED;
;             PG8_LDA(At, 0, 1); PG8_STAGE(PG8_SB(0, 0), b2, voffB); PG8_STAGE(PG8_SB(0, 1), b2 + hstepB, voffB); PG8_STAGE(PG8_SA(0, 0), a2, voffA);
.LBB0_553:
	s_add_u32 s35, s78, s82
	s_addc_u32 s45, s79, s83
	s_add_u32 s63, s35, 0x100
	s_addc_u32 s65, s45, 0
	s_and_b64 s[48:49], s[80:81], exec
	s_cselect_b32 s85, s71, s65
	s_cselect_b32 s84, s70, s63
	s_add_u32 s48, s76, s82
	s_addc_u32 s49, s77, s83
	s_add_u32 s63, s48, 0x100
	s_addc_u32 s65, s49, 0
	s_and_b64 s[48:49], s[80:81], exec
	s_cselect_b32 s87, s31, s65
	s_cselect_b32 s86, s34, s63
	s_add_u32 s90, s35, 0x80080
	ds_read_b128 v[64:67], v218
	ds_read_b128 v[68:71], v218 offset:1024
	ds_read_b128 v[72:75], v218 offset:2048
	ds_read_b128 v[80:83], v218 offset:3072
	ds_read_b128 v[88:91], v219
	ds_read_b128 v[92:95], v219 offset:1024
	ds_read_b128 v[100:103], v219 offset:2048
	ds_read_b128 v[108:111], v219 offset:3072
	s_addc_u32 s91, s45, 0
	s_add_i32 s75, s33, s12
	s_add_i32 m0, s13, 0xc000
	s_add_i32 s92, s13, 0xe000
	s_add_i32 s63, s75, 0x2000
	s_add_u32 s88, s86, 0x10000
	s_addc_u32 s89, s87, 0
	s_add_i32 s67, s36, s12
	s_add_i32 s65, s67, 0x2000
	s_add_u32 s82, s84, 0x80000
	s_addc_u32 s83, s85, 0
	s_add_i32 s49, s37, s12
	s_add_i32 s45, s49, 0x2000
	s_add_u32 s80, s86, 0x10080
	s_addc_u32 s81, s87, 0
	s_add_i32 s48, s26, s12
	s_add_i32 s35, s48, 0x2000
	v_lshl_add_u64 v[204:205], s[90:91], 0, v[190:191]
	ds_read_b128 v[128:131], v220
	ds_read_b128 v[148:151], v220 offset:1024
	ds_read_b128 v[164:167], v220 offset:2048
	ds_read_b128 v[172:175], v220 offset:3072
	ds_read_b128 v[176:179], v220 offset:4096
	ds_read_b128 v[180:183], v220 offset:5120
	ds_read_b128 v[196:199], v220 offset:6144
	ds_read_b128 v[200:203], v220 offset:7168
	global_load_lds_dwordx4 v[204:205], off
	v_lshl_add_u64 v[204:205], s[90:91], 0, v[186:187]
	s_mov_b32 m0, s92
	s_nop 0
	global_load_lds_dwordx4 v[204:205], off
	s_waitcnt vmcnt(8) lgkmcnt(0)
	s_barrier
	s_setprio 1
	v_mfma_f32_16x16x32_bf16 v[168:171], v[64:67], v[128:131], v[168:171]
	v_mfma_f32_16x16x32_bf16 v[156:159], v[72:75], v[128:131], v[156:159]
	v_mfma_f32_16x16x32_bf16 v[144:147], v[64:67], v[164:167], v[144:147]
	v_mfma_f32_16x16x32_bf16 v[136:139], v[72:75], v[164:167], v[136:139]
	v_mfma_f32_16x16x32_bf16 v[124:127], v[64:67], v[176:179], v[124:127]
	v_mfma_f32_16x16x32_bf16 v[116:119], v[72:75], v[176:179], v[116:119]
	v_mfma_f32_16x16x32_bf16 v[104:107], v[64:67], v[196:199], v[104:107]
	v_mfma_f32_16x16x32_bf16 v[84:87], v[72:75], v[196:199], v[84:87]
	v_mfma_f32_16x16x32_bf16 v[168:171], v[68:71], v[148:151], v[168:171]
	v_mfma_f32_16x16x32_bf16 v[156:159], v[80:83], v[148:151], v[156:159]
	v_mfma_f32_16x16x32_bf16 v[144:147], v[68:71], v[172:175], v[144:147]
	v_mfma_f32_16x16x32_bf16 v[136:139], v[80:83], v[172:175], v[136:139]
	v_mfma_f32_16x16x32_bf16 v[124:127], v[68:71], v[180:183], v[124:127]
	v_mfma_f32_16x16x32_bf16 v[116:119], v[80:83], v[180:183], v[116:119]
	v_mfma_f32_16x16x32_bf16 v[104:107], v[68:71], v[200:203], v[104:107]
	v_mfma_f32_16x16x32_bf16 v[84:87], v[80:83], v[200:203], v[84:87]
	s_setprio 0
	s_setprio 1
	v_mfma_f32_16x16x32_bf16 v[160:163], v[88:91], v[128:131], v[160:163]
	v_mfma_f32_16x16x32_bf16 v[140:143], v[88:91], v[164:167], v[140:143]
	v_mfma_f32_16x16x32_bf16 v[132:135], v[100:103], v[164:167], v[132:135]
	v_mfma_f32_16x16x32_bf16 v[120:123], v[88:91], v[176:179], v[120:123]
	v_mfma_f32_16x16x32_bf16 v[112:115], v[100:103], v[176:179], v[112:115]
	v_mfma_f32_16x16x32_bf16 v[96:99], v[88:91], v[196:199], v[96:99]
	v_mfma_f32_16x16x32_bf16 v[76:79], v[100:103], v[196:199], v[76:79]
	v_mfma_f32_16x16x32_bf16 v[160:163], v[92:95], v[148:151], v[160:163]
	v_mfma_f32_16x16x32_bf16 v[128:131], v[100:103], v[128:131], v[152:155]
	v_mfma_f32_16x16x32_bf16 v[140:143], v[92:95], v[172:175], v[140:143]
	v_mfma_f32_16x16x32_bf16 v[132:135], v[108:111], v[172:175], v[132:135]
	v_mfma_f32_16x16x32_bf16 v[120:123], v[92:95], v[180:183], v[120:123]
	v_mfma_f32_16x16x32_bf16 v[112:115], v[108:111], v[180:183], v[112:115]
	v_mfma_f32_16x16x32_bf16 v[96:99], v[92:95], v[200:203], v[96:99]
	v_mfma_f32_16x16x32_bf16 v[76:79], v[108:111], v[200:203], v[76:79]
	v_mfma_f32_16x16x32_bf16 v[128:131], v[108:111], v[148:151], v[128:131]
	s_setprio 0
	s_barrier
	s_mov_b32 m0, s75
	v_lshl_add_u64 v[204:205], s[86:87], 0, v[188:189]
	ds_read_b128 v[148:151], v220 offset:16384
	ds_read_b128 v[152:155], v220 offset:17408
	ds_read_b128 v[164:167], v220 offset:18432
	ds_read_b128 v[172:175], v220 offset:19456
	ds_read_b128 v[176:179], v220 offset:20480
	ds_read_b128 v[180:183], v220 offset:21504
	ds_read_b128 v[196:199], v220 offset:22528
	ds_read_b128 v[200:203], v220 offset:23552
	global_load_lds_dwordx4 v[204:205], off
	v_lshl_add_u64 v[206:207], s[86:87], 0, v[184:185]
	s_mov_b32 m0, s63
	v_lshl_add_u64 v[208:209], s[88:89], 0, v[188:189]
	global_load_lds_dwordx4 v[206:207], off
	s_mov_b32 m0, s67
	v_lshl_add_u64 v[210:211], s[84:85], 0, v[186:187]
	global_load_lds_dwordx4 v[208:209], off
	v_lshl_add_u64 v[208:209], s[88:89], 0, v[184:185]
	s_mov_b32 m0, s65
	s_nop 0
	global_load_lds_dwordx4 v[208:209], off
	v_lshl_add_u64 v[208:209], s[84:85], 0, v[190:191]
	s_mov_b32 m0, s13
	s_nop 0
	global_load_lds_dwordx4 v[208:209], off
	s_mov_b32 m0, s14
	s_nop 0
	global_load_lds_dwordx4 v[210:211], off
	s_waitcnt vmcnt(8) lgkmcnt(0)
	s_barrier
; #define PG8_STAGE(bufoff, gbase, voff) do { _Pragma("unroll") for (int _i = 0; _i < 2; ++_i) \
;         __builtin_amdgcn_global_load_lds((const unsigned*)((const char*)(gbase) + (voff)[_i]), (LAS unsigned*)(lds + (bufoff) + ldsw + _i * 8192), 16, 0, 0); } while (0)
; #define PG8_LDA(dst, b, h) do { _Pragma("unroll") for (int m = 0; m < 4; ++m) _Pragma("unroll") for (int k = 0; k < 2; ++k) dst[m][k] = *(const LAS bf16x8*)(lds + PG8_SA(b, h) + aoff + m * 2048 + k * 1024); } while (0)
; #define PG8_LDB(dst, b, h) do { _Pragma("unroll") for (int n = 0; n < 2; ++n) _Pragma("unroll") for (int k = 0; k < 2; ++k) dst[n][k] = *(const LAS bf16x8*)(lds + PG8_SB(b, h) + boff + n * 2048 + k * 1024); } while (0)
; #define PG8_MMA(ai, bj, At, Bt) do { __builtin_amdgcn_s_setprio(1); _Pragma("unroll") for (int m = 0; m < 4; ++m) _Pragma("unroll") for (int n = 0; n < 2; ++n) _Pragma("unroll") for (int k = 0; k < 2; ++k) \
;         acc[ai][bj][m][n] = __builtin_amdgcn_mfma_f32_16x16x32_bf16(Bt[n][k], At[m][k], acc[ai][bj][m][n], 0, 0, 0); __builtin_amdgcn_s_setprio(0); } while (0)
; #define PG8_WAIT_V(n) asm volatile("s_waitcnt vmcnt(" #n ")" ::: "memory")
; #define PG8_WAIT_L(n) asm volatile("s_waitcnt lgkmcnt(" #n ")" ::: "memory")
; #define PG8_BAR __builtin_amdgcn_s_barrier()
; #define PG8_SCHED __builtin_amdgcn_sched_barrier(0)
; template <class Epi, class Sched>
; __device__ __forceinline__ void gemm_phase(LAS unsigned char* lds, const Gemm g, const Sched& S, const Epi& E) {
;     ...
;             PG8_LDA(At, 0, 1); PG8_STAGE(PG8_SB(0, 0), b2, voffB); PG8_STAGE(PG8_SB(0, 1), b2 + hstepB, voffB); PG8_STAGE(PG8_SA(0, 0), a2, voffA);
;             PG8_WAIT_V(8); PG8_WAIT_L(0); PG8_BAR; PG8_MMA(1, 0, At, B0); PG8_MMA(1, 1, At, B1); PG8_BAR; PG8_SCHED;
;             PG8_LDB(B0, 1, 0); PG8_LDB(B1, 1, 1); PG8_SCHED; PG8_LDA(At, 1, 0); PG8_STAGE(PG8_SA(0, 1), a2 + hstepA, voffA);
;             PG8_WAIT_V(8); PG8_WAIT_L(0); PG8_BAR; PG8_MMA(0, 0, At, B0); PG8_MMA(0, 1, At, B1); PG8_BAR; PG8_SCHED;
	s_setprio 1
	v_mfma_f32_16x16x32_bf16 v[60:63], v[64:67], v[148:151], v[60:63]
	v_mfma_f32_16x16x32_bf16 v[52:55], v[72:75], v[148:151], v[52:55]
	v_mfma_f32_16x16x32_bf16 v[44:47], v[64:67], v[164:167], v[44:47]
	v_mfma_f32_16x16x32_bf16 v[36:39], v[72:75], v[164:167], v[36:39]
	v_mfma_f32_16x16x32_bf16 v[28:31], v[64:67], v[176:179], v[28:31]
	v_mfma_f32_16x16x32_bf16 v[20:23], v[72:75], v[176:179], v[20:23]
	v_mfma_f32_16x16x32_bf16 v[12:15], v[64:67], v[196:199], v[12:15]
	v_mfma_f32_16x16x32_bf16 v[4:7], v[72:75], v[196:199], v[4:7]
	v_mfma_f32_16x16x32_bf16 v[60:63], v[68:71], v[152:155], v[60:63]
	v_mfma_f32_16x16x32_bf16 v[52:55], v[80:83], v[152:155], v[52:55]
	v_mfma_f32_16x16x32_bf16 v[44:47], v[68:71], v[172:175], v[44:47]
	v_mfma_f32_16x16x32_bf16 v[36:39], v[80:83], v[172:175], v[36:39]
	v_mfma_f32_16x16x32_bf16 v[28:31], v[68:71], v[180:183], v[28:31]
	v_mfma_f32_16x16x32_bf16 v[20:23], v[80:83], v[180:183], v[20:23]
	v_mfma_f32_16x16x32_bf16 v[12:15], v[68:71], v[200:203], v[12:15]
	v_mfma_f32_16x16x32_bf16 v[4:7], v[80:83], v[200:203], v[4:7]
	s_setprio 0
	s_setprio 1
	v_mfma_f32_16x16x32_bf16 v[56:59], v[88:91], v[148:151], v[56:59]
	v_mfma_f32_16x16x32_bf16 v[48:51], v[100:103], v[148:151], v[48:51]
	v_mfma_f32_16x16x32_bf16 v[40:43], v[88:91], v[164:167], v[40:43]
	v_mfma_f32_16x16x32_bf16 v[32:35], v[100:103], v[164:167], v[32:35]
	v_mfma_f32_16x16x32_bf16 v[24:27], v[88:91], v[176:179], v[24:27]
	v_mfma_f32_16x16x32_bf16 v[16:19], v[100:103], v[176:179], v[16:19]
	v_mfma_f32_16x16x32_bf16 v[8:11], v[88:91], v[196:199], v[8:11]
	v_mfma_f32_16x16x32_bf16 v[0:3], v[100:103], v[196:199], v[0:3]
	v_mfma_f32_16x16x32_bf16 v[56:59], v[92:95], v[152:155], v[56:59]
	v_mfma_f32_16x16x32_bf16 v[48:51], v[108:111], v[152:155], v[48:51]
	v_mfma_f32_16x16x32_bf16 v[40:43], v[92:95], v[172:175], v[40:43]
	v_mfma_f32_16x16x32_bf16 v[32:35], v[108:111], v[172:175], v[32:35]
	v_mfma_f32_16x16x32_bf16 v[24:27], v[92:95], v[180:183], v[24:27]
	v_mfma_f32_16x16x32_bf16 v[16:19], v[108:111], v[180:183], v[16:19]
	v_mfma_f32_16x16x32_bf16 v[8:11], v[92:95], v[200:203], v[8:11]
	v_mfma_f32_16x16x32_bf16 v[0:3], v[108:111], v[200:203], v[0:3]
	s_setprio 0
	s_barrier
	v_add_u32_e32 v80, s37, v217
	v_add_u32_e32 v108, s26, v217
	ds_read_b128 v[64:67], v80
	ds_read_b128 v[68:71], v80 offset:1024
	ds_read_b128 v[72:75], v80 offset:2048
	ds_read_b128 v[80:83], v80 offset:3072
	ds_read_b128 v[88:91], v108
	ds_read_b128 v[92:95], v108 offset:1024
	ds_read_b128 v[100:103], v108 offset:2048
	ds_read_b128 v[108:111], v108 offset:3072
	s_mov_b32 m0, s15
	v_lshl_add_u64 v[222:223], s[82:83], 0, v[190:191]
	ds_read_b128 v[148:151], v220 offset:32768
	ds_read_b128 v[152:155], v220 offset:33792
	ds_read_b128 v[164:167], v220 offset:34816
	ds_read_b128 v[172:175], v220 offset:35840
	ds_read_b128 v[176:179], v220 offset:36864
	ds_read_b128 v[180:183], v220 offset:37888
	ds_read_b128 v[196:199], v220 offset:38912
	ds_read_b128 v[200:203], v220 offset:39936
	global_load_lds_dwordx4 v[222:223], off
	v_lshl_add_u64 v[222:223], s[82:83], 0, v[186:187]
	s_mov_b32 m0, s18
	s_nop 0
	global_load_lds_dwordx4 v[222:223], off
	s_waitcnt vmcnt(8) lgkmcnt(0)
	s_barrier
	s_setprio 1
	v_mfma_f32_16x16x32_bf16 v[168:171], v[64:67], v[148:151], v[168:171]
	v_mfma_f32_16x16x32_bf16 v[156:159], v[72:75], v[148:151], v[156:159]
	v_mfma_f32_16x16x32_bf16 v[144:147], v[64:67], v[164:167], v[144:147]
	v_mfma_f32_16x16x32_bf16 v[136:139], v[72:75], v[164:167], v[136:139]
	v_mfma_f32_16x16x32_bf16 v[124:127], v[64:67], v[176:179], v[124:127]
	v_mfma_f32_16x16x32_bf16 v[116:119], v[72:75], v[176:179], v[116:119]
	v_mfma_f32_16x16x32_bf16 v[104:107], v[64:67], v[196:199], v[104:107]
	v_mfma_f32_16x16x32_bf16 v[84:87], v[72:75], v[196:199], v[84:87]
	v_mfma_f32_16x16x32_bf16 v[168:171], v[68:71], v[152:155], v[168:171]
	v_mfma_f32_16x16x32_bf16 v[156:159], v[80:83], v[152:155], v[156:159]
	v_mfma_f32_16x16x32_bf16 v[144:147], v[68:71], v[172:175], v[144:147]
	v_mfma_f32_16x16x32_bf16 v[136:139], v[80:83], v[172:175], v[136:139]
	v_mfma_f32_16x16x32_bf16 v[124:127], v[68:71], v[180:183], v[124:127]
	v_mfma_f32_16x16x32_bf16 v[116:119], v[80:83], v[180:183], v[116:119]
	v_mfma_f32_16x16x32_bf16 v[104:107], v[68:71], v[200:203], v[104:107]
	v_mfma_f32_16x16x32_bf16 v[84:87], v[80:83], v[200:203], v[84:87]
	s_setprio 0
	s_setprio 1
	v_mfma_f32_16x16x32_bf16 v[160:163], v[88:91], v[148:151], v[160:163]
	v_mfma_f32_16x16x32_bf16 v[128:131], v[100:103], v[148:151], v[128:131]
	v_mfma_f32_16x16x32_bf16 v[160:163], v[92:95], v[152:155], v[160:163]
	v_mfma_f32_16x16x32_bf16 v[152:155], v[108:111], v[152:155], v[128:131]
	v_mfma_f32_16x16x32_bf16 v[128:131], v[88:91], v[164:167], v[140:143]
	v_mfma_f32_16x16x32_bf16 v[140:143], v[92:95], v[172:175], v[128:131]
	v_mfma_f32_16x16x32_bf16 v[128:131], v[100:103], v[164:167], v[132:135]
	v_mfma_f32_16x16x32_bf16 v[120:123], v[88:91], v[176:179], v[120:123]
	v_mfma_f32_16x16x32_bf16 v[112:115], v[100:103], v[176:179], v[112:115]
	v_mfma_f32_16x16x32_bf16 v[96:99], v[88:91], v[196:199], v[96:99]
	v_mfma_f32_16x16x32_bf16 v[76:79], v[100:103], v[196:199], v[76:79]
	v_mfma_f32_16x16x32_bf16 v[132:135], v[108:111], v[172:175], v[128:131]
	v_mfma_f32_16x16x32_bf16 v[120:123], v[92:95], v[180:183], v[120:123]
	v_mfma_f32_16x16x32_bf16 v[112:115], v[108:111], v[180:183], v[112:115]
	v_mfma_f32_16x16x32_bf16 v[96:99], v[92:95], v[200:203], v[96:99]
	v_mfma_f32_16x16x32_bf16 v[76:79], v[108:111], v[200:203], v[76:79]
	s_setprio 0
	s_barrier
; #define PG8_STAGE(bufoff, gbase, voff) do { _Pragma("unroll") for (int _i = 0; _i < 2; ++_i) \
;         __builtin_amdgcn_global_load_lds((const unsigned*)((const char*)(gbase) + (voff)[_i]), (LAS unsigned*)(lds + (bufoff) + ldsw + _i * 8192), 16, 0, 0); } while (0)
; #define PG8_LDA(dst, b, h) do { _Pragma("unroll") for (int m = 0; m < 4; ++m) _Pragma("unroll") for (int k = 0; k < 2; ++k) dst[m][k] = *(const LAS bf16x8*)(lds + PG8_SA(b, h) + aoff + m * 2048 + k * 1024); } while (0)
; #define PG8_MMA(ai, bj, At, Bt) do { __builtin_amdgcn_s_setprio(1); _Pragma("unroll") for (int m = 0; m < 4; ++m) _Pragma("unroll") for (int n = 0; n < 2; ++n) _Pragma("unroll") for (int k = 0; k < 2; ++k) \
;         acc[ai][bj][m][n] = __builtin_amdgcn_mfma_f32_16x16x32_bf16(Bt[n][k], At[m][k], acc[ai][bj][m][n], 0, 0, 0); __builtin_amdgcn_s_setprio(0); } while (0)
; #define PG8_WAIT_V(n) asm volatile("s_waitcnt vmcnt(" #n ")" ::: "memory")
; #define PG8_WAIT_L(n) asm volatile("s_waitcnt lgkmcnt(" #n ")" ::: "memory")
; #define PG8_BAR __builtin_amdgcn_s_barrier()
; #define PG8_SCHED __builtin_amdgcn_sched_barrier(0)
; template <class Epi, class Sched>
; __device__ __forceinline__ void gemm_phase(LAS unsigned char* lds, const Gemm g, const Sched& S, const Epi& E) {
;     ...
;             PG8_LDA(At, 1, 1); PG8_STAGE(PG8_SB(1, 0), b3, voffB); PG8_STAGE(PG8_SB(1, 1), b3 + hstepB, voffB); PG8_STAGE(PG8_SA(1, 0), a3, voffA);
;             PG8_WAIT_V(8); PG8_WAIT_L(0); PG8_BAR; PG8_MMA(1, 0, At, B0); PG8_MMA(1, 1, At, B1); PG8_BAR; PG8_SCHED;
;         }
;         if (wr == 0) PG8_BAR;
	s_mov_b32 m0, s49
	v_lshl_add_u64 v[204:205], v[204:205], 0, s[58:59]
	ds_read_b128 v[128:131], v220 offset:49152
	ds_read_b128 v[148:151], v220 offset:50176
	ds_read_b128 v[164:167], v220 offset:51200
	ds_read_b128 v[172:175], v220 offset:52224
	ds_read_b128 v[176:179], v220 offset:53248
	ds_read_b128 v[180:183], v220 offset:54272
	ds_read_b128 v[196:199], v220 offset:55296
	ds_read_b128 v[200:203], v220 offset:56320
	global_load_lds_dwordx4 v[204:205], off
	v_lshl_add_u64 v[204:205], v[206:207], 0, s[58:59]
	s_mov_b32 m0, s45
	s_nop 0
	global_load_lds_dwordx4 v[204:205], off
	v_lshl_add_u64 v[204:205], s[80:81], 0, v[188:189]
	s_mov_b32 m0, s48
	s_nop 0
	global_load_lds_dwordx4 v[204:205], off
	v_lshl_add_u64 v[204:205], s[80:81], 0, v[184:185]
	s_mov_b32 m0, s35
	s_nop 0
	global_load_lds_dwordx4 v[204:205], off
	v_lshl_add_u64 v[204:205], v[208:209], 0, s[58:59]
	s_mov_b32 m0, s24
	s_nop 0
	global_load_lds_dwordx4 v[204:205], off
	v_lshl_add_u64 v[204:205], v[210:211], 0, s[58:59]
	s_mov_b32 m0, s25
	s_nop 0
	global_load_lds_dwordx4 v[204:205], off
	s_waitcnt vmcnt(8) lgkmcnt(0)
	s_barrier
	s_setprio 1
	v_mfma_f32_16x16x32_bf16 v[60:63], v[64:67], v[128:131], v[60:63]
	v_mfma_f32_16x16x32_bf16 v[52:55], v[72:75], v[128:131], v[52:55]
	v_mfma_f32_16x16x32_bf16 v[44:47], v[64:67], v[164:167], v[44:47]
	v_mfma_f32_16x16x32_bf16 v[36:39], v[72:75], v[164:167], v[36:39]
	v_mfma_f32_16x16x32_bf16 v[28:31], v[64:67], v[176:179], v[28:31]
	v_mfma_f32_16x16x32_bf16 v[20:23], v[72:75], v[176:179], v[20:23]
	v_mfma_f32_16x16x32_bf16 v[12:15], v[64:67], v[196:199], v[12:15]
	v_mfma_f32_16x16x32_bf16 v[4:7], v[72:75], v[196:199], v[4:7]
	v_mfma_f32_16x16x32_bf16 v[60:63], v[68:71], v[148:151], v[60:63]
	v_mfma_f32_16x16x32_bf16 v[52:55], v[80:83], v[148:151], v[52:55]
	v_mfma_f32_16x16x32_bf16 v[44:47], v[68:71], v[172:175], v[44:47]
	v_mfma_f32_16x16x32_bf16 v[36:39], v[80:83], v[172:175], v[36:39]
	v_mfma_f32_16x16x32_bf16 v[28:31], v[68:71], v[180:183], v[28:31]
	v_mfma_f32_16x16x32_bf16 v[20:23], v[80:83], v[180:183], v[20:23]
	v_mfma_f32_16x16x32_bf16 v[12:15], v[68:71], v[200:203], v[12:15]
	v_mfma_f32_16x16x32_bf16 v[4:7], v[80:83], v[200:203], v[4:7]
	s_setprio 0
	s_setprio 1
	v_mfma_f32_16x16x32_bf16 v[56:59], v[88:91], v[128:131], v[56:59]
	v_mfma_f32_16x16x32_bf16 v[48:51], v[100:103], v[128:131], v[48:51]
	v_mfma_f32_16x16x32_bf16 v[40:43], v[88:91], v[164:167], v[40:43]
	v_mfma_f32_16x16x32_bf16 v[32:35], v[100:103], v[164:167], v[32:35]
	v_mfma_f32_16x16x32_bf16 v[24:27], v[88:91], v[176:179], v[24:27]
	v_mfma_f32_16x16x32_bf16 v[16:19], v[100:103], v[176:179], v[16:19]
	v_mfma_f32_16x16x32_bf16 v[8:11], v[88:91], v[196:199], v[8:11]
	v_mfma_f32_16x16x32_bf16 v[0:3], v[100:103], v[196:199], v[0:3]
	v_mfma_f32_16x16x32_bf16 v[56:59], v[92:95], v[148:151], v[56:59]
	v_mfma_f32_16x16x32_bf16 v[48:51], v[108:111], v[148:151], v[48:51]
	v_mfma_f32_16x16x32_bf16 v[40:43], v[92:95], v[172:175], v[40:43]
	v_mfma_f32_16x16x32_bf16 v[32:35], v[108:111], v[172:175], v[32:35]
	v_mfma_f32_16x16x32_bf16 v[24:27], v[92:95], v[180:183], v[24:27]
	v_mfma_f32_16x16x32_bf16 v[16:19], v[108:111], v[180:183], v[16:19]
	v_mfma_f32_16x16x32_bf16 v[8:11], v[92:95], v[200:203], v[8:11]
	v_mfma_f32_16x16x32_bf16 v[0:3], v[108:111], v[200:203], v[0:3]
	s_setprio 0
	s_barrier
	s_andn2_b64 vcc, exec, s[0:1]
	s_mov_b64 s[80:81], -1
	s_mov_b64 s[0:1], 0
	s_mov_b64 s[82:83], 0x100
	s_cbranch_vccz .LBB0_553
	s_and_b64 vcc, exec, s[60:61]
	s_cbranch_vccz .LBB0_556
	s_barrier

; #define PG8_STAGE(bufoff, gbase, voff) do { _Pragma("unroll") for (int _i = 0; _i < 2; ++_i) \
;         __builtin_amdgcn_global_load_lds((const unsigned*)((const char*)(gbase) + (voff)[_i]), (LAS unsigned*)(lds + (bufoff) + ldsw + _i * 8192), 16, 0, 0); } while (0)
; #define PG8_LDA(dst, b, h) do { _Pragma("unroll") for (int m = 0; m < 4; ++m) _Pragma("unroll") for (int k = 0; k < 2; ++k) dst[m][k] = *(const LAS bf16x8*)(lds + PG8_SA(b, h) + aoff + m * 2048 + k * 1024); } while (0)
; #define PG8_LDB(dst, b, h) do { _Pragma("unroll") for (int n = 0; n < 2; ++n) _Pragma("unroll") for (int k = 0; k < 2; ++k) dst[n][k] = *(const LAS bf16x8*)(lds + PG8_SB(b, h) + boff + n * 2048 + k * 1024); } while (0)
; #define PG8_MMA(ai, bj, At, Bt) do { __builtin_amdgcn_s_setprio(1); _Pragma("unroll") for (int m = 0; m < 4; ++m) _Pragma("unroll") for (int n = 0; n < 2; ++n) _Pragma("unroll") for (int k = 0; k < 2; ++k) \
;         acc[ai][bj][m][n] = __builtin_amdgcn_mfma_f32_16x16x32_bf16(Bt[n][k], At[m][k], acc[ai][bj][m][n], 0, 0, 0); __builtin_amdgcn_s_setprio(0); } while (0)
; #define PG8_WAIT_V(n) asm volatile("s_waitcnt vmcnt(" #n ")" ::: "memory")
; #define PG8_WAIT_L(n) asm volatile("s_waitcnt lgkmcnt(" #n ")" ::: "memory")
; #define PG8_BAR __builtin_amdgcn_s_barrier()
; #define PG8_SCHED __builtin_amdgcn_sched_barrier(0)
; template <class Epi, class Sched>
; __device__ __forceinline__ void gemm_phase(LAS unsigned char* lds, const Gemm g, const Sched& S, const Epi& E) {
;     ...
;             const bool last = (t == nt - 2);
;             const char* a1 = cA + (size_t)(t + 1) * kstep;
;             const char* a2 = last ? nA : cA + (size_t)(t + 2) * kstep; const char* b2 = last ? nB : cB + (size_t)(t + 2) * kstep;
;             const char* a3 = a2 + kstep; const char* b3 = b2 + kstep;
;             PG8_LDB(B0, 0, 0); PG8_LDB(B1, 0, 1); PG8_SCHED; PG8_LDA(At, 0, 0); PG8_STAGE(PG8_SA(1, 1), a1 + hstepA, voffA);
;             PG8_WAIT_V(8); PG8_WAIT_L(0); PG8_BAR; PG8_MMA(0, 0, At, B0); PG8_MMA(0, 1, At, B1); PG8_BAR; PG8_SCHED;
;             PG8_LDA(At, 0, 1); PG8_STAGE(PG8_SB(0, 0), b2, voffB); PG8_STAGE(PG8_SB(0, 1), b2 + hstepB, voffB); PG8_STAGE(PG8_SA(0, 0), a2, voffA);
.LBB0_752:
	v_add_u32_e32 v1, s33, v166
	ds_read_b128 v[152:155], v1
	ds_read_b128 v[156:159], v1 offset:1024
	ds_read_b128 v[160:163], v1 offset:2048
	ds_read_b128 v[168:171], v1 offset:3072
	v_add_u32_e32 v1, s36, v166
	s_add_u32 s64, s60, s62
	ds_read_b128 v[172:175], v1
	ds_read_b128 v[176:179], v1 offset:1024
	ds_read_b128 v[180:183], v1 offset:2048
	ds_read_b128 v[184:187], v1 offset:3072
	s_addc_u32 s65, s61, s63
	s_add_u32 s64, s64, 0x100
	s_addc_u32 s65, s65, 0
	s_add_u32 s75, s72, s62
	s_addc_u32 s76, s73, s63
	s_cmpk_eq_i32 s62, 0x1700
	s_cselect_b32 s67, s1, s65
	s_cselect_b32 s66, s0, s64
	s_cselect_b32 s65, s59, s76
	s_cselect_b32 s64, s58, s75
	v_lshl_add_u64 v[2:3], v[148:149], 0, s[62:63]
	s_add_i32 m0, s13, 0xc000
	ds_read_b128 v[188:191], v167
	ds_read_b128 v[192:195], v167 offset:1024
	ds_read_b128 v[196:199], v167 offset:2048
	ds_read_b128 v[200:203], v167 offset:3072
	ds_read_b128 v[204:207], v167 offset:4096
	ds_read_b128 v[208:211], v167 offset:5120
	ds_read_b128 v[216:219], v167 offset:6144
	ds_read_b128 v[220:223], v167 offset:7168
	global_load_lds_dwordx4 v[2:3], off
	v_lshl_add_u64 v[2:3], v[150:151], 0, s[62:63]
	s_add_i32 m0, s13, 0xe000
	s_nop 0
	global_load_lds_dwordx4 v[2:3], off
	s_waitcnt vmcnt(8) lgkmcnt(0)
	s_barrier
	s_setprio 1
	v_mfma_f32_16x16x32_bf16 v[128:131], v[152:155], v[188:191], v[128:131]
	v_mfma_f32_16x16x32_bf16 v[124:127], v[160:163], v[188:191], v[124:127]
	v_mfma_f32_16x16x32_bf16 v[112:115], v[152:155], v[196:199], v[112:115]
	v_mfma_f32_16x16x32_bf16 v[108:111], v[160:163], v[196:199], v[108:111]
	v_mfma_f32_16x16x32_bf16 v[96:99], v[152:155], v[204:207], v[96:99]
	v_mfma_f32_16x16x32_bf16 v[92:95], v[160:163], v[204:207], v[92:95]
	v_mfma_f32_16x16x32_bf16 v[80:83], v[152:155], v[216:219], v[80:83]
	v_mfma_f32_16x16x32_bf16 v[76:79], v[160:163], v[216:219], v[76:79]
	v_mfma_f32_16x16x32_bf16 v[128:131], v[156:159], v[192:195], v[128:131]
	v_mfma_f32_16x16x32_bf16 v[124:127], v[168:171], v[192:195], v[124:127]
	v_mfma_f32_16x16x32_bf16 v[112:115], v[156:159], v[200:203], v[112:115]
	v_mfma_f32_16x16x32_bf16 v[108:111], v[168:171], v[200:203], v[108:111]
	v_mfma_f32_16x16x32_bf16 v[96:99], v[156:159], v[208:211], v[96:99]
	v_mfma_f32_16x16x32_bf16 v[92:95], v[168:171], v[208:211], v[92:95]
	v_mfma_f32_16x16x32_bf16 v[80:83], v[156:159], v[220:223], v[80:83]
	v_mfma_f32_16x16x32_bf16 v[76:79], v[168:171], v[220:223], v[76:79]
	s_setprio 0
	s_setprio 1
	v_mfma_f32_16x16x32_bf16 v[120:123], v[172:175], v[188:191], v[120:123]
	v_mfma_f32_16x16x32_bf16 v[116:119], v[180:183], v[188:191], v[116:119]
	v_mfma_f32_16x16x32_bf16 v[104:107], v[172:175], v[196:199], v[104:107]
	v_mfma_f32_16x16x32_bf16 v[100:103], v[180:183], v[196:199], v[100:103]
	v_mfma_f32_16x16x32_bf16 v[88:91], v[172:175], v[204:207], v[88:91]
	v_mfma_f32_16x16x32_bf16 v[84:87], v[180:183], v[204:207], v[84:87]
	v_mfma_f32_16x16x32_bf16 v[72:75], v[172:175], v[216:219], v[72:75]
	v_mfma_f32_16x16x32_bf16 v[68:71], v[180:183], v[216:219], v[68:71]
	v_mfma_f32_16x16x32_bf16 v[120:123], v[176:179], v[192:195], v[120:123]
	v_mfma_f32_16x16x32_bf16 v[116:119], v[184:187], v[192:195], v[116:119]
	v_mfma_f32_16x16x32_bf16 v[104:107], v[176:179], v[200:203], v[104:107]
	v_mfma_f32_16x16x32_bf16 v[100:103], v[184:187], v[200:203], v[100:103]
	v_mfma_f32_16x16x32_bf16 v[88:91], v[176:179], v[208:211], v[88:91]
	v_mfma_f32_16x16x32_bf16 v[84:87], v[184:187], v[208:211], v[84:87]
	v_mfma_f32_16x16x32_bf16 v[72:75], v[176:179], v[220:223], v[72:75]
	v_mfma_f32_16x16x32_bf16 v[68:71], v[184:187], v[220:223], v[68:71]
	s_setprio 0
	s_barrier
	s_add_i32 s75, s33, s12
	v_lshl_add_u64 v[224:225], s[64:65], 0, v[136:137]
	s_mov_b32 m0, s75
	ds_read_b128 v[188:191], v167 offset:16384
	ds_read_b128 v[192:195], v167 offset:17408
	ds_read_b128 v[196:199], v167 offset:18432
	ds_read_b128 v[200:203], v167 offset:19456
	ds_read_b128 v[204:207], v167 offset:20480
	ds_read_b128 v[208:211], v167 offset:21504
	ds_read_b128 v[216:219], v167 offset:22528
	ds_read_b128 v[220:223], v167 offset:23552
	global_load_lds_dwordx4 v[224:225], off
	s_add_i32 m0, s75, 0x2000
	s_add_u32 s76, s64, 0xc0000
	v_lshl_add_u64 v[226:227], s[64:65], 0, v[132:133]
	s_addc_u32 s77, s65, 0
	s_add_i32 s75, s36, s12
	global_load_lds_dwordx4 v[226:227], off
	v_lshl_add_u64 v[2:3], s[76:77], 0, v[136:137]
	s_mov_b32 m0, s75
	v_lshl_add_u64 v[228:229], s[66:67], 0, v[138:139]
	global_load_lds_dwordx4 v[2:3], off
	v_lshl_add_u64 v[2:3], s[76:77], 0, v[132:133]
	s_add_i32 m0, s75, 0x2000
	v_lshl_add_u64 v[230:231], s[66:67], 0, v[134:135]
	global_load_lds_dwordx4 v[2:3], off
	s_mov_b32 m0, s13
	s_nop 0
	global_load_lds_dwordx4 v[228:229], off
	s_mov_b32 m0, s14
	s_nop 0
	global_load_lds_dwordx4 v[230:231], off
	s_waitcnt vmcnt(8) lgkmcnt(0)
	s_barrier
; #define PG8_STAGE(bufoff, gbase, voff) do { _Pragma("unroll") for (int _i = 0; _i < 2; ++_i) \
;         __builtin_amdgcn_global_load_lds((const unsigned*)((const char*)(gbase) + (voff)[_i]), (LAS unsigned*)(lds + (bufoff) + ldsw + _i * 8192), 16, 0, 0); } while (0)
; #define PG8_LDA(dst, b, h) do { _Pragma("unroll") for (int m = 0; m < 4; ++m) _Pragma("unroll") for (int k = 0; k < 2; ++k) dst[m][k] = *(const LAS bf16x8*)(lds + PG8_SA(b, h) + aoff + m * 2048 + k * 1024); } while (0)
; #define PG8_LDB(dst, b, h) do { _Pragma("unroll") for (int n = 0; n < 2; ++n) _Pragma("unroll") for (int k = 0; k < 2; ++k) dst[n][k] = *(const LAS bf16x8*)(lds + PG8_SB(b, h) + boff + n * 2048 + k * 1024); } while (0)
; #define PG8_MMA(ai, bj, At, Bt) do { __builtin_amdgcn_s_setprio(1); _Pragma("unroll") for (int m = 0; m < 4; ++m) _Pragma("unroll") for (int n = 0; n < 2; ++n) _Pragma("unroll") for (int k = 0; k < 2; ++k) \
;         acc[ai][bj][m][n] = __builtin_amdgcn_mfma_f32_16x16x32_bf16(Bt[n][k], At[m][k], acc[ai][bj][m][n], 0, 0, 0); __builtin_amdgcn_s_setprio(0); } while (0)
; #define PG8_WAIT_V(n) asm volatile("s_waitcnt vmcnt(" #n ")" ::: "memory")
; #define PG8_WAIT_L(n) asm volatile("s_waitcnt lgkmcnt(" #n ")" ::: "memory")
; #define PG8_BAR __builtin_amdgcn_s_barrier()
; #define PG8_SCHED __builtin_amdgcn_sched_barrier(0)
; template <class Epi, class Sched>
; __device__ __forceinline__ void gemm_phase(LAS unsigned char* lds, const Gemm g, const Sched& S, const Epi& E) {
;     ...
;             PG8_LDA(At, 0, 1); PG8_STAGE(PG8_SB(0, 0), b2, voffB); PG8_STAGE(PG8_SB(0, 1), b2 + hstepB, voffB); PG8_STAGE(PG8_SA(0, 0), a2, voffA);
;             PG8_WAIT_V(8); PG8_WAIT_L(0); PG8_BAR; PG8_MMA(1, 0, At, B0); PG8_MMA(1, 1, At, B1); PG8_BAR; PG8_SCHED;
;             PG8_LDB(B0, 1, 0); PG8_LDB(B1, 1, 1); PG8_SCHED; PG8_LDA(At, 1, 0); PG8_STAGE(PG8_SA(0, 1), a2 + hstepA, voffA);
;             PG8_WAIT_V(8); PG8_WAIT_L(0); PG8_BAR; PG8_MMA(0, 0, At, B0); PG8_MMA(0, 1, At, B1); PG8_BAR; PG8_SCHED;
	s_setprio 1
	v_mfma_f32_16x16x32_bf16 v[64:67], v[152:155], v[188:191], v[64:67]
	v_mfma_f32_16x16x32_bf16 v[60:63], v[160:163], v[188:191], v[60:63]
	v_mfma_f32_16x16x32_bf16 v[48:51], v[152:155], v[196:199], v[48:51]
	v_mfma_f32_16x16x32_bf16 v[44:47], v[160:163], v[196:199], v[44:47]
	v_mfma_f32_16x16x32_bf16 v[32:35], v[152:155], v[204:207], v[32:35]
	v_mfma_f32_16x16x32_bf16 v[28:31], v[160:163], v[204:207], v[28:31]
	v_mfma_f32_16x16x32_bf16 v[16:19], v[152:155], v[216:219], v[16:19]
	v_mfma_f32_16x16x32_bf16 v[12:15], v[160:163], v[216:219], v[12:15]
	v_mfma_f32_16x16x32_bf16 v[64:67], v[156:159], v[192:195], v[64:67]
	v_mfma_f32_16x16x32_bf16 v[60:63], v[168:171], v[192:195], v[60:63]
	v_mfma_f32_16x16x32_bf16 v[48:51], v[156:159], v[200:203], v[48:51]
	v_mfma_f32_16x16x32_bf16 v[44:47], v[168:171], v[200:203], v[44:47]
	v_mfma_f32_16x16x32_bf16 v[32:35], v[156:159], v[208:211], v[32:35]
	v_mfma_f32_16x16x32_bf16 v[28:31], v[168:171], v[208:211], v[28:31]
	v_mfma_f32_16x16x32_bf16 v[16:19], v[156:159], v[220:223], v[16:19]
	v_mfma_f32_16x16x32_bf16 v[12:15], v[168:171], v[220:223], v[12:15]
	s_setprio 0
	s_setprio 1
	v_mfma_f32_16x16x32_bf16 v[56:59], v[172:175], v[188:191], v[56:59]
	v_mfma_f32_16x16x32_bf16 v[52:55], v[180:183], v[188:191], v[52:55]
	v_mfma_f32_16x16x32_bf16 v[40:43], v[172:175], v[196:199], v[40:43]
	v_mfma_f32_16x16x32_bf16 v[36:39], v[180:183], v[196:199], v[36:39]
	v_mfma_f32_16x16x32_bf16 v[24:27], v[172:175], v[204:207], v[24:27]
	v_mfma_f32_16x16x32_bf16 v[20:23], v[180:183], v[204:207], v[20:23]
	v_mfma_f32_16x16x32_bf16 v[8:11], v[172:175], v[216:219], v[8:11]
	v_mfma_f32_16x16x32_bf16 v[2:5], v[180:183], v[216:219], v[4:7]
	v_mfma_f32_16x16x32_bf16 v[56:59], v[176:179], v[192:195], v[56:59]
	v_mfma_f32_16x16x32_bf16 v[52:55], v[184:187], v[192:195], v[52:55]
	v_mfma_f32_16x16x32_bf16 v[40:43], v[176:179], v[200:203], v[40:43]
	v_mfma_f32_16x16x32_bf16 v[36:39], v[184:187], v[200:203], v[36:39]
	v_mfma_f32_16x16x32_bf16 v[24:27], v[176:179], v[208:211], v[24:27]
	v_mfma_f32_16x16x32_bf16 v[20:23], v[184:187], v[208:211], v[20:23]
	v_mfma_f32_16x16x32_bf16 v[8:11], v[176:179], v[220:223], v[8:11]
	v_mfma_f32_16x16x32_bf16 v[2:5], v[184:187], v[220:223], v[2:5]
	s_setprio 0
	s_barrier
	v_add_u32_e32 v1, s37, v166
	ds_read_b128 v[152:155], v1
	ds_read_b128 v[156:159], v1 offset:1024
	ds_read_b128 v[160:163], v1 offset:2048
	ds_read_b128 v[168:171], v1 offset:3072
	v_add_u32_e32 v1, s26, v166
	ds_read_b128 v[172:175], v1
	ds_read_b128 v[176:179], v1 offset:1024
	ds_read_b128 v[180:183], v1 offset:2048
	ds_read_b128 v[184:187], v1 offset:3072
	s_add_u32 s66, s66, 0xc0000
	s_addc_u32 s67, s67, 0
	s_mov_b32 m0, s15
	v_lshl_add_u64 v[6:7], s[66:67], 0, v[138:139]
	ds_read_b128 v[188:191], v167 offset:32768
	ds_read_b128 v[192:195], v167 offset:33792
	ds_read_b128 v[196:199], v167 offset:34816
	ds_read_b128 v[200:203], v167 offset:35840
	ds_read_b128 v[204:207], v167 offset:36864
	ds_read_b128 v[208:211], v167 offset:37888
	ds_read_b128 v[216:219], v167 offset:38912
	ds_read_b128 v[220:223], v167 offset:39936
	global_load_lds_dwordx4 v[6:7], off
	v_lshl_add_u64 v[6:7], s[66:67], 0, v[134:135]
	s_mov_b32 m0, s19
	s_nop 0
	global_load_lds_dwordx4 v[6:7], off
	s_waitcnt vmcnt(8) lgkmcnt(0)
	s_barrier
	s_setprio 1
	v_mfma_f32_16x16x32_bf16 v[128:131], v[152:155], v[188:191], v[128:131]
	v_mfma_f32_16x16x32_bf16 v[124:127], v[160:163], v[188:191], v[124:127]
	v_mfma_f32_16x16x32_bf16 v[112:115], v[152:155], v[196:199], v[112:115]
	v_mfma_f32_16x16x32_bf16 v[108:111], v[160:163], v[196:199], v[108:111]
	v_mfma_f32_16x16x32_bf16 v[96:99], v[152:155], v[204:207], v[96:99]
	v_mfma_f32_16x16x32_bf16 v[92:95], v[160:163], v[204:207], v[92:95]
	v_mfma_f32_16x16x32_bf16 v[80:83], v[152:155], v[216:219], v[80:83]
	v_mfma_f32_16x16x32_bf16 v[76:79], v[160:163], v[216:219], v[76:79]
	v_mfma_f32_16x16x32_bf16 v[128:131], v[156:159], v[192:195], v[128:131]
	v_mfma_f32_16x16x32_bf16 v[124:127], v[168:171], v[192:195], v[124:127]
	v_mfma_f32_16x16x32_bf16 v[112:115], v[156:159], v[200:203], v[112:115]
	v_mfma_f32_16x16x32_bf16 v[108:111], v[168:171], v[200:203], v[108:111]
	v_mfma_f32_16x16x32_bf16 v[96:99], v[156:159], v[208:211], v[96:99]
	v_mfma_f32_16x16x32_bf16 v[92:95], v[168:171], v[208:211], v[92:95]
	v_mfma_f32_16x16x32_bf16 v[80:83], v[156:159], v[220:223], v[80:83]
	v_mfma_f32_16x16x32_bf16 v[76:79], v[168:171], v[220:223], v[76:79]
	s_setprio 0
	s_setprio 1
	v_mfma_f32_16x16x32_bf16 v[120:123], v[172:175], v[188:191], v[120:123]
	v_mfma_f32_16x16x32_bf16 v[116:119], v[180:183], v[188:191], v[116:119]
	v_mfma_f32_16x16x32_bf16 v[104:107], v[172:175], v[196:199], v[104:107]
	v_mfma_f32_16x16x32_bf16 v[100:103], v[180:183], v[196:199], v[100:103]
	v_mfma_f32_16x16x32_bf16 v[88:91], v[172:175], v[204:207], v[88:91]
	v_mfma_f32_16x16x32_bf16 v[84:87], v[180:183], v[204:207], v[84:87]
	v_mfma_f32_16x16x32_bf16 v[72:75], v[172:175], v[216:219], v[72:75]
	v_mfma_f32_16x16x32_bf16 v[68:71], v[180:183], v[216:219], v[68:71]
	v_mfma_f32_16x16x32_bf16 v[120:123], v[176:179], v[192:195], v[120:123]
	v_mfma_f32_16x16x32_bf16 v[116:119], v[184:187], v[192:195], v[116:119]
	v_mfma_f32_16x16x32_bf16 v[104:107], v[176:179], v[200:203], v[104:107]
	v_mfma_f32_16x16x32_bf16 v[100:103], v[184:187], v[200:203], v[100:103]
	v_mfma_f32_16x16x32_bf16 v[88:91], v[176:179], v[208:211], v[88:91]
	v_mfma_f32_16x16x32_bf16 v[84:87], v[184:187], v[208:211], v[84:87]
	v_mfma_f32_16x16x32_bf16 v[72:75], v[176:179], v[220:223], v[72:75]
	v_mfma_f32_16x16x32_bf16 v[68:71], v[184:187], v[220:223], v[68:71]
	s_setprio 0
	s_barrier
; #define PG8_STAGE(bufoff, gbase, voff) do { _Pragma("unroll") for (int _i = 0; _i < 2; ++_i) \
;         __builtin_amdgcn_global_load_lds((const unsigned*)((const char*)(gbase) + (voff)[_i]), (LAS unsigned*)(lds + (bufoff) + ldsw + _i * 8192), 16, 0, 0); } while (0)
; #define PG8_LDA(dst, b, h) do { _Pragma("unroll") for (int m = 0; m < 4; ++m) _Pragma("unroll") for (int k = 0; k < 2; ++k) dst[m][k] = *(const LAS bf16x8*)(lds + PG8_SA(b, h) + aoff + m * 2048 + k * 1024); } while (0)
; #define PG8_MMA(ai, bj, At, Bt) do { __builtin_amdgcn_s_setprio(1); _Pragma("unroll") for (int m = 0; m < 4; ++m) _Pragma("unroll") for (int n = 0; n < 2; ++n) _Pragma("unroll") for (int k = 0; k < 2; ++k) \
;         acc[ai][bj][m][n] = __builtin_amdgcn_mfma_f32_16x16x32_bf16(Bt[n][k], At[m][k], acc[ai][bj][m][n], 0, 0, 0); __builtin_amdgcn_s_setprio(0); } while (0)
; #define PG8_WAIT_V(n) asm volatile("s_waitcnt vmcnt(" #n ")" ::: "memory")
; #define PG8_WAIT_L(n) asm volatile("s_waitcnt lgkmcnt(" #n ")" ::: "memory")
; #define PG8_BAR __builtin_amdgcn_s_barrier()
; #define PG8_SCHED __builtin_amdgcn_sched_barrier(0)
; template <class Epi, class Sched>
; __device__ __forceinline__ void gemm_phase(LAS unsigned char* lds, const Gemm g, const Sched& S, const Epi& E) {
;     ...
;             PG8_LDA(At, 1, 1); PG8_STAGE(PG8_SB(1, 0), b3, voffB); PG8_STAGE(PG8_SB(1, 1), b3 + hstepB, voffB); PG8_STAGE(PG8_SA(1, 0), a3, voffA);
;             PG8_WAIT_V(8); PG8_WAIT_L(0); PG8_BAR; PG8_MMA(1, 0, At, B0); PG8_MMA(1, 1, At, B1); PG8_BAR; PG8_SCHED;
;         }
;         if (wr == 0) PG8_BAR;
	s_add_i32 s66, s37, s12
	v_lshl_add_u64 v[6:7], v[224:225], 0, s[42:43]
	s_mov_b32 m0, s66
	ds_read_b128 v[188:191], v167 offset:49152
	ds_read_b128 v[192:195], v167 offset:50176
	ds_read_b128 v[196:199], v167 offset:51200
	ds_read_b128 v[200:203], v167 offset:52224
	ds_read_b128 v[204:207], v167 offset:53248
	ds_read_b128 v[208:211], v167 offset:54272
	ds_read_b128 v[216:219], v167 offset:55296
	ds_read_b128 v[220:223], v167 offset:56320
	global_load_lds_dwordx4 v[6:7], off
	s_add_i32 m0, s66, 0x2000
	s_add_u32 s64, s64, 0xc0080
	v_lshl_add_u64 v[6:7], v[226:227], 0, s[42:43]
	s_addc_u32 s65, s65, 0
	s_add_i32 s66, s26, s12
	global_load_lds_dwordx4 v[6:7], off
	v_lshl_add_u64 v[6:7], s[64:65], 0, v[136:137]
	s_mov_b32 m0, s66
	s_nop 0
	global_load_lds_dwordx4 v[6:7], off
	v_lshl_add_u64 v[6:7], s[64:65], 0, v[132:133]
	s_add_i32 m0, s66, 0x2000
	s_nop 0
	global_load_lds_dwordx4 v[6:7], off
	v_lshl_add_u64 v[6:7], v[228:229], 0, s[42:43]
	s_mov_b32 m0, s23
	s_nop 0
	global_load_lds_dwordx4 v[6:7], off
	v_lshl_add_u64 v[6:7], v[230:231], 0, s[42:43]
	s_mov_b32 m0, s24
	s_nop 0
	global_load_lds_dwordx4 v[6:7], off
	s_waitcnt vmcnt(8) lgkmcnt(0)
	s_barrier
	s_setprio 1
	v_mfma_f32_16x16x32_bf16 v[64:67], v[152:155], v[188:191], v[64:67]
	v_mfma_f32_16x16x32_bf16 v[60:63], v[160:163], v[188:191], v[60:63]
	v_mfma_f32_16x16x32_bf16 v[48:51], v[152:155], v[196:199], v[48:51]
	v_mfma_f32_16x16x32_bf16 v[44:47], v[160:163], v[196:199], v[44:47]
	v_mfma_f32_16x16x32_bf16 v[32:35], v[152:155], v[204:207], v[32:35]
	v_mfma_f32_16x16x32_bf16 v[28:31], v[160:163], v[204:207], v[28:31]
	v_mfma_f32_16x16x32_bf16 v[16:19], v[152:155], v[216:219], v[16:19]
	v_mfma_f32_16x16x32_bf16 v[12:15], v[160:163], v[216:219], v[12:15]
	v_mfma_f32_16x16x32_bf16 v[64:67], v[156:159], v[192:195], v[64:67]
	v_mfma_f32_16x16x32_bf16 v[60:63], v[168:171], v[192:195], v[60:63]
	v_mfma_f32_16x16x32_bf16 v[48:51], v[156:159], v[200:203], v[48:51]
	v_mfma_f32_16x16x32_bf16 v[44:47], v[168:171], v[200:203], v[44:47]
	v_mfma_f32_16x16x32_bf16 v[32:35], v[156:159], v[208:211], v[32:35]
	v_mfma_f32_16x16x32_bf16 v[28:31], v[168:171], v[208:211], v[28:31]
	v_mfma_f32_16x16x32_bf16 v[16:19], v[156:159], v[220:223], v[16:19]
	v_mfma_f32_16x16x32_bf16 v[12:15], v[168:171], v[220:223], v[12:15]
	s_setprio 0
	s_setprio 1
	v_mfma_f32_16x16x32_bf16 v[56:59], v[172:175], v[188:191], v[56:59]
	v_mfma_f32_16x16x32_bf16 v[52:55], v[180:183], v[188:191], v[52:55]
	v_mfma_f32_16x16x32_bf16 v[40:43], v[172:175], v[196:199], v[40:43]
	v_mfma_f32_16x16x32_bf16 v[36:39], v[180:183], v[196:199], v[36:39]
	v_mfma_f32_16x16x32_bf16 v[24:27], v[172:175], v[204:207], v[24:27]
	v_mfma_f32_16x16x32_bf16 v[20:23], v[180:183], v[204:207], v[20:23]
	v_mfma_f32_16x16x32_bf16 v[6:9], v[172:175], v[216:219], v[8:11]
	v_mfma_f32_16x16x32_bf16 v[2:5], v[180:183], v[216:219], v[2:5]
	v_mfma_f32_16x16x32_bf16 v[56:59], v[176:179], v[192:195], v[56:59]
	v_mfma_f32_16x16x32_bf16 v[52:55], v[184:187], v[192:195], v[52:55]
	v_mfma_f32_16x16x32_bf16 v[40:43], v[176:179], v[200:203], v[40:43]
	v_mfma_f32_16x16x32_bf16 v[36:39], v[184:187], v[200:203], v[36:39]
	v_mfma_f32_16x16x32_bf16 v[24:27], v[176:179], v[208:211], v[24:27]
	v_mfma_f32_16x16x32_bf16 v[20:23], v[184:187], v[208:211], v[20:23]
	v_mfma_f32_16x16x32_bf16 v[8:11], v[176:179], v[220:223], v[6:9]
	v_mfma_f32_16x16x32_bf16 v[4:7], v[184:187], v[220:223], v[2:5]
	s_setprio 0
	s_barrier
	s_add_i32 s74, s74, 2
	s_add_u32 s62, s62, 0x100
	s_addc_u32 s63, s63, 0
	s_cmp_gt_u32 s74, 45
	s_cbranch_scc1 .LBB0_755

; #define PG8_STAGE(bufoff, gbase, voff) do { _Pragma("unroll") for (int _i = 0; _i < 2; ++_i) \
;         __builtin_amdgcn_global_load_lds((const unsigned*)((const char*)(gbase) + (voff)[_i]), (LAS unsigned*)(lds + (bufoff) + ldsw + _i * 8192), 16, 0, 0); } while (0)
; #define PG8_LDA(dst, b, h) do { _Pragma("unroll") for (int m = 0; m < 4; ++m) _Pragma("unroll") for (int k = 0; k < 2; ++k) dst[m][k] = *(const LAS bf16x8*)(lds + PG8_SA(b, h) + aoff + m * 2048 + k * 1024); } while (0)
; #define PG8_LDB(dst, b, h) do { _Pragma("unroll") for (int n = 0; n < 2; ++n) _Pragma("unroll") for (int k = 0; k < 2; ++k) dst[n][k] = *(const LAS bf16x8*)(lds + PG8_SB(b, h) + boff + n * 2048 + k * 1024); } while (0)
; #define PG8_MMA(ai, bj, At, Bt) do { __builtin_amdgcn_s_setprio(1); _Pragma("unroll") for (int m = 0; m < 4; ++m) _Pragma("unroll") for (int n = 0; n < 2; ++n) _Pragma("unroll") for (int k = 0; k < 2; ++k) \
;         acc[ai][bj][m][n] = __builtin_amdgcn_mfma_f32_16x16x32_bf16(Bt[n][k], At[m][k], acc[ai][bj][m][n], 0, 0, 0); __builtin_amdgcn_s_setprio(0); } while (0)
; #define PG8_WAIT_V(n) asm volatile("s_waitcnt vmcnt(" #n ")" ::: "memory")
; #define PG8_WAIT_L(n) asm volatile("s_waitcnt lgkmcnt(" #n ")" ::: "memory")
; #define PG8_BAR __builtin_amdgcn_s_barrier()
; #define PG8_SCHED __builtin_amdgcn_sched_barrier(0)
; template <class Epi, class Sched>
; __device__ __forceinline__ void gemm_phase(LAS unsigned char* lds, const Gemm g, const Sched& S, const Epi& E) {
;     ...
;             const bool last = (t == nt - 2);
;             const char* a1 = cA + (size_t)(t + 1) * kstep;
;             const char* a2 = last ? nA : cA + (size_t)(t + 2) * kstep; const char* b2 = last ? nB : cB + (size_t)(t + 2) * kstep;
;             const char* a3 = a2 + kstep; const char* b3 = b2 + kstep;
;             PG8_LDB(B0, 0, 0); PG8_LDB(B1, 0, 1); PG8_SCHED; PG8_LDA(At, 0, 0); PG8_STAGE(PG8_SA(1, 1), a1 + hstepA, voffA);
;             PG8_WAIT_V(8); PG8_WAIT_L(0); PG8_BAR; PG8_MMA(0, 0, At, B0); PG8_MMA(0, 1, At, B1); PG8_BAR; PG8_SCHED;
;             PG8_LDA(At, 0, 1); PG8_STAGE(PG8_SB(0, 0), b2, voffB); PG8_STAGE(PG8_SB(0, 1), b2 + hstepB, voffB); PG8_STAGE(PG8_SA(0, 0), a2, voffA);
.LBB0_829:
	ds_read_b128 v[128:131], v167
	ds_read_b128 v[132:135], v167 offset:1024
	ds_read_b128 v[170:173], v167 offset:2048
	ds_read_b128 v[176:179], v167 offset:3072
	ds_read_b128 v[180:183], v169
	ds_read_b128 v[184:187], v169 offset:1024
	ds_read_b128 v[188:191], v169 offset:2048
	ds_read_b128 v[192:195], v169 offset:3072
	s_add_u32 s39, s60, 0xfff80080
	s_addc_u32 s43, s61, -1
	s_cmp_eq_u32 s35, 28
	s_cselect_b32 s65, s12, s43
	s_cselect_b32 s64, s13, s39
	s_cselect_b32 s63, s29, s34
	s_cselect_b32 s62, s30, s31
	v_lshl_add_u64 v[152:153], s[60:61], 0, v[144:145]
	s_add_i32 m0, s18, 0xc000
	ds_read_b128 v[196:199], v175
	ds_read_b128 v[200:203], v175 offset:1024
	ds_read_b128 v[204:207], v175 offset:2048
	ds_read_b128 v[208:211], v175 offset:3072
	ds_read_b128 v[216:219], v175 offset:4096
	ds_read_b128 v[220:223], v175 offset:5120
	ds_read_b128 v[224:227], v175 offset:6144
	ds_read_b128 v[228:231], v175 offset:7168
	global_load_lds_dwordx4 v[152:153], off
	v_lshl_add_u64 v[152:153], s[60:61], 0, v[146:147]
	s_add_i32 m0, s18, 0xe000
	s_nop 0
	global_load_lds_dwordx4 v[152:153], off
	s_waitcnt vmcnt(8) lgkmcnt(0)
	s_barrier
	s_setprio 1
	v_mfma_f32_16x16x32_bf16 v[124:127], v[128:131], v[196:199], v[124:127]
	v_mfma_f32_16x16x32_bf16 v[120:123], v[170:173], v[196:199], v[120:123]
	v_mfma_f32_16x16x32_bf16 v[108:111], v[128:131], v[204:207], v[108:111]
	v_mfma_f32_16x16x32_bf16 v[104:107], v[170:173], v[204:207], v[104:107]
	v_mfma_f32_16x16x32_bf16 v[92:95], v[128:131], v[216:219], v[92:95]
	v_mfma_f32_16x16x32_bf16 v[88:91], v[170:173], v[216:219], v[88:91]
	v_mfma_f32_16x16x32_bf16 v[76:79], v[128:131], v[224:227], v[76:79]
	v_mfma_f32_16x16x32_bf16 v[72:75], v[170:173], v[224:227], v[72:75]
	v_mfma_f32_16x16x32_bf16 v[124:127], v[132:135], v[200:203], v[124:127]
	v_mfma_f32_16x16x32_bf16 v[120:123], v[176:179], v[200:203], v[120:123]
	v_mfma_f32_16x16x32_bf16 v[108:111], v[132:135], v[208:211], v[108:111]
	v_mfma_f32_16x16x32_bf16 v[104:107], v[176:179], v[208:211], v[104:107]
	v_mfma_f32_16x16x32_bf16 v[92:95], v[132:135], v[220:223], v[92:95]
	v_mfma_f32_16x16x32_bf16 v[88:91], v[176:179], v[220:223], v[88:91]
	v_mfma_f32_16x16x32_bf16 v[76:79], v[132:135], v[228:231], v[76:79]
	v_mfma_f32_16x16x32_bf16 v[72:75], v[176:179], v[228:231], v[72:75]
	s_setprio 0
	s_setprio 1
	v_mfma_f32_16x16x32_bf16 v[116:119], v[180:183], v[196:199], v[116:119]
	v_mfma_f32_16x16x32_bf16 v[112:115], v[188:191], v[196:199], v[112:115]
	v_mfma_f32_16x16x32_bf16 v[100:103], v[180:183], v[204:207], v[100:103]
	v_mfma_f32_16x16x32_bf16 v[96:99], v[188:191], v[204:207], v[96:99]
	v_mfma_f32_16x16x32_bf16 v[84:87], v[180:183], v[216:219], v[84:87]
	v_mfma_f32_16x16x32_bf16 v[80:83], v[188:191], v[216:219], v[80:83]
	v_mfma_f32_16x16x32_bf16 v[68:71], v[180:183], v[224:227], v[68:71]
	v_mfma_f32_16x16x32_bf16 v[64:67], v[188:191], v[224:227], v[64:67]
	v_mfma_f32_16x16x32_bf16 v[116:119], v[184:187], v[200:203], v[116:119]
	v_mfma_f32_16x16x32_bf16 v[112:115], v[192:195], v[200:203], v[112:115]
	v_mfma_f32_16x16x32_bf16 v[100:103], v[184:187], v[208:211], v[100:103]
	v_mfma_f32_16x16x32_bf16 v[96:99], v[192:195], v[208:211], v[96:99]
	v_mfma_f32_16x16x32_bf16 v[84:87], v[184:187], v[220:223], v[84:87]
	v_mfma_f32_16x16x32_bf16 v[80:83], v[192:195], v[220:223], v[80:83]
	v_mfma_f32_16x16x32_bf16 v[68:71], v[184:187], v[228:231], v[68:71]
	v_mfma_f32_16x16x32_bf16 v[64:67], v[192:195], v[228:231], v[64:67]
	s_setprio 0
	s_barrier
	s_add_i32 s39, s33, s15
	v_lshl_add_u64 v[152:153], s[62:63], 0, v[138:139]
	s_mov_b32 m0, s39
	ds_read_b128 v[196:199], v175 offset:16384
	ds_read_b128 v[200:203], v175 offset:17408
	ds_read_b128 v[204:207], v175 offset:18432
	ds_read_b128 v[208:211], v175 offset:19456
	ds_read_b128 v[216:219], v175 offset:20480
	ds_read_b128 v[220:223], v175 offset:21504
	ds_read_b128 v[224:227], v175 offset:22528
	ds_read_b128 v[228:231], v175 offset:23552
	global_load_lds_dwordx4 v[152:153], off
	s_add_i32 m0, s39, 0x2000
	s_add_u32 s48, s62, 0x80000
	v_lshl_add_u64 v[156:157], s[62:63], 0, v[142:143]
	s_addc_u32 s49, s63, 0
	s_add_i32 s39, s36, s15
	global_load_lds_dwordx4 v[156:157], off
	v_lshl_add_u64 v[160:161], s[48:49], 0, v[138:139]
	s_mov_b32 m0, s39
	v_lshl_add_u64 v[232:233], s[64:65], 0, v[140:141]
	global_load_lds_dwordx4 v[160:161], off
	v_lshl_add_u64 v[160:161], s[48:49], 0, v[142:143]
	s_add_i32 m0, s39, 0x2000
	s_nop 0
	global_load_lds_dwordx4 v[160:161], off
	v_lshl_add_u64 v[160:161], s[64:65], 0, v[136:137]
	s_mov_b32 m0, s18
	s_nop 0
	global_load_lds_dwordx4 v[160:161], off
	s_mov_b32 m0, s19
	s_nop 0
	global_load_lds_dwordx4 v[232:233], off
	s_waitcnt vmcnt(8) lgkmcnt(0)
	s_barrier
; #define PG8_STAGE(bufoff, gbase, voff) do { _Pragma("unroll") for (int _i = 0; _i < 2; ++_i) \
;         __builtin_amdgcn_global_load_lds((const unsigned*)((const char*)(gbase) + (voff)[_i]), (LAS unsigned*)(lds + (bufoff) + ldsw + _i * 8192), 16, 0, 0); } while (0)
; #define PG8_LDA(dst, b, h) do { _Pragma("unroll") for (int m = 0; m < 4; ++m) _Pragma("unroll") for (int k = 0; k < 2; ++k) dst[m][k] = *(const LAS bf16x8*)(lds + PG8_SA(b, h) + aoff + m * 2048 + k * 1024); } while (0)
; #define PG8_LDB(dst, b, h) do { _Pragma("unroll") for (int n = 0; n < 2; ++n) _Pragma("unroll") for (int k = 0; k < 2; ++k) dst[n][k] = *(const LAS bf16x8*)(lds + PG8_SB(b, h) + boff + n * 2048 + k * 1024); } while (0)
; #define PG8_MMA(ai, bj, At, Bt) do { __builtin_amdgcn_s_setprio(1); _Pragma("unroll") for (int m = 0; m < 4; ++m) _Pragma("unroll") for (int n = 0; n < 2; ++n) _Pragma("unroll") for (int k = 0; k < 2; ++k) \
;         acc[ai][bj][m][n] = __builtin_amdgcn_mfma_f32_16x16x32_bf16(Bt[n][k], At[m][k], acc[ai][bj][m][n], 0, 0, 0); __builtin_amdgcn_s_setprio(0); } while (0)
; #define PG8_WAIT_V(n) asm volatile("s_waitcnt vmcnt(" #n ")" ::: "memory")
; #define PG8_WAIT_L(n) asm volatile("s_waitcnt lgkmcnt(" #n ")" ::: "memory")
; #define PG8_BAR __builtin_amdgcn_s_barrier()
; #define PG8_SCHED __builtin_amdgcn_sched_barrier(0)
; template <class Epi, class Sched>
; __device__ __forceinline__ void gemm_phase(LAS unsigned char* lds, const Gemm g, const Sched& S, const Epi& E) {
;     ...
;             PG8_LDA(At, 0, 1); PG8_STAGE(PG8_SB(0, 0), b2, voffB); PG8_STAGE(PG8_SB(0, 1), b2 + hstepB, voffB); PG8_STAGE(PG8_SA(0, 0), a2, voffA);
;             PG8_WAIT_V(8); PG8_WAIT_L(0); PG8_BAR; PG8_MMA(1, 0, At, B0); PG8_MMA(1, 1, At, B1); PG8_BAR; PG8_SCHED;
;             PG8_LDB(B0, 1, 0); PG8_LDB(B1, 1, 1); PG8_SCHED; PG8_LDA(At, 1, 0); PG8_STAGE(PG8_SA(0, 1), a2 + hstepA, voffA);
;             PG8_WAIT_V(8); PG8_WAIT_L(0); PG8_BAR; PG8_MMA(0, 0, At, B0); PG8_MMA(0, 1, At, B1); PG8_BAR; PG8_SCHED;
	s_setprio 1
	v_mfma_f32_16x16x32_bf16 v[60:63], v[128:131], v[196:199], v[60:63]
	v_mfma_f32_16x16x32_bf16 v[56:59], v[170:173], v[196:199], v[56:59]
	v_mfma_f32_16x16x32_bf16 v[44:47], v[128:131], v[204:207], v[44:47]
	v_mfma_f32_16x16x32_bf16 v[40:43], v[170:173], v[204:207], v[40:43]
	v_mfma_f32_16x16x32_bf16 v[28:31], v[128:131], v[216:219], v[28:31]
	v_mfma_f32_16x16x32_bf16 v[24:27], v[170:173], v[216:219], v[24:27]
	v_mfma_f32_16x16x32_bf16 v[12:15], v[128:131], v[224:227], v[12:15]
	v_mfma_f32_16x16x32_bf16 v[8:11], v[170:173], v[224:227], v[8:11]
	v_mfma_f32_16x16x32_bf16 v[60:63], v[132:135], v[200:203], v[60:63]
	v_mfma_f32_16x16x32_bf16 v[56:59], v[176:179], v[200:203], v[56:59]
	v_mfma_f32_16x16x32_bf16 v[44:47], v[132:135], v[208:211], v[44:47]
	v_mfma_f32_16x16x32_bf16 v[40:43], v[176:179], v[208:211], v[40:43]
	v_mfma_f32_16x16x32_bf16 v[28:31], v[132:135], v[220:223], v[28:31]
	v_mfma_f32_16x16x32_bf16 v[24:27], v[176:179], v[220:223], v[24:27]
	v_mfma_f32_16x16x32_bf16 v[12:15], v[132:135], v[228:231], v[12:15]
	v_mfma_f32_16x16x32_bf16 v[8:11], v[176:179], v[228:231], v[8:11]
	s_setprio 0
	s_setprio 1
	v_mfma_f32_16x16x32_bf16 v[52:55], v[180:183], v[196:199], v[52:55]
	v_mfma_f32_16x16x32_bf16 v[48:51], v[188:191], v[196:199], v[48:51]
	v_mfma_f32_16x16x32_bf16 v[36:39], v[180:183], v[204:207], v[36:39]
	v_mfma_f32_16x16x32_bf16 v[32:35], v[188:191], v[204:207], v[32:35]
	v_mfma_f32_16x16x32_bf16 v[20:23], v[180:183], v[216:219], v[20:23]
	v_mfma_f32_16x16x32_bf16 v[16:19], v[188:191], v[216:219], v[16:19]
	v_mfma_f32_16x16x32_bf16 v[4:7], v[180:183], v[224:227], v[4:7]
	v_mfma_f32_16x16x32_bf16 v[0:3], v[188:191], v[224:227], v[0:3]
	v_mfma_f32_16x16x32_bf16 v[52:55], v[184:187], v[200:203], v[52:55]
	v_mfma_f32_16x16x32_bf16 v[48:51], v[192:195], v[200:203], v[48:51]
	v_mfma_f32_16x16x32_bf16 v[36:39], v[184:187], v[208:211], v[36:39]
	v_mfma_f32_16x16x32_bf16 v[32:35], v[192:195], v[208:211], v[32:35]
	v_mfma_f32_16x16x32_bf16 v[20:23], v[184:187], v[220:223], v[20:23]
	v_mfma_f32_16x16x32_bf16 v[16:19], v[192:195], v[220:223], v[16:19]
	v_mfma_f32_16x16x32_bf16 v[4:7], v[184:187], v[228:231], v[4:7]
	v_mfma_f32_16x16x32_bf16 v[0:3], v[192:195], v[228:231], v[0:3]
	s_setprio 0
	s_barrier
	v_add_u32_e32 v154, s37, v165
	ds_read_b128 v[128:131], v154
	ds_read_b128 v[132:135], v154 offset:1024
	ds_read_b128 v[170:173], v154 offset:2048
	ds_read_b128 v[176:179], v154 offset:3072
	v_add_u32_e32 v154, s26, v165
	ds_read_b128 v[180:183], v154
	ds_read_b128 v[184:187], v154 offset:1024
	ds_read_b128 v[188:191], v154 offset:2048
	ds_read_b128 v[192:195], v154 offset:3072
	s_add_u32 s48, s64, 0x80000
	s_addc_u32 s49, s65, 0
	s_mov_b32 m0, s21
	v_lshl_add_u64 v[234:235], s[48:49], 0, v[136:137]
	ds_read_b128 v[196:199], v175 offset:32768
	ds_read_b128 v[200:203], v175 offset:33792
	ds_read_b128 v[204:207], v175 offset:34816
	ds_read_b128 v[208:211], v175 offset:35840
	ds_read_b128 v[216:219], v175 offset:36864
	ds_read_b128 v[220:223], v175 offset:37888
	ds_read_b128 v[224:227], v175 offset:38912
	ds_read_b128 v[228:231], v175 offset:39936
	global_load_lds_dwordx4 v[234:235], off
	v_lshl_add_u64 v[234:235], s[48:49], 0, v[140:141]
	s_mov_b32 m0, s22
	s_nop 0
	global_load_lds_dwordx4 v[234:235], off
	s_waitcnt vmcnt(8) lgkmcnt(0)
	s_barrier
	s_setprio 1
	v_mfma_f32_16x16x32_bf16 v[124:127], v[128:131], v[196:199], v[124:127]
	v_mfma_f32_16x16x32_bf16 v[120:123], v[170:173], v[196:199], v[120:123]
	v_mfma_f32_16x16x32_bf16 v[108:111], v[128:131], v[204:207], v[108:111]
	v_mfma_f32_16x16x32_bf16 v[104:107], v[170:173], v[204:207], v[104:107]
	v_mfma_f32_16x16x32_bf16 v[92:95], v[128:131], v[216:219], v[92:95]
	v_mfma_f32_16x16x32_bf16 v[88:91], v[170:173], v[216:219], v[88:91]
	v_mfma_f32_16x16x32_bf16 v[76:79], v[128:131], v[224:227], v[76:79]
	v_mfma_f32_16x16x32_bf16 v[72:75], v[170:173], v[224:227], v[72:75]
	v_mfma_f32_16x16x32_bf16 v[124:127], v[132:135], v[200:203], v[124:127]
	v_mfma_f32_16x16x32_bf16 v[120:123], v[176:179], v[200:203], v[120:123]
	v_mfma_f32_16x16x32_bf16 v[108:111], v[132:135], v[208:211], v[108:111]
	v_mfma_f32_16x16x32_bf16 v[104:107], v[176:179], v[208:211], v[104:107]
	v_mfma_f32_16x16x32_bf16 v[92:95], v[132:135], v[220:223], v[92:95]
	v_mfma_f32_16x16x32_bf16 v[88:91], v[176:179], v[220:223], v[88:91]
	v_mfma_f32_16x16x32_bf16 v[76:79], v[132:135], v[228:231], v[76:79]
	v_mfma_f32_16x16x32_bf16 v[72:75], v[176:179], v[228:231], v[72:75]
	s_setprio 0
	s_setprio 1
	v_mfma_f32_16x16x32_bf16 v[116:119], v[180:183], v[196:199], v[116:119]
	v_mfma_f32_16x16x32_bf16 v[112:115], v[188:191], v[196:199], v[112:115]
	v_mfma_f32_16x16x32_bf16 v[100:103], v[180:183], v[204:207], v[100:103]
	v_mfma_f32_16x16x32_bf16 v[96:99], v[188:191], v[204:207], v[96:99]
	v_mfma_f32_16x16x32_bf16 v[84:87], v[180:183], v[216:219], v[84:87]
	v_mfma_f32_16x16x32_bf16 v[80:83], v[188:191], v[216:219], v[80:83]
	v_mfma_f32_16x16x32_bf16 v[68:71], v[180:183], v[224:227], v[68:71]
	v_mfma_f32_16x16x32_bf16 v[64:67], v[188:191], v[224:227], v[64:67]
	v_mfma_f32_16x16x32_bf16 v[116:119], v[184:187], v[200:203], v[116:119]
	v_mfma_f32_16x16x32_bf16 v[112:115], v[192:195], v[200:203], v[112:115]
	v_mfma_f32_16x16x32_bf16 v[100:103], v[184:187], v[208:211], v[100:103]
	v_mfma_f32_16x16x32_bf16 v[96:99], v[192:195], v[208:211], v[96:99]
	v_mfma_f32_16x16x32_bf16 v[84:87], v[184:187], v[220:223], v[84:87]
	v_mfma_f32_16x16x32_bf16 v[80:83], v[192:195], v[220:223], v[80:83]
	v_mfma_f32_16x16x32_bf16 v[68:71], v[184:187], v[228:231], v[68:71]
	v_mfma_f32_16x16x32_bf16 v[64:67], v[192:195], v[228:231], v[64:67]
	s_setprio 0
	s_barrier
; #define PG8_STAGE(bufoff, gbase, voff) do { _Pragma("unroll") for (int _i = 0; _i < 2; ++_i) \
;         __builtin_amdgcn_global_load_lds((const unsigned*)((const char*)(gbase) + (voff)[_i]), (LAS unsigned*)(lds + (bufoff) + ldsw + _i * 8192), 16, 0, 0); } while (0)
; #define PG8_LDA(dst, b, h) do { _Pragma("unroll") for (int m = 0; m < 4; ++m) _Pragma("unroll") for (int k = 0; k < 2; ++k) dst[m][k] = *(const LAS bf16x8*)(lds + PG8_SA(b, h) + aoff + m * 2048 + k * 1024); } while (0)
; #define PG8_MMA(ai, bj, At, Bt) do { __builtin_amdgcn_s_setprio(1); _Pragma("unroll") for (int m = 0; m < 4; ++m) _Pragma("unroll") for (int n = 0; n < 2; ++n) _Pragma("unroll") for (int k = 0; k < 2; ++k) \
;         acc[ai][bj][m][n] = __builtin_amdgcn_mfma_f32_16x16x32_bf16(Bt[n][k], At[m][k], acc[ai][bj][m][n], 0, 0, 0); __builtin_amdgcn_s_setprio(0); } while (0)
; #define PG8_WAIT_V(n) asm volatile("s_waitcnt vmcnt(" #n ")" ::: "memory")
; #define PG8_WAIT_L(n) asm volatile("s_waitcnt lgkmcnt(" #n ")" ::: "memory")
; #define PG8_BAR __builtin_amdgcn_s_barrier()
; #define PG8_SCHED __builtin_amdgcn_sched_barrier(0)
; template <class Epi, class Sched>
; __device__ __forceinline__ void gemm_phase(LAS unsigned char* lds, const Gemm g, const Sched& S, const Epi& E) {
;     ...
;             PG8_LDA(At, 1, 1); PG8_STAGE(PG8_SB(1, 0), b3, voffB); PG8_STAGE(PG8_SB(1, 1), b3 + hstepB, voffB); PG8_STAGE(PG8_SA(1, 0), a3, voffA);
;             PG8_WAIT_V(8); PG8_WAIT_L(0); PG8_BAR; PG8_MMA(1, 0, At, B0); PG8_MMA(1, 1, At, B1); PG8_BAR; PG8_SCHED;
;         }
;         if (wr == 0) PG8_BAR;
	s_add_i32 s39, s37, s15
	v_lshl_add_u64 v[152:153], v[152:153], 0, s[8:9]
	s_mov_b32 m0, s39
	ds_read_b128 v[196:199], v175 offset:49152
	ds_read_b128 v[200:203], v175 offset:50176
	ds_read_b128 v[204:207], v175 offset:51200
	ds_read_b128 v[208:211], v175 offset:52224
	ds_read_b128 v[216:219], v175 offset:53248
	ds_read_b128 v[220:223], v175 offset:54272
	ds_read_b128 v[224:227], v175 offset:55296
	ds_read_b128 v[228:231], v175 offset:56320
	global_load_lds_dwordx4 v[152:153], off
	s_add_i32 m0, s39, 0x2000
	s_add_u32 s48, s62, 0x80080
	v_lshl_add_u64 v[152:153], v[156:157], 0, s[8:9]
	s_addc_u32 s49, s63, 0
	s_add_i32 s39, s26, s15
	global_load_lds_dwordx4 v[152:153], off
	v_lshl_add_u64 v[152:153], s[48:49], 0, v[138:139]
	s_mov_b32 m0, s39
	s_nop 0
	global_load_lds_dwordx4 v[152:153], off
	v_lshl_add_u64 v[152:153], s[48:49], 0, v[142:143]
	s_add_i32 m0, s39, 0x2000
	s_nop 0
	global_load_lds_dwordx4 v[152:153], off
	v_lshl_add_u64 v[152:153], v[160:161], 0, s[8:9]
	s_mov_b32 m0, s25
	s_nop 0
	global_load_lds_dwordx4 v[152:153], off
	v_lshl_add_u64 v[152:153], v[232:233], 0, s[8:9]
	s_mov_b32 m0, s27
	s_nop 0
	global_load_lds_dwordx4 v[152:153], off
	s_waitcnt vmcnt(8) lgkmcnt(0)
	s_barrier
	s_setprio 1
	v_mfma_f32_16x16x32_bf16 v[60:63], v[128:131], v[196:199], v[60:63]
	v_mfma_f32_16x16x32_bf16 v[56:59], v[170:173], v[196:199], v[56:59]
	v_mfma_f32_16x16x32_bf16 v[44:47], v[128:131], v[204:207], v[44:47]
	v_mfma_f32_16x16x32_bf16 v[40:43], v[170:173], v[204:207], v[40:43]
	v_mfma_f32_16x16x32_bf16 v[28:31], v[128:131], v[216:219], v[28:31]
	v_mfma_f32_16x16x32_bf16 v[24:27], v[170:173], v[216:219], v[24:27]
	v_mfma_f32_16x16x32_bf16 v[12:15], v[128:131], v[224:227], v[12:15]
	v_mfma_f32_16x16x32_bf16 v[8:11], v[170:173], v[224:227], v[8:11]
	v_mfma_f32_16x16x32_bf16 v[60:63], v[132:135], v[200:203], v[60:63]
	v_mfma_f32_16x16x32_bf16 v[56:59], v[176:179], v[200:203], v[56:59]
	v_mfma_f32_16x16x32_bf16 v[44:47], v[132:135], v[208:211], v[44:47]
	v_mfma_f32_16x16x32_bf16 v[40:43], v[176:179], v[208:211], v[40:43]
	v_mfma_f32_16x16x32_bf16 v[28:31], v[132:135], v[220:223], v[28:31]
	v_mfma_f32_16x16x32_bf16 v[24:27], v[176:179], v[220:223], v[24:27]
	v_mfma_f32_16x16x32_bf16 v[12:15], v[132:135], v[228:231], v[12:15]
	v_mfma_f32_16x16x32_bf16 v[8:11], v[176:179], v[228:231], v[8:11]
	s_setprio 0
	s_setprio 1
	v_mfma_f32_16x16x32_bf16 v[52:55], v[180:183], v[196:199], v[52:55]
	v_mfma_f32_16x16x32_bf16 v[48:51], v[188:191], v[196:199], v[48:51]
	v_mfma_f32_16x16x32_bf16 v[36:39], v[180:183], v[204:207], v[36:39]
	v_mfma_f32_16x16x32_bf16 v[32:35], v[188:191], v[204:207], v[32:35]
	v_mfma_f32_16x16x32_bf16 v[20:23], v[180:183], v[216:219], v[20:23]
	v_mfma_f32_16x16x32_bf16 v[16:19], v[188:191], v[216:219], v[16:19]
	v_mfma_f32_16x16x32_bf16 v[4:7], v[180:183], v[224:227], v[4:7]
	v_mfma_f32_16x16x32_bf16 v[0:3], v[188:191], v[224:227], v[0:3]
	v_mfma_f32_16x16x32_bf16 v[52:55], v[184:187], v[200:203], v[52:55]
	v_mfma_f32_16x16x32_bf16 v[48:51], v[192:195], v[200:203], v[48:51]
	v_mfma_f32_16x16x32_bf16 v[36:39], v[184:187], v[208:211], v[36:39]
	v_mfma_f32_16x16x32_bf16 v[32:35], v[192:195], v[208:211], v[32:35]
	v_mfma_f32_16x16x32_bf16 v[20:23], v[184:187], v[220:223], v[20:23]
	v_mfma_f32_16x16x32_bf16 v[16:19], v[192:195], v[220:223], v[16:19]
	v_mfma_f32_16x16x32_bf16 v[4:7], v[184:187], v[228:231], v[4:7]
	v_mfma_f32_16x16x32_bf16 v[0:3], v[192:195], v[228:231], v[0:3]
	s_setprio 0
	s_barrier
	s_add_i32 s35, s35, 2
	s_add_u32 s60, s60, 0x100
	s_addc_u32 s61, s61, 0
	s_add_u32 s31, s31, 0x100
	s_addc_u32 s34, s34, 0
	s_cmp_gt_u32 s35, 29
	s_cbranch_scc0 .LBB0_829
	s_and_b64 vcc, exec, s[10:11]
	s_cbranch_vccz .LBB0_832
	s_barrier

; #define PG8_STAGE(bufoff, gbase, voff) do { _Pragma("unroll") for (int _i = 0; _i < 2; ++_i) \
;         __builtin_amdgcn_global_load_lds((const unsigned*)((const char*)(gbase) + (voff)[_i]), (LAS unsigned*)(lds + (bufoff) + ldsw + _i * 8192), 16, 0, 0); } while (0)
; #define PG8_LDA(dst, b, h) do { _Pragma("unroll") for (int m = 0; m < 4; ++m) _Pragma("unroll") for (int k = 0; k < 2; ++k) dst[m][k] = *(const LAS bf16x8*)(lds + PG8_SA(b, h) + aoff + m * 2048 + k * 1024); } while (0)
; #define PG8_LDB(dst, b, h) do { _Pragma("unroll") for (int n = 0; n < 2; ++n) _Pragma("unroll") for (int k = 0; k < 2; ++k) dst[n][k] = *(const LAS bf16x8*)(lds + PG8_SB(b, h) + boff + n * 2048 + k * 1024); } while (0)
; #define PG8_MMA(ai, bj, At, Bt) do { __builtin_amdgcn_s_setprio(1); _Pragma("unroll") for (int m = 0; m < 4; ++m) _Pragma("unroll") for (int n = 0; n < 2; ++n) _Pragma("unroll") for (int k = 0; k < 2; ++k) \
;         acc[ai][bj][m][n] = __builtin_amdgcn_mfma_f32_16x16x32_bf16(Bt[n][k], At[m][k], acc[ai][bj][m][n], 0, 0, 0); __builtin_amdgcn_s_setprio(0); } while (0)
; #define PG8_WAIT_V(n) asm volatile("s_waitcnt vmcnt(" #n ")" ::: "memory")
; #define PG8_WAIT_L(n) asm volatile("s_waitcnt lgkmcnt(" #n ")" ::: "memory")
; #define PG8_BAR __builtin_amdgcn_s_barrier()
; #define PG8_SCHED __builtin_amdgcn_sched_barrier(0)
; template <class Epi, class Sched>
; __device__ __forceinline__ void gemm_phase(LAS unsigned char* lds, const Gemm g, const Sched& S, const Epi& E) {
;     ...
;             const bool last = (t == nt - 2);
;             const char* a1 = cA + (size_t)(t + 1) * kstep;
;             const char* a2 = last ? nA : cA + (size_t)(t + 2) * kstep; const char* b2 = last ? nB : cB + (size_t)(t + 2) * kstep;
;             const char* a3 = a2 + kstep; const char* b3 = b2 + kstep;
;             PG8_LDB(B0, 0, 0); PG8_LDB(B1, 0, 1); PG8_SCHED; PG8_LDA(At, 0, 0); PG8_STAGE(PG8_SA(1, 1), a1 + hstepA, voffA);
;             PG8_WAIT_V(8); PG8_WAIT_L(0); PG8_BAR; PG8_MMA(0, 0, At, B0); PG8_MMA(0, 1, At, B1); PG8_BAR; PG8_SCHED;
;             PG8_LDA(At, 0, 1); PG8_STAGE(PG8_SB(0, 0), b2, voffB); PG8_STAGE(PG8_SB(0, 1), b2 + hstepB, voffB); PG8_STAGE(PG8_SA(0, 0), a2, voffA);
.LBB0_923:
	ds_read_b128 v[64:67], v209
	ds_read_b128 v[68:71], v209 offset:1024
	ds_read_b128 v[72:75], v209 offset:2048
	ds_read_b128 v[76:79], v209 offset:3072
	ds_read_b128 v[84:87], v210
	ds_read_b128 v[88:91], v210 offset:1024
	ds_read_b128 v[92:95], v210 offset:2048
	ds_read_b128 v[96:99], v210 offset:3072
	s_add_u32 s4, s0, 0xfff80080
	s_addc_u32 s5, s1, -1
	s_cmp_eq_u32 s62, 28
	s_cselect_b32 s7, s12, s5
	s_cselect_b32 s6, s13, s4
	s_cselect_b32 s5, s53, s61
	s_cselect_b32 s4, s55, s60
	v_lshl_add_u64 v[218:219], s[0:1], 0, v[170:171]
	s_add_i32 m0, s15, 0xc000
	ds_read_b128 v[174:177], v211
	ds_read_b128 v[178:181], v211 offset:1024
	ds_read_b128 v[182:185], v211 offset:2048
	ds_read_b128 v[186:189], v211 offset:3072
	ds_read_b128 v[190:193], v211 offset:4096
	ds_read_b128 v[194:197], v211 offset:5120
	ds_read_b128 v[198:201], v211 offset:6144
	ds_read_b128 v[202:205], v211 offset:7168
	global_load_lds_dwordx4 v[218:219], off
	v_lshl_add_u64 v[218:219], s[0:1], 0, v[172:173]
	s_add_i32 m0, s15, 0xe000
	s_nop 0
	global_load_lds_dwordx4 v[218:219], off
	s_waitcnt vmcnt(8) lgkmcnt(0)
	s_barrier
	s_setprio 1
	v_mfma_f32_16x16x32_bf16 v[156:159], v[64:67], v[174:177], v[156:159]
	v_mfma_f32_16x16x32_bf16 v[148:151], v[72:75], v[174:177], v[148:151]
	v_mfma_f32_16x16x32_bf16 v[140:143], v[64:67], v[182:185], v[140:143]
	v_mfma_f32_16x16x32_bf16 v[136:139], v[72:75], v[182:185], v[136:139]
	v_mfma_f32_16x16x32_bf16 v[124:127], v[64:67], v[190:193], v[124:127]
	v_mfma_f32_16x16x32_bf16 v[120:123], v[72:75], v[190:193], v[120:123]
	v_mfma_f32_16x16x32_bf16 v[108:111], v[64:67], v[198:201], v[108:111]
	v_mfma_f32_16x16x32_bf16 v[104:107], v[72:75], v[198:201], v[104:107]
	v_mfma_f32_16x16x32_bf16 v[156:159], v[68:71], v[178:181], v[156:159]
	v_mfma_f32_16x16x32_bf16 v[148:151], v[76:79], v[178:181], v[148:151]
	v_mfma_f32_16x16x32_bf16 v[140:143], v[68:71], v[186:189], v[140:143]
	v_mfma_f32_16x16x32_bf16 v[136:139], v[76:79], v[186:189], v[136:139]
	v_mfma_f32_16x16x32_bf16 v[124:127], v[68:71], v[194:197], v[124:127]
	v_mfma_f32_16x16x32_bf16 v[120:123], v[76:79], v[194:197], v[120:123]
	v_mfma_f32_16x16x32_bf16 v[108:111], v[68:71], v[202:205], v[108:111]
	v_mfma_f32_16x16x32_bf16 v[104:107], v[76:79], v[202:205], v[104:107]
	s_setprio 0
	s_setprio 1
	v_mfma_f32_16x16x32_bf16 v[152:155], v[84:87], v[174:177], v[152:155]
	v_mfma_f32_16x16x32_bf16 v[144:147], v[92:95], v[174:177], v[144:147]
	v_mfma_f32_16x16x32_bf16 v[132:135], v[84:87], v[182:185], v[132:135]
	v_mfma_f32_16x16x32_bf16 v[128:131], v[92:95], v[182:185], v[128:131]
	v_mfma_f32_16x16x32_bf16 v[116:119], v[84:87], v[190:193], v[116:119]
	v_mfma_f32_16x16x32_bf16 v[112:115], v[92:95], v[190:193], v[112:115]
	v_mfma_f32_16x16x32_bf16 v[80:83], v[84:87], v[198:201], v[80:83]
	v_mfma_f32_16x16x32_bf16 v[100:103], v[92:95], v[198:201], v[100:103]
	v_mfma_f32_16x16x32_bf16 v[152:155], v[88:91], v[178:181], v[152:155]
	v_mfma_f32_16x16x32_bf16 v[144:147], v[96:99], v[178:181], v[144:147]
	v_mfma_f32_16x16x32_bf16 v[132:135], v[88:91], v[186:189], v[132:135]
	v_mfma_f32_16x16x32_bf16 v[128:131], v[96:99], v[186:189], v[128:131]
	v_mfma_f32_16x16x32_bf16 v[116:119], v[88:91], v[194:197], v[116:119]
	v_mfma_f32_16x16x32_bf16 v[112:115], v[96:99], v[194:197], v[112:115]
	v_mfma_f32_16x16x32_bf16 v[80:83], v[88:91], v[202:205], v[80:83]
	v_mfma_f32_16x16x32_bf16 v[100:103], v[96:99], v[202:205], v[100:103]
	s_setprio 0
	s_barrier
	s_add_i32 s63, s33, s14
	v_lshl_add_u64 v[218:219], s[4:5], 0, v[162:163]
	s_mov_b32 m0, s63
	ds_read_b128 v[174:177], v211 offset:16384
	ds_read_b128 v[178:181], v211 offset:17408
	ds_read_b128 v[182:185], v211 offset:18432
	ds_read_b128 v[186:189], v211 offset:19456
	ds_read_b128 v[190:193], v211 offset:20480
	ds_read_b128 v[194:197], v211 offset:21504
	ds_read_b128 v[198:201], v211 offset:22528
	ds_read_b128 v[202:205], v211 offset:23552
	global_load_lds_dwordx4 v[218:219], off
	s_add_i32 m0, s63, 0x2000
	s_add_u32 s70, s4, 0x80000
	v_lshl_add_u64 v[220:221], s[4:5], 0, v[166:167]
	s_addc_u32 s71, s5, 0
	s_add_i32 s63, s36, s14
	global_load_lds_dwordx4 v[220:221], off
	v_lshl_add_u64 v[222:223], s[70:71], 0, v[162:163]
	s_mov_b32 m0, s63
	v_lshl_add_u64 v[224:225], s[6:7], 0, v[164:165]
	global_load_lds_dwordx4 v[222:223], off
	v_lshl_add_u64 v[222:223], s[70:71], 0, v[166:167]
	s_add_i32 m0, s63, 0x2000
	s_nop 0
	global_load_lds_dwordx4 v[222:223], off
	v_lshl_add_u64 v[222:223], s[6:7], 0, v[160:161]
	s_mov_b32 m0, s15
	s_nop 0
	global_load_lds_dwordx4 v[222:223], off
	s_mov_b32 m0, s21
	s_nop 0
	global_load_lds_dwordx4 v[224:225], off
	s_waitcnt vmcnt(8) lgkmcnt(0)
	s_barrier
; #define PG8_STAGE(bufoff, gbase, voff) do { _Pragma("unroll") for (int _i = 0; _i < 2; ++_i) \
;         __builtin_amdgcn_global_load_lds((const unsigned*)((const char*)(gbase) + (voff)[_i]), (LAS unsigned*)(lds + (bufoff) + ldsw + _i * 8192), 16, 0, 0); } while (0)
; #define PG8_LDA(dst, b, h) do { _Pragma("unroll") for (int m = 0; m < 4; ++m) _Pragma("unroll") for (int k = 0; k < 2; ++k) dst[m][k] = *(const LAS bf16x8*)(lds + PG8_SA(b, h) + aoff + m * 2048 + k * 1024); } while (0)
; #define PG8_LDB(dst, b, h) do { _Pragma("unroll") for (int n = 0; n < 2; ++n) _Pragma("unroll") for (int k = 0; k < 2; ++k) dst[n][k] = *(const LAS bf16x8*)(lds + PG8_SB(b, h) + boff + n * 2048 + k * 1024); } while (0)
; #define PG8_MMA(ai, bj, At, Bt) do { __builtin_amdgcn_s_setprio(1); _Pragma("unroll") for (int m = 0; m < 4; ++m) _Pragma("unroll") for (int n = 0; n < 2; ++n) _Pragma("unroll") for (int k = 0; k < 2; ++k) \
;         acc[ai][bj][m][n] = __builtin_amdgcn_mfma_f32_16x16x32_bf16(Bt[n][k], At[m][k], acc[ai][bj][m][n], 0, 0, 0); __builtin_amdgcn_s_setprio(0); } while (0)
; #define PG8_WAIT_V(n) asm volatile("s_waitcnt vmcnt(" #n ")" ::: "memory")
; #define PG8_WAIT_L(n) asm volatile("s_waitcnt lgkmcnt(" #n ")" ::: "memory")
; #define PG8_BAR __builtin_amdgcn_s_barrier()
; #define PG8_SCHED __builtin_amdgcn_sched_barrier(0)
; template <class Epi, class Sched>
; __device__ __forceinline__ void gemm_phase(LAS unsigned char* lds, const Gemm g, const Sched& S, const Epi& E) {
;     ...
;             PG8_LDA(At, 0, 1); PG8_STAGE(PG8_SB(0, 0), b2, voffB); PG8_STAGE(PG8_SB(0, 1), b2 + hstepB, voffB); PG8_STAGE(PG8_SA(0, 0), a2, voffA);
;             PG8_WAIT_V(8); PG8_WAIT_L(0); PG8_BAR; PG8_MMA(1, 0, At, B0); PG8_MMA(1, 1, At, B1); PG8_BAR; PG8_SCHED;
;             PG8_LDB(B0, 1, 0); PG8_LDB(B1, 1, 1); PG8_SCHED; PG8_LDA(At, 1, 0); PG8_STAGE(PG8_SA(0, 1), a2 + hstepA, voffA);
;             PG8_WAIT_V(8); PG8_WAIT_L(0); PG8_BAR; PG8_MMA(0, 0, At, B0); PG8_MMA(0, 1, At, B1); PG8_BAR; PG8_SCHED;
	s_setprio 1
	v_mfma_f32_16x16x32_bf16 v[60:63], v[64:67], v[174:177], v[60:63]
	v_mfma_f32_16x16x32_bf16 v[56:59], v[72:75], v[174:177], v[56:59]
	v_mfma_f32_16x16x32_bf16 v[44:47], v[64:67], v[182:185], v[44:47]
	v_mfma_f32_16x16x32_bf16 v[40:43], v[72:75], v[182:185], v[40:43]
	v_mfma_f32_16x16x32_bf16 v[28:31], v[64:67], v[190:193], v[28:31]
	v_mfma_f32_16x16x32_bf16 v[24:27], v[72:75], v[190:193], v[24:27]
	v_mfma_f32_16x16x32_bf16 v[12:15], v[64:67], v[198:201], v[12:15]
	v_mfma_f32_16x16x32_bf16 v[8:11], v[72:75], v[198:201], v[8:11]
	v_mfma_f32_16x16x32_bf16 v[60:63], v[68:71], v[178:181], v[60:63]
	v_mfma_f32_16x16x32_bf16 v[56:59], v[76:79], v[178:181], v[56:59]
	v_mfma_f32_16x16x32_bf16 v[44:47], v[68:71], v[186:189], v[44:47]
	v_mfma_f32_16x16x32_bf16 v[40:43], v[76:79], v[186:189], v[40:43]
	v_mfma_f32_16x16x32_bf16 v[28:31], v[68:71], v[194:197], v[28:31]
	v_mfma_f32_16x16x32_bf16 v[24:27], v[76:79], v[194:197], v[24:27]
	v_mfma_f32_16x16x32_bf16 v[12:15], v[68:71], v[202:205], v[12:15]
	v_mfma_f32_16x16x32_bf16 v[8:11], v[76:79], v[202:205], v[8:11]
	s_setprio 0
	s_setprio 1
	v_mfma_f32_16x16x32_bf16 v[52:55], v[84:87], v[174:177], v[52:55]
	v_mfma_f32_16x16x32_bf16 v[48:51], v[92:95], v[174:177], v[48:51]
	v_mfma_f32_16x16x32_bf16 v[36:39], v[84:87], v[182:185], v[36:39]
	v_mfma_f32_16x16x32_bf16 v[32:35], v[92:95], v[182:185], v[32:35]
	v_mfma_f32_16x16x32_bf16 v[20:23], v[84:87], v[190:193], v[20:23]
	v_mfma_f32_16x16x32_bf16 v[16:19], v[92:95], v[190:193], v[16:19]
	v_mfma_f32_16x16x32_bf16 v[0:3], v[84:87], v[198:201], v[0:3]
	v_mfma_f32_16x16x32_bf16 v[4:7], v[92:95], v[198:201], v[4:7]
	v_mfma_f32_16x16x32_bf16 v[52:55], v[88:91], v[178:181], v[52:55]
	v_mfma_f32_16x16x32_bf16 v[48:51], v[96:99], v[178:181], v[48:51]
	v_mfma_f32_16x16x32_bf16 v[36:39], v[88:91], v[186:189], v[36:39]
	v_mfma_f32_16x16x32_bf16 v[32:35], v[96:99], v[186:189], v[32:35]
	v_mfma_f32_16x16x32_bf16 v[20:23], v[88:91], v[194:197], v[20:23]
	v_mfma_f32_16x16x32_bf16 v[16:19], v[96:99], v[194:197], v[16:19]
	v_mfma_f32_16x16x32_bf16 v[0:3], v[88:91], v[202:205], v[0:3]
	v_mfma_f32_16x16x32_bf16 v[4:7], v[96:99], v[202:205], v[4:7]
	s_setprio 0
	s_barrier
	v_add_u32_e32 v76, s37, v208
	v_add_u32_e32 v96, s26, v208
	ds_read_b128 v[64:67], v76
	ds_read_b128 v[68:71], v76 offset:1024
	ds_read_b128 v[72:75], v76 offset:2048
	ds_read_b128 v[76:79], v76 offset:3072
	ds_read_b128 v[84:87], v96
	ds_read_b128 v[88:91], v96 offset:1024
	ds_read_b128 v[92:95], v96 offset:2048
	ds_read_b128 v[96:99], v96 offset:3072
	s_add_u32 s6, s6, 0x80000
	s_addc_u32 s7, s7, 0
	s_mov_b32 m0, s22
	v_lshl_add_u64 v[226:227], s[6:7], 0, v[160:161]
	ds_read_b128 v[174:177], v211 offset:32768
	ds_read_b128 v[178:181], v211 offset:33792
	ds_read_b128 v[182:185], v211 offset:34816
	ds_read_b128 v[186:189], v211 offset:35840
	ds_read_b128 v[190:193], v211 offset:36864
	ds_read_b128 v[194:197], v211 offset:37888
	ds_read_b128 v[198:201], v211 offset:38912
	ds_read_b128 v[202:205], v211 offset:39936
	global_load_lds_dwordx4 v[226:227], off
	v_lshl_add_u64 v[226:227], s[6:7], 0, v[164:165]
	s_mov_b32 m0, s23
	s_nop 0
	global_load_lds_dwordx4 v[226:227], off
	s_waitcnt vmcnt(8) lgkmcnt(0)
	s_barrier
	s_setprio 1
	v_mfma_f32_16x16x32_bf16 v[156:159], v[64:67], v[174:177], v[156:159]
	v_mfma_f32_16x16x32_bf16 v[148:151], v[72:75], v[174:177], v[148:151]
	v_mfma_f32_16x16x32_bf16 v[140:143], v[64:67], v[182:185], v[140:143]
	v_mfma_f32_16x16x32_bf16 v[136:139], v[72:75], v[182:185], v[136:139]
	v_mfma_f32_16x16x32_bf16 v[124:127], v[64:67], v[190:193], v[124:127]
	v_mfma_f32_16x16x32_bf16 v[120:123], v[72:75], v[190:193], v[120:123]
	v_mfma_f32_16x16x32_bf16 v[108:111], v[64:67], v[198:201], v[108:111]
	v_mfma_f32_16x16x32_bf16 v[104:107], v[72:75], v[198:201], v[104:107]
	v_mfma_f32_16x16x32_bf16 v[156:159], v[68:71], v[178:181], v[156:159]
	v_mfma_f32_16x16x32_bf16 v[148:151], v[76:79], v[178:181], v[148:151]
	v_mfma_f32_16x16x32_bf16 v[140:143], v[68:71], v[186:189], v[140:143]
	v_mfma_f32_16x16x32_bf16 v[136:139], v[76:79], v[186:189], v[136:139]
	v_mfma_f32_16x16x32_bf16 v[124:127], v[68:71], v[194:197], v[124:127]
	v_mfma_f32_16x16x32_bf16 v[120:123], v[76:79], v[194:197], v[120:123]
	v_mfma_f32_16x16x32_bf16 v[108:111], v[68:71], v[202:205], v[108:111]
	v_mfma_f32_16x16x32_bf16 v[104:107], v[76:79], v[202:205], v[104:107]
	s_setprio 0
	s_setprio 1
	v_mfma_f32_16x16x32_bf16 v[152:155], v[84:87], v[174:177], v[152:155]
	v_mfma_f32_16x16x32_bf16 v[144:147], v[92:95], v[174:177], v[144:147]
	v_mfma_f32_16x16x32_bf16 v[132:135], v[84:87], v[182:185], v[132:135]
	v_mfma_f32_16x16x32_bf16 v[128:131], v[92:95], v[182:185], v[128:131]
	v_mfma_f32_16x16x32_bf16 v[116:119], v[84:87], v[190:193], v[116:119]
	v_mfma_f32_16x16x32_bf16 v[112:115], v[92:95], v[190:193], v[112:115]
	v_mfma_f32_16x16x32_bf16 v[80:83], v[84:87], v[198:201], v[80:83]
	v_mfma_f32_16x16x32_bf16 v[100:103], v[92:95], v[198:201], v[100:103]
	v_mfma_f32_16x16x32_bf16 v[152:155], v[88:91], v[178:181], v[152:155]
	v_mfma_f32_16x16x32_bf16 v[144:147], v[96:99], v[178:181], v[144:147]
	v_mfma_f32_16x16x32_bf16 v[132:135], v[88:91], v[186:189], v[132:135]
	v_mfma_f32_16x16x32_bf16 v[128:131], v[96:99], v[186:189], v[128:131]
	v_mfma_f32_16x16x32_bf16 v[116:119], v[88:91], v[194:197], v[116:119]
	v_mfma_f32_16x16x32_bf16 v[112:115], v[96:99], v[194:197], v[112:115]
	v_mfma_f32_16x16x32_bf16 v[80:83], v[88:91], v[202:205], v[80:83]
	v_mfma_f32_16x16x32_bf16 v[100:103], v[96:99], v[202:205], v[100:103]
	s_setprio 0
	s_barrier
; #define PG8_STAGE(bufoff, gbase, voff) do { _Pragma("unroll") for (int _i = 0; _i < 2; ++_i) \
;         __builtin_amdgcn_global_load_lds((const unsigned*)((const char*)(gbase) + (voff)[_i]), (LAS unsigned*)(lds + (bufoff) + ldsw + _i * 8192), 16, 0, 0); } while (0)
; #define PG8_LDA(dst, b, h) do { _Pragma("unroll") for (int m = 0; m < 4; ++m) _Pragma("unroll") for (int k = 0; k < 2; ++k) dst[m][k] = *(const LAS bf16x8*)(lds + PG8_SA(b, h) + aoff + m * 2048 + k * 1024); } while (0)
; #define PG8_MMA(ai, bj, At, Bt) do { __builtin_amdgcn_s_setprio(1); _Pragma("unroll") for (int m = 0; m < 4; ++m) _Pragma("unroll") for (int n = 0; n < 2; ++n) _Pragma("unroll") for (int k = 0; k < 2; ++k) \
;         acc[ai][bj][m][n] = __builtin_amdgcn_mfma_f32_16x16x32_bf16(Bt[n][k], At[m][k], acc[ai][bj][m][n], 0, 0, 0); __builtin_amdgcn_s_setprio(0); } while (0)
; #define PG8_WAIT_V(n) asm volatile("s_waitcnt vmcnt(" #n ")" ::: "memory")
; #define PG8_WAIT_L(n) asm volatile("s_waitcnt lgkmcnt(" #n ")" ::: "memory")
; #define PG8_BAR __builtin_amdgcn_s_barrier()
; #define PG8_SCHED __builtin_amdgcn_sched_barrier(0)
; template <class Epi, class Sched>
; __device__ __forceinline__ void gemm_phase(LAS unsigned char* lds, const Gemm g, const Sched& S, const Epi& E) {
;     ...
;             PG8_LDA(At, 1, 1); PG8_STAGE(PG8_SB(1, 0), b3, voffB); PG8_STAGE(PG8_SB(1, 1), b3 + hstepB, voffB); PG8_STAGE(PG8_SA(1, 0), a3, voffA);
;             PG8_WAIT_V(8); PG8_WAIT_L(0); PG8_BAR; PG8_MMA(1, 0, At, B0); PG8_MMA(1, 1, At, B1); PG8_BAR; PG8_SCHED;
;         }
;         if (wr == 0) PG8_BAR;
	s_add_i32 s6, s37, s14
	v_lshl_add_u64 v[218:219], v[218:219], 0, s[48:49]
	s_mov_b32 m0, s6
	ds_read_b128 v[174:177], v211 offset:49152
	ds_read_b128 v[178:181], v211 offset:50176
	ds_read_b128 v[182:185], v211 offset:51200
	ds_read_b128 v[186:189], v211 offset:52224
	ds_read_b128 v[190:193], v211 offset:53248
	ds_read_b128 v[194:197], v211 offset:54272
	ds_read_b128 v[198:201], v211 offset:55296
	ds_read_b128 v[202:205], v211 offset:56320
	global_load_lds_dwordx4 v[218:219], off
	s_add_i32 m0, s6, 0x2000
	s_add_u32 s4, s4, 0x80080
	v_lshl_add_u64 v[218:219], v[220:221], 0, s[48:49]
	s_addc_u32 s5, s5, 0
	s_add_i32 s6, s26, s14
	global_load_lds_dwordx4 v[218:219], off
	v_lshl_add_u64 v[218:219], s[4:5], 0, v[162:163]
	s_mov_b32 m0, s6
	s_nop 0
	global_load_lds_dwordx4 v[218:219], off
	v_lshl_add_u64 v[218:219], s[4:5], 0, v[166:167]
	s_add_i32 m0, s6, 0x2000
	s_nop 0
	global_load_lds_dwordx4 v[218:219], off
	v_lshl_add_u64 v[218:219], v[222:223], 0, s[48:49]
	s_mov_b32 m0, s45
	s_nop 0
	global_load_lds_dwordx4 v[218:219], off
	v_lshl_add_u64 v[218:219], v[224:225], 0, s[48:49]
	s_mov_b32 m0, s64
	s_nop 0
	global_load_lds_dwordx4 v[218:219], off
	s_waitcnt vmcnt(8) lgkmcnt(0)
	s_barrier
	s_setprio 1
	v_mfma_f32_16x16x32_bf16 v[60:63], v[64:67], v[174:177], v[60:63]
	v_mfma_f32_16x16x32_bf16 v[56:59], v[72:75], v[174:177], v[56:59]
	v_mfma_f32_16x16x32_bf16 v[44:47], v[64:67], v[182:185], v[44:47]
	v_mfma_f32_16x16x32_bf16 v[40:43], v[72:75], v[182:185], v[40:43]
	v_mfma_f32_16x16x32_bf16 v[28:31], v[64:67], v[190:193], v[28:31]
	v_mfma_f32_16x16x32_bf16 v[24:27], v[72:75], v[190:193], v[24:27]
	v_mfma_f32_16x16x32_bf16 v[12:15], v[64:67], v[198:201], v[12:15]
	v_mfma_f32_16x16x32_bf16 v[8:11], v[72:75], v[198:201], v[8:11]
	v_mfma_f32_16x16x32_bf16 v[60:63], v[68:71], v[178:181], v[60:63]
	v_mfma_f32_16x16x32_bf16 v[56:59], v[76:79], v[178:181], v[56:59]
	v_mfma_f32_16x16x32_bf16 v[44:47], v[68:71], v[186:189], v[44:47]
	v_mfma_f32_16x16x32_bf16 v[40:43], v[76:79], v[186:189], v[40:43]
	v_mfma_f32_16x16x32_bf16 v[28:31], v[68:71], v[194:197], v[28:31]
	v_mfma_f32_16x16x32_bf16 v[24:27], v[76:79], v[194:197], v[24:27]
	v_mfma_f32_16x16x32_bf16 v[12:15], v[68:71], v[202:205], v[12:15]
	v_mfma_f32_16x16x32_bf16 v[8:11], v[76:79], v[202:205], v[8:11]
	s_setprio 0
	s_setprio 1
	v_mfma_f32_16x16x32_bf16 v[52:55], v[84:87], v[174:177], v[52:55]
	v_mfma_f32_16x16x32_bf16 v[48:51], v[92:95], v[174:177], v[48:51]
	v_mfma_f32_16x16x32_bf16 v[36:39], v[84:87], v[182:185], v[36:39]
	v_mfma_f32_16x16x32_bf16 v[32:35], v[92:95], v[182:185], v[32:35]
	v_mfma_f32_16x16x32_bf16 v[20:23], v[84:87], v[190:193], v[20:23]
	v_mfma_f32_16x16x32_bf16 v[16:19], v[92:95], v[190:193], v[16:19]
	v_mfma_f32_16x16x32_bf16 v[0:3], v[84:87], v[198:201], v[0:3]
	v_mfma_f32_16x16x32_bf16 v[4:7], v[92:95], v[198:201], v[4:7]
	v_mfma_f32_16x16x32_bf16 v[52:55], v[88:91], v[178:181], v[52:55]
	v_mfma_f32_16x16x32_bf16 v[48:51], v[96:99], v[178:181], v[48:51]
	v_mfma_f32_16x16x32_bf16 v[36:39], v[88:91], v[186:189], v[36:39]
	v_mfma_f32_16x16x32_bf16 v[32:35], v[96:99], v[186:189], v[32:35]
	v_mfma_f32_16x16x32_bf16 v[20:23], v[88:91], v[194:197], v[20:23]
	v_mfma_f32_16x16x32_bf16 v[16:19], v[96:99], v[194:197], v[16:19]
	v_mfma_f32_16x16x32_bf16 v[0:3], v[88:91], v[202:205], v[0:3]
	v_mfma_f32_16x16x32_bf16 v[4:7], v[96:99], v[202:205], v[4:7]
	s_setprio 0
	s_barrier
	s_add_i32 s62, s62, 2
	s_add_u32 s0, s0, 0x100
	s_addc_u32 s1, s1, 0
	s_add_u32 s60, s60, 0x100
	s_addc_u32 s61, s61, 0
	s_cmp_gt_u32 s62, 29
	s_cbranch_scc0 .LBB0_923
	s_and_b64 vcc, exec, s[50:51]
	s_cbranch_vccz .LBB0_926
	s_barrier

; #define PG8_STAGE(bufoff, gbase, voff) do { _Pragma("unroll") for (int _i = 0; _i < 2; ++_i) \
;         __builtin_amdgcn_global_load_lds((const unsigned*)((const char*)(gbase) + (voff)[_i]), (LAS unsigned*)(lds + (bufoff) + ldsw + _i * 8192), 16, 0, 0); } while (0)
; #define PG8_LDA(dst, b, h) do { _Pragma("unroll") for (int m = 0; m < 4; ++m) _Pragma("unroll") for (int k = 0; k < 2; ++k) dst[m][k] = *(const LAS bf16x8*)(lds + PG8_SA(b, h) + aoff + m * 2048 + k * 1024); } while (0)
; #define PG8_LDB(dst, b, h) do { _Pragma("unroll") for (int n = 0; n < 2; ++n) _Pragma("unroll") for (int k = 0; k < 2; ++k) dst[n][k] = *(const LAS bf16x8*)(lds + PG8_SB(b, h) + boff + n * 2048 + k * 1024); } while (0)
; #define PG8_MMA(ai, bj, At, Bt) do { __builtin_amdgcn_s_setprio(1); _Pragma("unroll") for (int m = 0; m < 4; ++m) _Pragma("unroll") for (int n = 0; n < 2; ++n) _Pragma("unroll") for (int k = 0; k < 2; ++k) \
;         acc[ai][bj][m][n] = __builtin_amdgcn_mfma_f32_16x16x32_bf16(Bt[n][k], At[m][k], acc[ai][bj][m][n], 0, 0, 0); __builtin_amdgcn_s_setprio(0); } while (0)
; #define PG8_WAIT_V(n) asm volatile("s_waitcnt vmcnt(" #n ")" ::: "memory")
; #define PG8_WAIT_L(n) asm volatile("s_waitcnt lgkmcnt(" #n ")" ::: "memory")
; #define PG8_BAR __builtin_amdgcn_s_barrier()
; #define PG8_SCHED __builtin_amdgcn_sched_barrier(0)
; template <class Epi, class Sched>
; __device__ __forceinline__ void gemm_phase(LAS unsigned char* lds, const Gemm g, const Sched& S, const Epi& E) {
;     ...
;             const bool last = (t == nt - 2);
;             const char* a1 = cA + (size_t)(t + 1) * kstep;
;             const char* a2 = last ? nA : cA + (size_t)(t + 2) * kstep; const char* b2 = last ? nB : cB + (size_t)(t + 2) * kstep;
;             const char* a3 = a2 + kstep; const char* b3 = b2 + kstep;
;             PG8_LDB(B0, 0, 0); PG8_LDB(B1, 0, 1); PG8_SCHED; PG8_LDA(At, 0, 0); PG8_STAGE(PG8_SA(1, 1), a1 + hstepA, voffA);
;             PG8_WAIT_V(8); PG8_WAIT_L(0); PG8_BAR; PG8_MMA(0, 0, At, B0); PG8_MMA(0, 1, At, B1); PG8_BAR; PG8_SCHED;
;             PG8_LDA(At, 0, 1); PG8_STAGE(PG8_SB(0, 0), b2, voffB); PG8_STAGE(PG8_SB(0, 1), b2 + hstepB, voffB); PG8_STAGE(PG8_SA(0, 0), a2, voffA);
.LBB0_1077:
	ds_read_b128 v[128:131], v193
	ds_read_b128 v[132:135], v193 offset:1024
	ds_read_b128 v[148:151], v193 offset:2048
	ds_read_b128 v[152:155], v193 offset:3072
	ds_read_b128 v[156:159], v194
	ds_read_b128 v[160:163], v194 offset:1024
	ds_read_b128 v[164:167], v194 offset:2048
	ds_read_b128 v[168:171], v194 offset:3072
	s_add_u32 s30, s24, 0x100
	s_addc_u32 s31, s25, 0
	s_cmpk_eq_i32 s1, 0x5c
	s_cselect_b32 s39, s23, s31
	s_cselect_b32 s38, s22, s30
	s_cselect_b32 s35, s7, s5
	s_cselect_b32 s34, s6, s4
	v_lshl_add_u64 v[214:215], s[24:25], 0, v[144:145]
	s_add_i32 m0, s28, 0xc000
	ds_read_b128 v[172:175], v195
	ds_read_b128 v[176:179], v195 offset:1024
	ds_read_b128 v[180:183], v195 offset:2048
	ds_read_b128 v[184:187], v195 offset:3072
	ds_read_b128 v[198:201], v195 offset:4096
	ds_read_b128 v[202:205], v195 offset:5120
	ds_read_b128 v[206:209], v195 offset:6144
	ds_read_b128 v[210:213], v195 offset:7168
	global_load_lds_dwordx4 v[214:215], off
	v_lshl_add_u64 v[214:215], s[24:25], 0, v[146:147]
	s_add_i32 m0, s28, 0xe000
	s_nop 0
	global_load_lds_dwordx4 v[214:215], off
	s_waitcnt vmcnt(8) lgkmcnt(0)
	s_barrier
	s_setprio 1
	v_mfma_f32_16x16x32_bf16 v[124:127], v[128:131], v[172:175], v[124:127]
	v_mfma_f32_16x16x32_bf16 v[120:123], v[148:151], v[172:175], v[120:123]
	v_mfma_f32_16x16x32_bf16 v[108:111], v[128:131], v[180:183], v[108:111]
	v_mfma_f32_16x16x32_bf16 v[104:107], v[148:151], v[180:183], v[104:107]
	v_mfma_f32_16x16x32_bf16 v[92:95], v[128:131], v[198:201], v[92:95]
	v_mfma_f32_16x16x32_bf16 v[88:91], v[148:151], v[198:201], v[88:91]
	v_mfma_f32_16x16x32_bf16 v[76:79], v[128:131], v[206:209], v[76:79]
	v_mfma_f32_16x16x32_bf16 v[72:75], v[148:151], v[206:209], v[72:75]
	v_mfma_f32_16x16x32_bf16 v[124:127], v[132:135], v[176:179], v[124:127]
	v_mfma_f32_16x16x32_bf16 v[120:123], v[152:155], v[176:179], v[120:123]
	v_mfma_f32_16x16x32_bf16 v[108:111], v[132:135], v[184:187], v[108:111]
	v_mfma_f32_16x16x32_bf16 v[104:107], v[152:155], v[184:187], v[104:107]
	v_mfma_f32_16x16x32_bf16 v[92:95], v[132:135], v[202:205], v[92:95]
	v_mfma_f32_16x16x32_bf16 v[88:91], v[152:155], v[202:205], v[88:91]
	v_mfma_f32_16x16x32_bf16 v[76:79], v[132:135], v[210:213], v[76:79]
	v_mfma_f32_16x16x32_bf16 v[72:75], v[152:155], v[210:213], v[72:75]
	s_setprio 0
	s_setprio 1
	v_mfma_f32_16x16x32_bf16 v[116:119], v[156:159], v[172:175], v[116:119]
	v_mfma_f32_16x16x32_bf16 v[112:115], v[164:167], v[172:175], v[112:115]
	v_mfma_f32_16x16x32_bf16 v[100:103], v[156:159], v[180:183], v[100:103]
	v_mfma_f32_16x16x32_bf16 v[96:99], v[164:167], v[180:183], v[96:99]
	v_mfma_f32_16x16x32_bf16 v[84:87], v[156:159], v[198:201], v[84:87]
	v_mfma_f32_16x16x32_bf16 v[80:83], v[164:167], v[198:201], v[80:83]
	v_mfma_f32_16x16x32_bf16 v[68:71], v[156:159], v[206:209], v[68:71]
	v_mfma_f32_16x16x32_bf16 v[64:67], v[164:167], v[206:209], v[64:67]
	v_mfma_f32_16x16x32_bf16 v[116:119], v[160:163], v[176:179], v[116:119]
	v_mfma_f32_16x16x32_bf16 v[112:115], v[168:171], v[176:179], v[112:115]
	v_mfma_f32_16x16x32_bf16 v[100:103], v[160:163], v[184:187], v[100:103]
	v_mfma_f32_16x16x32_bf16 v[96:99], v[168:171], v[184:187], v[96:99]
	v_mfma_f32_16x16x32_bf16 v[84:87], v[160:163], v[202:205], v[84:87]
	v_mfma_f32_16x16x32_bf16 v[80:83], v[168:171], v[202:205], v[80:83]
	v_mfma_f32_16x16x32_bf16 v[68:71], v[160:163], v[210:213], v[68:71]
	v_mfma_f32_16x16x32_bf16 v[64:67], v[168:171], v[210:213], v[64:67]
	s_setprio 0
	s_barrier
	s_add_i32 s12, s33, s27
	v_lshl_add_u64 v[214:215], s[34:35], 0, v[138:139]
	s_mov_b32 m0, s12
	ds_read_b128 v[172:175], v195 offset:16384
	ds_read_b128 v[176:179], v195 offset:17408
	ds_read_b128 v[180:183], v195 offset:18432
	ds_read_b128 v[184:187], v195 offset:19456
	ds_read_b128 v[198:201], v195 offset:20480
	ds_read_b128 v[202:205], v195 offset:21504
	ds_read_b128 v[206:209], v195 offset:22528
	ds_read_b128 v[210:213], v195 offset:23552
	global_load_lds_dwordx4 v[214:215], off
	s_add_i32 m0, s12, 0x2000
	s_add_u32 s12, s34, 0x180000
	v_lshl_add_u64 v[216:217], s[34:35], 0, v[142:143]
	s_addc_u32 s13, s35, 0
	s_add_i32 s24, s36, s27
	global_load_lds_dwordx4 v[216:217], off
	v_lshl_add_u64 v[218:219], s[12:13], 0, v[138:139]
	s_mov_b32 m0, s24
	v_lshl_add_u64 v[220:221], s[38:39], 0, v[140:141]
	global_load_lds_dwordx4 v[218:219], off
	v_lshl_add_u64 v[218:219], s[12:13], 0, v[142:143]
	s_add_i32 m0, s24, 0x2000
	s_nop 0
	global_load_lds_dwordx4 v[218:219], off
	v_lshl_add_u64 v[218:219], s[38:39], 0, v[136:137]
	s_mov_b32 m0, s28
	s_nop 0
	global_load_lds_dwordx4 v[218:219], off
	s_mov_b32 m0, s40
	s_nop 0
	global_load_lds_dwordx4 v[220:221], off
	s_waitcnt vmcnt(8) lgkmcnt(0)
	s_barrier
; #define PG8_STAGE(bufoff, gbase, voff) do { _Pragma("unroll") for (int _i = 0; _i < 2; ++_i) \
;         __builtin_amdgcn_global_load_lds((const unsigned*)((const char*)(gbase) + (voff)[_i]), (LAS unsigned*)(lds + (bufoff) + ldsw + _i * 8192), 16, 0, 0); } while (0)
; #define PG8_LDA(dst, b, h) do { _Pragma("unroll") for (int m = 0; m < 4; ++m) _Pragma("unroll") for (int k = 0; k < 2; ++k) dst[m][k] = *(const LAS bf16x8*)(lds + PG8_SA(b, h) + aoff + m * 2048 + k * 1024); } while (0)
; #define PG8_LDB(dst, b, h) do { _Pragma("unroll") for (int n = 0; n < 2; ++n) _Pragma("unroll") for (int k = 0; k < 2; ++k) dst[n][k] = *(const LAS bf16x8*)(lds + PG8_SB(b, h) + boff + n * 2048 + k * 1024); } while (0)
; #define PG8_MMA(ai, bj, At, Bt) do { __builtin_amdgcn_s_setprio(1); _Pragma("unroll") for (int m = 0; m < 4; ++m) _Pragma("unroll") for (int n = 0; n < 2; ++n) _Pragma("unroll") for (int k = 0; k < 2; ++k) \
;         acc[ai][bj][m][n] = __builtin_amdgcn_mfma_f32_16x16x32_bf16(Bt[n][k], At[m][k], acc[ai][bj][m][n], 0, 0, 0); __builtin_amdgcn_s_setprio(0); } while (0)
; #define PG8_WAIT_V(n) asm volatile("s_waitcnt vmcnt(" #n ")" ::: "memory")
; #define PG8_WAIT_L(n) asm volatile("s_waitcnt lgkmcnt(" #n ")" ::: "memory")
; #define PG8_BAR __builtin_amdgcn_s_barrier()
; #define PG8_SCHED __builtin_amdgcn_sched_barrier(0)
; template <class Epi, class Sched>
; __device__ __forceinline__ void gemm_phase(LAS unsigned char* lds, const Gemm g, const Sched& S, const Epi& E) {
;     ...
;             PG8_WAIT_V(8); PG8_WAIT_L(0); PG8_BAR; PG8_MMA(1, 0, At, B0); PG8_MMA(1, 1, At, B1); PG8_BAR; PG8_SCHED;
;             PG8_LDB(B0, 1, 0); PG8_LDB(B1, 1, 1); PG8_SCHED; PG8_LDA(At, 1, 0); PG8_STAGE(PG8_SA(0, 1), a2 + hstepA, voffA);
;             PG8_WAIT_V(8); PG8_WAIT_L(0); PG8_BAR; PG8_MMA(0, 0, At, B0); PG8_MMA(0, 1, At, B1); PG8_BAR; PG8_SCHED;
	s_setprio 1
	v_mfma_f32_16x16x32_bf16 v[60:63], v[128:131], v[172:175], v[60:63]
	v_mfma_f32_16x16x32_bf16 v[56:59], v[148:151], v[172:175], v[56:59]
	v_mfma_f32_16x16x32_bf16 v[44:47], v[128:131], v[180:183], v[44:47]
	v_mfma_f32_16x16x32_bf16 v[40:43], v[148:151], v[180:183], v[40:43]
	v_mfma_f32_16x16x32_bf16 v[28:31], v[128:131], v[198:201], v[28:31]
	v_mfma_f32_16x16x32_bf16 v[24:27], v[148:151], v[198:201], v[24:27]
	v_mfma_f32_16x16x32_bf16 v[12:15], v[128:131], v[206:209], v[12:15]
	v_mfma_f32_16x16x32_bf16 v[8:11], v[148:151], v[206:209], v[8:11]
	v_mfma_f32_16x16x32_bf16 v[60:63], v[132:135], v[176:179], v[60:63]
	v_mfma_f32_16x16x32_bf16 v[56:59], v[152:155], v[176:179], v[56:59]
	v_mfma_f32_16x16x32_bf16 v[44:47], v[132:135], v[184:187], v[44:47]
	v_mfma_f32_16x16x32_bf16 v[40:43], v[152:155], v[184:187], v[40:43]
	v_mfma_f32_16x16x32_bf16 v[28:31], v[132:135], v[202:205], v[28:31]
	v_mfma_f32_16x16x32_bf16 v[24:27], v[152:155], v[202:205], v[24:27]
	v_mfma_f32_16x16x32_bf16 v[12:15], v[132:135], v[210:213], v[12:15]
	v_mfma_f32_16x16x32_bf16 v[8:11], v[152:155], v[210:213], v[8:11]
	s_setprio 0
	s_setprio 1
	v_mfma_f32_16x16x32_bf16 v[52:55], v[156:159], v[172:175], v[52:55]
	v_mfma_f32_16x16x32_bf16 v[48:51], v[164:167], v[172:175], v[48:51]
	v_mfma_f32_16x16x32_bf16 v[36:39], v[156:159], v[180:183], v[36:39]
	v_mfma_f32_16x16x32_bf16 v[32:35], v[164:167], v[180:183], v[32:35]
	v_mfma_f32_16x16x32_bf16 v[20:23], v[156:159], v[198:201], v[20:23]
	v_mfma_f32_16x16x32_bf16 v[16:19], v[164:167], v[198:201], v[16:19]
	v_mfma_f32_16x16x32_bf16 v[4:7], v[156:159], v[206:209], v[4:7]
	v_mfma_f32_16x16x32_bf16 v[0:3], v[164:167], v[206:209], v[0:3]
	v_mfma_f32_16x16x32_bf16 v[52:55], v[160:163], v[176:179], v[52:55]
	v_mfma_f32_16x16x32_bf16 v[48:51], v[168:171], v[176:179], v[48:51]
	v_mfma_f32_16x16x32_bf16 v[36:39], v[160:163], v[184:187], v[36:39]
	v_mfma_f32_16x16x32_bf16 v[32:35], v[168:171], v[184:187], v[32:35]
	v_mfma_f32_16x16x32_bf16 v[20:23], v[160:163], v[202:205], v[20:23]
	v_mfma_f32_16x16x32_bf16 v[16:19], v[168:171], v[202:205], v[16:19]
	v_mfma_f32_16x16x32_bf16 v[4:7], v[160:163], v[210:213], v[4:7]
	v_mfma_f32_16x16x32_bf16 v[0:3], v[168:171], v[210:213], v[0:3]
	s_setprio 0
	s_barrier
	v_add_u32_e32 v152, s37, v190
	v_add_u32_e32 v168, s26, v190
	ds_read_b128 v[128:131], v152
	ds_read_b128 v[132:135], v152 offset:1024
	ds_read_b128 v[148:151], v152 offset:2048
	ds_read_b128 v[152:155], v152 offset:3072
	ds_read_b128 v[156:159], v168
	ds_read_b128 v[160:163], v168 offset:1024
	ds_read_b128 v[164:167], v168 offset:2048
	ds_read_b128 v[168:171], v168 offset:3072
	s_add_u32 s12, s38, 0x180000
	s_addc_u32 s13, s39, 0
	s_mov_b32 m0, s41
	v_lshl_add_u64 v[222:223], s[12:13], 0, v[136:137]
	ds_read_b128 v[172:175], v195 offset:32768
	ds_read_b128 v[176:179], v195 offset:33792
	ds_read_b128 v[180:183], v195 offset:34816
	ds_read_b128 v[184:187], v195 offset:35840
	ds_read_b128 v[198:201], v195 offset:36864
	ds_read_b128 v[202:205], v195 offset:37888
	ds_read_b128 v[206:209], v195 offset:38912
	ds_read_b128 v[210:213], v195 offset:39936
	global_load_lds_dwordx4 v[222:223], off
	v_lshl_add_u64 v[222:223], s[12:13], 0, v[140:141]
	s_mov_b32 m0, s42
	s_nop 0
	global_load_lds_dwordx4 v[222:223], off
	s_waitcnt vmcnt(8) lgkmcnt(0)
	s_barrier
	s_setprio 1
	v_mfma_f32_16x16x32_bf16 v[124:127], v[128:131], v[172:175], v[124:127]
	v_mfma_f32_16x16x32_bf16 v[120:123], v[148:151], v[172:175], v[120:123]
	v_mfma_f32_16x16x32_bf16 v[108:111], v[128:131], v[180:183], v[108:111]
	v_mfma_f32_16x16x32_bf16 v[104:107], v[148:151], v[180:183], v[104:107]
	v_mfma_f32_16x16x32_bf16 v[92:95], v[128:131], v[198:201], v[92:95]
	v_mfma_f32_16x16x32_bf16 v[88:91], v[148:151], v[198:201], v[88:91]
	v_mfma_f32_16x16x32_bf16 v[76:79], v[128:131], v[206:209], v[76:79]
	v_mfma_f32_16x16x32_bf16 v[72:75], v[148:151], v[206:209], v[72:75]
	v_mfma_f32_16x16x32_bf16 v[124:127], v[132:135], v[176:179], v[124:127]
	v_mfma_f32_16x16x32_bf16 v[120:123], v[152:155], v[176:179], v[120:123]
	v_mfma_f32_16x16x32_bf16 v[108:111], v[132:135], v[184:187], v[108:111]
	v_mfma_f32_16x16x32_bf16 v[104:107], v[152:155], v[184:187], v[104:107]
	v_mfma_f32_16x16x32_bf16 v[92:95], v[132:135], v[202:205], v[92:95]
	v_mfma_f32_16x16x32_bf16 v[88:91], v[152:155], v[202:205], v[88:91]
	v_mfma_f32_16x16x32_bf16 v[76:79], v[132:135], v[210:213], v[76:79]
	v_mfma_f32_16x16x32_bf16 v[72:75], v[152:155], v[210:213], v[72:75]
	s_setprio 0
	s_setprio 1
	v_mfma_f32_16x16x32_bf16 v[116:119], v[156:159], v[172:175], v[116:119]
	v_mfma_f32_16x16x32_bf16 v[112:115], v[164:167], v[172:175], v[112:115]
	v_mfma_f32_16x16x32_bf16 v[100:103], v[156:159], v[180:183], v[100:103]
	v_mfma_f32_16x16x32_bf16 v[96:99], v[164:167], v[180:183], v[96:99]
	v_mfma_f32_16x16x32_bf16 v[84:87], v[156:159], v[198:201], v[84:87]
	v_mfma_f32_16x16x32_bf16 v[80:83], v[164:167], v[198:201], v[80:83]
	v_mfma_f32_16x16x32_bf16 v[68:71], v[156:159], v[206:209], v[68:71]
	v_mfma_f32_16x16x32_bf16 v[64:67], v[164:167], v[206:209], v[64:67]
	v_mfma_f32_16x16x32_bf16 v[116:119], v[160:163], v[176:179], v[116:119]
	v_mfma_f32_16x16x32_bf16 v[112:115], v[168:171], v[176:179], v[112:115]
	v_mfma_f32_16x16x32_bf16 v[100:103], v[160:163], v[184:187], v[100:103]
	v_mfma_f32_16x16x32_bf16 v[96:99], v[168:171], v[184:187], v[96:99]
	v_mfma_f32_16x16x32_bf16 v[84:87], v[160:163], v[202:205], v[84:87]
	v_mfma_f32_16x16x32_bf16 v[80:83], v[168:171], v[202:205], v[80:83]
	v_mfma_f32_16x16x32_bf16 v[68:71], v[160:163], v[210:213], v[68:71]
	v_mfma_f32_16x16x32_bf16 v[64:67], v[168:171], v[210:213], v[64:67]
	s_setprio 0
	s_barrier
; #define PG8_STAGE(bufoff, gbase, voff) do { _Pragma("unroll") for (int _i = 0; _i < 2; ++_i) \
;         __builtin_amdgcn_global_load_lds((const unsigned*)((const char*)(gbase) + (voff)[_i]), (LAS unsigned*)(lds + (bufoff) + ldsw + _i * 8192), 16, 0, 0); } while (0)
; #define PG8_LDA(dst, b, h) do { _Pragma("unroll") for (int m = 0; m < 4; ++m) _Pragma("unroll") for (int k = 0; k < 2; ++k) dst[m][k] = *(const LAS bf16x8*)(lds + PG8_SA(b, h) + aoff + m * 2048 + k * 1024); } while (0)
; #define PG8_MMA(ai, bj, At, Bt) do { __builtin_amdgcn_s_setprio(1); _Pragma("unroll") for (int m = 0; m < 4; ++m) _Pragma("unroll") for (int n = 0; n < 2; ++n) _Pragma("unroll") for (int k = 0; k < 2; ++k) \
;         acc[ai][bj][m][n] = __builtin_amdgcn_mfma_f32_16x16x32_bf16(Bt[n][k], At[m][k], acc[ai][bj][m][n], 0, 0, 0); __builtin_amdgcn_s_setprio(0); } while (0)
; #define PG8_WAIT_V(n) asm volatile("s_waitcnt vmcnt(" #n ")" ::: "memory")
; #define PG8_WAIT_L(n) asm volatile("s_waitcnt lgkmcnt(" #n ")" ::: "memory")
; #define PG8_BAR __builtin_amdgcn_s_barrier()
; #define PG8_SCHED __builtin_amdgcn_sched_barrier(0)
; template <class Epi, class Sched>
; __device__ __forceinline__ void gemm_phase(LAS unsigned char* lds, const Gemm g, const Sched& S, const Epi& E) {
;     ...
;             PG8_LDA(At, 1, 1); PG8_STAGE(PG8_SB(1, 0), b3, voffB); PG8_STAGE(PG8_SB(1, 1), b3 + hstepB, voffB); PG8_STAGE(PG8_SA(1, 0), a3, voffA);
;             PG8_WAIT_V(8); PG8_WAIT_L(0); PG8_BAR; PG8_MMA(1, 0, At, B0); PG8_MMA(1, 1, At, B1); PG8_BAR; PG8_SCHED;
;         }
;         if (wr == 0) PG8_BAR;
	s_add_i32 s12, s37, s27
	v_lshl_add_u64 v[214:215], v[214:215], 0, s[16:17]
	s_mov_b32 m0, s12
	ds_read_b128 v[172:175], v195 offset:49152
	ds_read_b128 v[176:179], v195 offset:50176
	ds_read_b128 v[180:183], v195 offset:51200
	ds_read_b128 v[184:187], v195 offset:52224
	ds_read_b128 v[198:201], v195 offset:53248
	ds_read_b128 v[202:205], v195 offset:54272
	ds_read_b128 v[206:209], v195 offset:55296
	ds_read_b128 v[210:213], v195 offset:56320
	global_load_lds_dwordx4 v[214:215], off
	s_add_i32 m0, s12, 0x2000
	s_add_u32 s12, s34, 0x180080
	v_lshl_add_u64 v[214:215], v[216:217], 0, s[16:17]
	s_addc_u32 s13, s35, 0
	s_add_i32 s24, s26, s27
	global_load_lds_dwordx4 v[214:215], off
	v_lshl_add_u64 v[214:215], s[12:13], 0, v[138:139]
	s_mov_b32 m0, s24
	s_nop 0
	global_load_lds_dwordx4 v[214:215], off
	v_lshl_add_u64 v[214:215], s[12:13], 0, v[142:143]
	s_add_i32 m0, s24, 0x2000
	s_nop 0
	global_load_lds_dwordx4 v[214:215], off
	v_lshl_add_u64 v[214:215], v[218:219], 0, s[16:17]
	s_mov_b32 m0, s46
	s_nop 0
	global_load_lds_dwordx4 v[214:215], off
	v_lshl_add_u64 v[214:215], v[220:221], 0, s[16:17]
	s_mov_b32 m0, s47
	s_nop 0
	global_load_lds_dwordx4 v[214:215], off
	s_waitcnt vmcnt(8) lgkmcnt(0)
	s_barrier
	s_setprio 1
	v_mfma_f32_16x16x32_bf16 v[60:63], v[128:131], v[172:175], v[60:63]
	v_mfma_f32_16x16x32_bf16 v[56:59], v[148:151], v[172:175], v[56:59]
	v_mfma_f32_16x16x32_bf16 v[44:47], v[128:131], v[180:183], v[44:47]
	v_mfma_f32_16x16x32_bf16 v[40:43], v[148:151], v[180:183], v[40:43]
	v_mfma_f32_16x16x32_bf16 v[28:31], v[128:131], v[198:201], v[28:31]
	v_mfma_f32_16x16x32_bf16 v[24:27], v[148:151], v[198:201], v[24:27]
	v_mfma_f32_16x16x32_bf16 v[12:15], v[128:131], v[206:209], v[12:15]
	v_mfma_f32_16x16x32_bf16 v[8:11], v[148:151], v[206:209], v[8:11]
	v_mfma_f32_16x16x32_bf16 v[60:63], v[132:135], v[176:179], v[60:63]
	v_mfma_f32_16x16x32_bf16 v[56:59], v[152:155], v[176:179], v[56:59]
	v_mfma_f32_16x16x32_bf16 v[44:47], v[132:135], v[184:187], v[44:47]
	v_mfma_f32_16x16x32_bf16 v[40:43], v[152:155], v[184:187], v[40:43]
	v_mfma_f32_16x16x32_bf16 v[28:31], v[132:135], v[202:205], v[28:31]
	v_mfma_f32_16x16x32_bf16 v[24:27], v[152:155], v[202:205], v[24:27]
	v_mfma_f32_16x16x32_bf16 v[12:15], v[132:135], v[210:213], v[12:15]
	v_mfma_f32_16x16x32_bf16 v[8:11], v[152:155], v[210:213], v[8:11]
	s_setprio 0
	s_setprio 1
	v_mfma_f32_16x16x32_bf16 v[52:55], v[156:159], v[172:175], v[52:55]
	v_mfma_f32_16x16x32_bf16 v[48:51], v[164:167], v[172:175], v[48:51]
	v_mfma_f32_16x16x32_bf16 v[36:39], v[156:159], v[180:183], v[36:39]
	v_mfma_f32_16x16x32_bf16 v[32:35], v[164:167], v[180:183], v[32:35]
	v_mfma_f32_16x16x32_bf16 v[20:23], v[156:159], v[198:201], v[20:23]
	v_mfma_f32_16x16x32_bf16 v[16:19], v[164:167], v[198:201], v[16:19]
	v_mfma_f32_16x16x32_bf16 v[4:7], v[156:159], v[206:209], v[4:7]
	v_mfma_f32_16x16x32_bf16 v[0:3], v[164:167], v[206:209], v[0:3]
	v_mfma_f32_16x16x32_bf16 v[52:55], v[160:163], v[176:179], v[52:55]
	v_mfma_f32_16x16x32_bf16 v[48:51], v[168:171], v[176:179], v[48:51]
	v_mfma_f32_16x16x32_bf16 v[36:39], v[160:163], v[184:187], v[36:39]
	v_mfma_f32_16x16x32_bf16 v[32:35], v[168:171], v[184:187], v[32:35]
	v_mfma_f32_16x16x32_bf16 v[20:23], v[160:163], v[202:205], v[20:23]
	v_mfma_f32_16x16x32_bf16 v[16:19], v[168:171], v[202:205], v[16:19]
	v_mfma_f32_16x16x32_bf16 v[4:7], v[160:163], v[210:213], v[4:7]
	v_mfma_f32_16x16x32_bf16 v[0:3], v[168:171], v[210:213], v[0:3]
	s_setprio 0
	s_barrier
	s_add_i32 s1, s1, 2
	s_add_u32 s4, s4, 0x100
	s_addc_u32 s5, s5, 0
	s_cmpk_gt_u32 s1, 0x5d
	s_mov_b64 s[24:25], s[30:31]
	s_cbranch_scc0 .LBB0_1077
	s_and_b64 vcc, exec, s[18:19]
	s_cbranch_vccz .LBB0_1080
	s_barrier
